# baseline (speedup 1.0000x reference)
; #define MFMA(a, b, c) __builtin_amdgcn_mfma_f32_16x16x32_bf16((a), (b), (c), 0, 0, 0)
; template <int AMODE>
; __device__ __forceinline__ void gemm_kloop(f32x4 (&acc)[4][4], const u16* __restrict__ A, int lda,
;                                            const u16* __restrict__ Bt, int ldb, int K, char* smem,
;                                            const float* __restrict__ ssq_rows) {
;     ...
;     for (int kt = 0; kt < nk; ++kt) {
;         const int buf = kt & 1;
;         if (kt + 1 < nk) GLOAD(kt + 1, buf ^ 1);
;         const char* ab = As + buf * 16384 + (wr * 64 + r) * 128;
;         const char* bb = Bs + buf * 16384 + (wc * 64 + r) * 128;
;         bf16x8 af[2][4], bfr[2][4];
; #pragma unroll
;         for (int ks = 0; ks < 2; ++ks) {
;             const int co = ((ks * 4 + g4) ^ (r & 7)) << 4;
; #pragma unroll
;             for (int i = 0; i < 4; ++i) af[ks][i] = ld_frag(ab + i * 2048 + co);
; #pragma unroll
;             for (int j = 0; j < 4; ++j) bfr[ks][j] = ld_frag(bb + j * 2048 + co);
;         }
;         __builtin_amdgcn_sched_barrier(0);
;         __builtin_amdgcn_s_setprio(1);
; #pragma unroll
;         for (int ks = 0; ks < 2; ++ks)
; #pragma unroll
;             for (int i = 0; i < 4; ++i)
; #pragma unroll
;                 for (int j = 0; j < 4; ++j) acc[i][j] = MFMA(bfr[ks][j], af[ks][i], acc[i][j]);
;         __builtin_amdgcn_s_setprio(0);
;         __builtin_amdgcn_sched_barrier(0);
;         if (kt + 1 < nk) LSTORE(buf ^ 1);
;         asm volatile("s_waitcnt vmcnt(0)" ::: "memory");
;         __syncthreads();
;     }
.LBB0_152:
	s_setprio 2
	v_add_u32_e32 v0, s2, v73
	v_or_b32_e32 v77, s2, v72
	v_add_u32_e32 v90, v0, v76
	v_add_u32_e32 v102, v77, v76
	v_add_u32_e32 v0, v0, v74
	ds_read_b128 v[78:81], v90
	ds_read_b128 v[82:85], v90 offset:2048
	ds_read_b128 v[86:89], v90 offset:4096
	ds_read_b128 v[90:93], v90 offset:6144
	ds_read_b128 v[94:97], v102 offset:32768
	ds_read_b128 v[98:101], v102 offset:34816
	ds_read_b128 v[110:113], v102 offset:36864
	ds_read_b128 v[114:117], v102 offset:38912
	ds_read_b128 v[118:121], v0
	ds_read_b128 v[122:125], v0 offset:2048
	ds_read_b128 v[126:129], v0 offset:4096
	ds_read_b128 v[130:133], v0 offset:6144
	v_add_u32_e32 v0, v77, v74
	ds_read_b128 v[134:137], v0 offset:32768
	ds_read_b128 v[142:145], v0 offset:34816
	ds_read_b128 v[146:149], v0 offset:36864
	ds_read_b128 v[150:153], v0 offset:38912
	s_xor_b32 s4, s2, 0x4000
	s_add_u32 s4, s4, s5
	s_add_u32 s100, s100, 0x80
	s_addc_u32 s101, s101, 0
	s_add_u32 s98, s98, 0x80
	s_addc_u32 s99, s99, 0
	s_add_u32 m0, s4, 0x8000
	s_nop 0
	global_load_lds_dwordx4 v216, s[100:101]
	s_add_u32 m0, s4, 0x0
	s_nop 0
	global_load_lds_dwordx4 v216, s[98:99]
	s_add_u32 m0, s4, 0x9000
	s_nop 0
	global_load_lds_dwordx4 v217, s[100:101]
	s_add_u32 m0, s4, 0x1000
	s_nop 0
	global_load_lds_dwordx4 v217, s[98:99]
	s_add_u32 m0, s4, 0xa000
	s_nop 0
	global_load_lds_dwordx4 v218, s[100:101]
	s_add_u32 m0, s4, 0x2000
	s_nop 0
	global_load_lds_dwordx4 v218, s[98:99]
	s_add_u32 m0, s4, 0xb000
	s_nop 0
	global_load_lds_dwordx4 v219, s[100:101]
	s_add_u32 m0, s4, 0x3000
	s_nop 0
	global_load_lds_dwordx4 v219, s[98:99]
	s_setprio 1
	s_waitcnt lgkmcnt(11)
	v_mfma_f32_16x16x32_bf16 v[62:65], v[94:97], v[78:81], v[62:65]
	s_waitcnt lgkmcnt(10)
	v_mfma_f32_16x16x32_bf16 v[58:61], v[98:101], v[78:81], v[58:61]
	s_waitcnt lgkmcnt(9)
	v_mfma_f32_16x16x32_bf16 v[54:57], v[110:113], v[78:81], v[54:57]
	s_waitcnt lgkmcnt(8)
	v_mfma_f32_16x16x32_bf16 v[50:53], v[114:117], v[78:81], v[50:53]
	v_mfma_f32_16x16x32_bf16 v[46:49], v[94:97], v[82:85], v[46:49]
	v_mfma_f32_16x16x32_bf16 v[42:45], v[98:101], v[82:85], v[42:45]
	v_mfma_f32_16x16x32_bf16 v[38:41], v[110:113], v[82:85], v[38:41]
	v_mfma_f32_16x16x32_bf16 v[34:37], v[114:117], v[82:85], v[34:37]
	v_mfma_f32_16x16x32_bf16 v[30:33], v[94:97], v[86:89], v[30:33]
	v_mfma_f32_16x16x32_bf16 v[26:29], v[98:101], v[86:89], v[26:29]
	v_mfma_f32_16x16x32_bf16 v[22:25], v[110:113], v[86:89], v[22:25]
	v_mfma_f32_16x16x32_bf16 v[18:21], v[114:117], v[86:89], v[18:21]
	v_mfma_f32_16x16x32_bf16 v[14:17], v[94:97], v[90:93], v[14:17]
	v_mfma_f32_16x16x32_bf16 v[10:13], v[98:101], v[90:93], v[10:13]
	v_mfma_f32_16x16x32_bf16 v[6:9], v[110:113], v[90:93], v[6:9]
	v_mfma_f32_16x16x32_bf16 v[2:5], v[114:117], v[90:93], v[2:5]
	s_waitcnt lgkmcnt(3)
	v_mfma_f32_16x16x32_bf16 v[62:65], v[134:137], v[118:121], v[62:65]
	s_waitcnt lgkmcnt(2)
	v_mfma_f32_16x16x32_bf16 v[58:61], v[142:145], v[118:121], v[58:61]
	s_waitcnt lgkmcnt(1)
	v_mfma_f32_16x16x32_bf16 v[54:57], v[146:149], v[118:121], v[54:57]
	s_waitcnt lgkmcnt(0)
	v_mfma_f32_16x16x32_bf16 v[50:53], v[150:153], v[118:121], v[50:53]
	v_mfma_f32_16x16x32_bf16 v[46:49], v[134:137], v[122:125], v[46:49]
	v_mfma_f32_16x16x32_bf16 v[42:45], v[142:145], v[122:125], v[42:45]
	v_mfma_f32_16x16x32_bf16 v[38:41], v[146:149], v[122:125], v[38:41]
	v_mfma_f32_16x16x32_bf16 v[34:37], v[150:153], v[122:125], v[34:37]
	v_mfma_f32_16x16x32_bf16 v[30:33], v[134:137], v[126:129], v[30:33]
	v_mfma_f32_16x16x32_bf16 v[26:29], v[142:145], v[126:129], v[26:29]
	v_mfma_f32_16x16x32_bf16 v[22:25], v[146:149], v[126:129], v[22:25]
	v_mfma_f32_16x16x32_bf16 v[18:21], v[150:153], v[126:129], v[18:21]
	v_mfma_f32_16x16x32_bf16 v[14:17], v[134:137], v[130:133], v[14:17]
	v_mfma_f32_16x16x32_bf16 v[10:13], v[142:145], v[130:133], v[10:13]
	v_mfma_f32_16x16x32_bf16 v[6:9], v[146:149], v[130:133], v[6:9]
	v_mfma_f32_16x16x32_bf16 v[2:5], v[150:153], v[130:133], v[2:5]
	s_nop 0
	s_xor_b32 s2, s2, 0x4000
	s_add_i32 s0, s0, 1
	s_cmp_eq_u32 s0, 15
	s_waitcnt vmcnt(0)
	s_barrier
	s_cbranch_scc0 .LBB0_152
	s_setprio 2
	v_add_u32_e32 v0, v73, v76
	ds_read_b128 v[66:69], v0 offset:16384
	ds_read_b128 v[78:81], v0 offset:18432
	ds_read_b128 v[82:85], v0 offset:20480
	ds_read_b128 v[86:89], v0 offset:22528
	v_add_u32_e32 v0, v72, v76
	ds_read_b128 v[90:93], v0 offset:49152
	ds_read_b128 v[98:101], v0 offset:51200
	ds_read_b128 v[110:113], v0 offset:53248
	ds_read_b128 v[114:117], v0 offset:55296
	v_add_u32_e32 v0, v73, v74
	ds_read_b128 v[118:121], v0 offset:16384
	ds_read_b128 v[122:125], v0 offset:18432
	ds_read_b128 v[126:129], v0 offset:20480
	ds_read_b128 v[130:133], v0 offset:22528
	v_add_u32_e32 v0, v72, v74
	ds_read_b128 v[134:137], v0 offset:49152
	ds_read_b128 v[142:145], v0 offset:51200
	ds_read_b128 v[146:149], v0 offset:53248
	ds_read_b128 v[150:153], v0 offset:55296
	v_ashrrev_i32_e32 v96, 7, v70
	v_and_b32_e32 v72, 15, v70
	v_bfe_u32 v74, v70, 6, 1
	v_bfe_u32 v73, v70, 4, 2
	s_setprio 1
	s_waitcnt lgkmcnt(11)
	v_mfma_f32_16x16x32_bf16 v[62:65], v[90:93], v[66:69], v[62:65]
	s_waitcnt lgkmcnt(10)
	v_mfma_f32_16x16x32_bf16 v[58:61], v[98:101], v[66:69], v[58:61]
	s_waitcnt lgkmcnt(9)
	v_mfma_f32_16x16x32_bf16 v[54:57], v[110:113], v[66:69], v[54:57]
	s_waitcnt lgkmcnt(8)
; __device__ __forceinline__ float softplusf(float x) { return fmaxf(x, 0.f) + log1pf(__expf(-fabsf(x))); }
; #define MFMA(a, b, c) __builtin_amdgcn_mfma_f32_16x16x32_bf16((a), (b), (c), 0, 0, 0)
; template <int AMODE>
; __device__ __forceinline__ void gemm_kloop(f32x4 (&acc)[4][4], const u16* __restrict__ A, int lda,
;                                            const u16* __restrict__ Bt, int ldb, int K, char* smem,
;                                            const float* __restrict__ ssq_rows) {
;     ...
;         for (int ks = 0; ks < 2; ++ks)
; #pragma unroll
;             for (int i = 0; i < 4; ++i)
; #pragma unroll
;                 for (int j = 0; j < 4; ++j) acc[i][j] = MFMA(bfr[ks][j], af[ks][i], acc[i][j]);
; __device__ void phaseA_tile(const Params& p, int l, int mt, int nt, char* smem) {
;     ...
;         float* lf_s = (float*)smem;
;         if (wc == 0) {
; #pragma unroll
;             for (int i = 0; i < 4; ++i) {
;                 const int rl = wr * 64 + i * 16 + r;
;                 const int row = m0 + rl;
; #pragma unroll
;                 for (int j = 0; j < 2; ++j) {
;                     const int c = j * 16 + g4 * 4;
;                     const float4 db = *(const float4*)(p.dt_bias + l * 32 + c);
;                     const f32x4 v = acc[i][j];
;                     *(float4*)(p.dtb + (size_t)row * 32 + c) =
;                         make_float4(softplusf(v[0] + db.x), softplusf(v[1] + db.y), softplusf(v[2] + db.z), softplusf(v[3] + db.w));
;                 }
	v_mfma_f32_16x16x32_bf16 v[50:53], v[114:117], v[66:69], v[50:53]
	v_mfma_f32_16x16x32_bf16 v[46:49], v[90:93], v[78:81], v[46:49]
	v_mfma_f32_16x16x32_bf16 v[42:45], v[98:101], v[78:81], v[42:45]
	v_mfma_f32_16x16x32_bf16 v[38:41], v[110:113], v[78:81], v[38:41]
	v_mfma_f32_16x16x32_bf16 v[34:37], v[114:117], v[78:81], v[34:37]
	v_mfma_f32_16x16x32_bf16 v[30:33], v[90:93], v[82:85], v[30:33]
	v_mfma_f32_16x16x32_bf16 v[26:29], v[98:101], v[82:85], v[26:29]
	v_mfma_f32_16x16x32_bf16 v[22:25], v[110:113], v[82:85], v[22:25]
	v_mfma_f32_16x16x32_bf16 v[18:21], v[114:117], v[82:85], v[18:21]
	v_mfma_f32_16x16x32_bf16 v[14:17], v[90:93], v[86:89], v[14:17]
	v_mfma_f32_16x16x32_bf16 v[10:13], v[98:101], v[86:89], v[10:13]
	v_mfma_f32_16x16x32_bf16 v[6:9], v[110:113], v[86:89], v[6:9]
	v_mfma_f32_16x16x32_bf16 v[2:5], v[114:117], v[86:89], v[2:5]
	s_waitcnt lgkmcnt(3)
	v_mfma_f32_16x16x32_bf16 v[62:65], v[134:137], v[118:121], v[62:65]
	s_waitcnt lgkmcnt(2)
	v_mfma_f32_16x16x32_bf16 v[58:61], v[142:145], v[118:121], v[58:61]
	s_waitcnt lgkmcnt(1)
	v_mfma_f32_16x16x32_bf16 v[54:57], v[146:149], v[118:121], v[54:57]
	s_waitcnt lgkmcnt(0)
	v_mfma_f32_16x16x32_bf16 v[50:53], v[150:153], v[118:121], v[50:53]
	v_mfma_f32_16x16x32_bf16 v[46:49], v[134:137], v[122:125], v[46:49]
	v_mfma_f32_16x16x32_bf16 v[42:45], v[142:145], v[122:125], v[42:45]
	v_mfma_f32_16x16x32_bf16 v[38:41], v[146:149], v[122:125], v[38:41]
	v_mfma_f32_16x16x32_bf16 v[34:37], v[150:153], v[122:125], v[34:37]
	v_mfma_f32_16x16x32_bf16 v[30:33], v[134:137], v[126:129], v[30:33]
	v_mfma_f32_16x16x32_bf16 v[26:29], v[142:145], v[126:129], v[26:29]
	v_mfma_f32_16x16x32_bf16 v[22:25], v[146:149], v[126:129], v[22:25]
	v_mfma_f32_16x16x32_bf16 v[18:21], v[150:153], v[126:129], v[18:21]
	v_mfma_f32_16x16x32_bf16 v[14:17], v[134:137], v[130:133], v[14:17]
	v_mfma_f32_16x16x32_bf16 v[10:13], v[142:145], v[130:133], v[10:13]
	v_mfma_f32_16x16x32_bf16 v[6:9], v[146:149], v[130:133], v[6:9]
	v_mfma_f32_16x16x32_bf16 v[2:5], v[150:153], v[130:133], v[2:5]
	s_setprio 0
	s_waitcnt vmcnt(0)
	s_cmpk_eq_i32 s52, 0x100
	s_cselect_b64 s[60:61], -1, 0
	s_cmpk_lg_i32 s52, 0x100
	s_cselect_b64 s[24:25], -1, 0
	s_cmpk_gt_i32 s53, 0x5f
	s_mov_b64 s[0:1], -1
	s_barrier
	s_cbranch_scc0 .LBB0_182
	v_cmp_eq_u32_e32 vcc, 0, v74
	s_and_saveexec_b64 s[4:5], vcc
	s_cbranch_execz .LBB0_156
	v_lshlrev_b32_e32 v0, 4, v73
	global_load_dwordx4 v[66:69], v0, s[74:75]
	s_mov_b32 s2, 0xbfb8aa3b
	s_mov_b32 s26, 0x3f2aaaab
	s_mov_b32 s0, 0x3ecc95a3
	s_mov_b32 s28, 0x3e9b6dac
	s_mov_b32 s30, 0x3f2aaada
	v_lshl_or_b32 v71, v96, 6, v72
	v_add_u32_e32 v76, s54, v71
	v_ashrrev_i32_e32 v77, 31, v76
	v_readlane_b32 s8, v213, 4
	v_lshlrev_b64 v[80:81], 7, v[76:77]
	v_readlane_b32 s10, v213, 6
	v_readlane_b32 s11, v213, 7
	v_readlane_b32 s12, v213, 8
	v_readlane_b32 s13, v213, 9
	s_mov_b32 s12, 0x3f317218
	v_readlane_b32 s14, v213, 10
	v_readlane_b32 s15, v213, 11
	s_mov_b32 s14, 0xb102e308
	s_mov_b32 s8, 0x7f800000
	v_readlane_b32 s9, v213, 5
	s_mov_b32 s9, 0x33800000
	v_readlane_b32 s16, v213, 12
	v_readlane_b32 s17, v213, 13
	v_readlane_b32 s18, v213, 14
	v_readlane_b32 s19, v213, 15
	v_readlane_b32 s20, v213, 16
	v_readlane_b32 s21, v213, 17
	v_readlane_b32 s22, v213, 18
	v_readlane_b32 s23, v213, 19
	s_waitcnt vmcnt(0)
	v_add_f32_e32 v66, v62, v66
	v_max_f32_e32 v78, 0, v66
	v_mul_f32_e64 v66, |v66|, s2
	v_exp_f32_e32 v97, v66
	v_add_f32_e32 v67, v63, v67
	v_add_f32_e32 v68, v64, v68
	v_add_f32_e32 v69, v65, v69
	v_add_f32_e32 v66, 1.0, v97
	v_add_f32_e32 v79, -1.0, v66
	v_sub_f32_e32 v82, v79, v66
	v_add_f32_e32 v82, 1.0, v82
	v_sub_f32_e32 v79, v97, v79
	v_add_f32_e32 v79, v79, v82
	v_frexp_mant_f32_e32 v82, v66
	v_cmp_gt_f32_e32 vcc, s26, v82
	v_cvt_f64_f32_e32 v[82:83], v66
	v_frexp_exp_i32_f64_e32 v82, v[82:83]
	v_subbrev_co_u32_e32 v88, vcc, 0, v82, vcc
	v_sub_u32_e32 v82, 0, v88
	v_ldexp_f32 v66, v66, v82
	v_ldexp_f32 v82, v79, v82
	v_max_f32_e32 v79, 0, v67
	v_mul_f32_e64 v67, |v67|, s2
	v_exp_f32_e32 v98, v67
	s_nop 0
	v_add_f32_e32 v67, 1.0, v98
	v_add_f32_e32 v83, -1.0, v67
	v_sub_f32_e32 v84, v83, v67
	v_add_f32_e32 v84, 1.0, v84
	v_sub_f32_e32 v83, v98, v83
	v_add_f32_e32 v83, v83, v84
	v_frexp_mant_f32_e32 v84, v67
	v_cmp_gt_f32_e32 vcc, s26, v84
	v_cvt_f64_f32_e32 v[84:85], v67
	v_frexp_exp_i32_f64_e32 v84, v[84:85]
	v_subbrev_co_u32_e32 v99, vcc, 0, v84, vcc
	v_sub_u32_e32 v84, 0, v99
	v_ldexp_f32 v67, v67, v84
	v_ldexp_f32 v83, v83, v84
	v_pk_add_f32 v[84:85], v[66:67], 1.0 op_sel_hi:[1,0]
	v_pk_add_f32 v[94:95], v[66:67], -1.0 op_sel_hi:[1,0]
	v_pk_add_f32 v[86:87], v[84:85], -1.0 op_sel_hi:[1,0]
	v_pk_add_f32 v[100:101], v[94:95], 1.0 op_sel_hi:[1,0]
	v_pk_add_f32 v[86:87], v[66:67], v[86:87] neg_lo:[0,1] neg_hi:[0,1]
	v_pk_add_f32 v[66:67], v[66:67], v[100:101] neg_lo:[0,1] neg_hi:[0,1]
	v_pk_add_f32 v[86:87], v[82:83], v[86:87]
	v_pk_add_f32 v[66:67], v[82:83], v[66:67]
	v_pk_add_f32 v[90:91], v[84:85], v[86:87]
	v_pk_add_f32 v[82:83], v[94:95], v[66:67]
	v_rcp_f32_e32 v92, v90
	v_rcp_f32_e32 v93, v91
	v_pk_add_f32 v[84:85], v[90:91], v[84:85] neg_lo:[0,1] neg_hi:[0,1]
	v_pk_add_f32 v[94:95], v[82:83], v[94:95] neg_lo:[0,1] neg_hi:[0,1]
	v_pk_add_f32 v[84:85], v[86:87], v[84:85] neg_lo:[0,1] neg_hi:[0,1]
	v_pk_mul_f32 v[86:87], v[82:83], v[92:93]
	v_pk_add_f32 v[66:67], v[66:67], v[94:95] neg_lo:[0,1] neg_hi:[0,1]
	v_pk_mul_f32 v[94:95], v[90:91], v[86:87]
	s_nop 0
	v_pk_fma_f32 v[100:101], v[86:87], v[90:91], v[94:95] neg_lo:[0,0,1] neg_hi:[0,0,1]
	s_nop 0
	v_pk_fma_f32 v[100:101], v[86:87], v[84:85], v[100:101]
	s_nop 0
	v_pk_add_f32 v[102:103], v[94:95], v[100:101]
	s_nop 0
; __device__ __forceinline__ float softplusf(float x) { return fmaxf(x, 0.f) + log1pf(__expf(-fabsf(x))); }
; __device__ void phaseA_tile(const Params& p, int l, int mt, int nt, char* smem) {
;     ...
;                 for (int j = 0; j < 2; ++j) {
;                     const int c = j * 16 + g4 * 4;
;                     const float4 db = *(const float4*)(p.dt_bias + l * 32 + c);
;                     const f32x4 v = acc[i][j];
;                     *(float4*)(p.dtb + (size_t)row * 32 + c) =
;                         make_float4(softplusf(v[0] + db.x), softplusf(v[1] + db.y), softplusf(v[2] + db.z), softplusf(v[3] + db.w));
;                 }
	v_pk_add_f32 v[110:111], v[82:83], v[102:103] neg_lo:[0,1] neg_hi:[0,1]
	v_pk_add_f32 v[94:95], v[102:103], v[94:95] neg_lo:[0,1] neg_hi:[0,1]
	v_pk_add_f32 v[82:83], v[82:83], v[110:111] neg_lo:[0,1] neg_hi:[0,1]
	s_nop 0
	v_pk_add_f32 v[82:83], v[82:83], v[102:103] neg_lo:[0,1] neg_hi:[0,1]
	s_nop 0
	v_pk_add_f32 v[66:67], v[66:67], v[82:83]
	v_pk_add_f32 v[82:83], v[94:95], v[100:101] neg_lo:[0,1] neg_hi:[0,1]
	s_nop 0
	v_pk_add_f32 v[66:67], v[82:83], v[66:67]
	s_nop 0
	v_pk_add_f32 v[82:83], v[110:111], v[66:67]
	s_nop 0
	v_pk_mul_f32 v[94:95], v[92:93], v[82:83]
	s_nop 0
	v_pk_mul_f32 v[100:101], v[90:91], v[94:95]
	s_nop 0
	v_pk_fma_f32 v[90:91], v[94:95], v[90:91], v[100:101] neg_lo:[0,0,1] neg_hi:[0,0,1]
	s_nop 0
	v_pk_fma_f32 v[84:85], v[94:95], v[84:85], v[90:91]
	v_pk_add_f32 v[90:91], v[110:111], v[82:83] neg_lo:[0,1] neg_hi:[0,1]
	s_nop 0
	v_pk_add_f32 v[66:67], v[66:67], v[90:91]
	v_pk_add_f32 v[90:91], v[100:101], v[84:85]
	s_nop 0
	v_pk_add_f32 v[102:103], v[82:83], v[90:91] neg_lo:[0,1] neg_hi:[0,1]
	v_pk_add_f32 v[100:101], v[90:91], v[100:101] neg_lo:[0,1] neg_hi:[0,1]
	v_pk_add_f32 v[82:83], v[82:83], v[102:103] neg_lo:[0,1] neg_hi:[0,1]
	s_nop 0
	v_pk_add_f32 v[82:83], v[82:83], v[90:91] neg_lo:[0,1] neg_hi:[0,1]
	s_nop 0
	v_pk_add_f32 v[66:67], v[66:67], v[82:83]
	v_pk_add_f32 v[82:83], v[100:101], v[84:85] neg_lo:[0,1] neg_hi:[0,1]
	s_nop 0
	v_pk_add_f32 v[66:67], v[82:83], v[66:67]
	v_pk_add_f32 v[82:83], v[86:87], v[94:95]
	v_pk_add_f32 v[66:67], v[102:103], v[66:67]
	v_pk_add_f32 v[84:85], v[82:83], v[86:87] neg_lo:[0,1] neg_hi:[0,1]
	v_pk_mul_f32 v[66:67], v[92:93], v[66:67]
	v_pk_add_f32 v[84:85], v[94:95], v[84:85] neg_lo:[0,1] neg_hi:[0,1]
	s_nop 0
	v_pk_add_f32 v[66:67], v[84:85], v[66:67]
	s_nop 0
	v_pk_add_f32 v[86:87], v[82:83], v[66:67]
	s_nop 0
	v_pk_add_f32 v[82:83], v[86:87], v[82:83] neg_lo:[0,1] neg_hi:[0,1]
	v_pk_mul_f32 v[92:93], v[86:87], v[86:87]
	v_pk_add_f32 v[82:83], v[66:67], v[82:83] neg_lo:[0,1] neg_hi:[0,1]
	v_mov_b64_e32 v[66:67], s[0:1]
	v_pk_fma_f32 v[90:91], v[92:93], s[28:29], v[66:67] op_sel_hi:[1,0,0]
	v_ldexp_f32 v84, v86, 1
	v_pk_fma_f32 v[90:91], v[92:93], v[90:91], s[30:31] op_sel_hi:[1,1,0]
	v_pk_mul_f32 v[92:93], v[86:87], v[92:93]
	v_max_f32_e32 v86, 0, v68
	v_mul_f32_e64 v68, |v68|, s2
	v_exp_f32_e32 v100, v68
	v_ldexp_f32 v89, v83, 1
	v_ldexp_f32 v85, v87, 1
	v_pk_mul_f32 v[90:91], v[92:93], v[90:91]
	v_add_f32_e32 v68, 1.0, v100
	v_add_f32_e32 v83, -1.0, v68
	v_sub_f32_e32 v87, v83, v68
	v_add_f32_e32 v87, 1.0, v87
	v_sub_f32_e32 v83, v100, v83
	v_add_f32_e32 v83, v83, v87
	v_frexp_mant_f32_e32 v87, v68
	v_cvt_f64_f32_e32 v[94:95], v68
	v_cmp_gt_f32_e32 vcc, s26, v87
	v_frexp_exp_i32_f64_e32 v87, v[94:95]
	v_pk_add_f32 v[92:93], v[84:85], v[90:91]
	v_subbrev_co_u32_e32 v102, vcc, 0, v87, vcc
	v_sub_u32_e32 v87, 0, v102
	v_ldexp_f32 v94, v68, v87
	v_ldexp_f32 v68, v83, v87
	v_max_f32_e32 v87, 0, v69
	v_mul_f32_e64 v69, |v69|, s2
	v_exp_f32_e32 v101, v69
	v_pk_add_f32 v[84:85], v[92:93], v[84:85] neg_lo:[0,1] neg_hi:[0,1]
	v_ldexp_f32 v82, v82, 1
	v_pk_add_f32 v[84:85], v[90:91], v[84:85] neg_lo:[0,1] neg_hi:[0,1]
	v_add_f32_e32 v69, 1.0, v101
	v_add_f32_e32 v83, -1.0, v69
	v_sub_f32_e32 v95, v83, v69
	v_add_f32_e32 v95, 1.0, v95
	v_sub_f32_e32 v83, v101, v83
	v_add_f32_e32 v83, v83, v95
	v_frexp_mant_f32_e32 v95, v69
	v_cvt_f64_f32_e32 v[110:111], v69
	v_cmp_gt_f32_e32 vcc, s26, v95
	v_frexp_exp_i32_f64_e32 v95, v[110:111]
	v_mov_b32_e32 v91, v85
	v_subbrev_co_u32_e32 v132, vcc, 0, v95, vcc
	v_sub_u32_e32 v103, 0, v132
	v_ldexp_f32 v95, v69, v103
	v_pk_add_f32 v[110:111], v[94:95], 1.0 op_sel_hi:[1,0]
	v_ldexp_f32 v69, v83, v103
	v_pk_add_f32 v[112:113], v[110:111], -1.0 op_sel_hi:[1,0]
	v_pk_add_f32 v[118:119], v[94:95], -1.0 op_sel_hi:[1,0]
	v_pk_add_f32 v[112:113], v[94:95], v[112:113] neg_lo:[0,1] neg_hi:[0,1]
	v_pk_add_f32 v[120:121], v[118:119], 1.0 op_sel_hi:[1,0]
	v_pk_add_f32 v[112:113], v[68:69], v[112:113]
	v_pk_add_f32 v[94:95], v[94:95], v[120:121] neg_lo:[0,1] neg_hi:[0,1]
	v_pk_add_f32 v[114:115], v[110:111], v[112:113]
	v_pk_add_f32 v[68:69], v[68:69], v[94:95]
	v_rcp_f32_e32 v116, v114
	v_rcp_f32_e32 v117, v115
	v_pk_add_f32 v[94:95], v[118:119], v[68:69]
	v_pk_add_f32 v[110:111], v[114:115], v[110:111] neg_lo:[0,1] neg_hi:[0,1]
	v_pk_add_f32 v[118:119], v[94:95], v[118:119] neg_lo:[0,1] neg_hi:[0,1]
	v_pk_add_f32 v[110:111], v[112:113], v[110:111] neg_lo:[0,1] neg_hi:[0,1]
	v_pk_mul_f32 v[112:113], v[94:95], v[116:117]
	v_pk_add_f32 v[68:69], v[68:69], v[118:119] neg_lo:[0,1] neg_hi:[0,1]
	v_pk_mul_f32 v[118:119], v[114:115], v[112:113]
	v_mov_b32_e32 v83, v89
	v_pk_fma_f32 v[120:121], v[112:113], v[114:115], v[118:119] neg_lo:[0,0,1] neg_hi:[0,0,1]
	v_mov_b32_e32 v128, v92
	v_pk_fma_f32 v[120:121], v[112:113], v[110:111], v[120:121]
	v_cmp_neq_f32_e32 vcc, s8, v97
	v_pk_add_f32 v[122:123], v[118:119], v[120:121]
	v_cmp_lt_f32_e64 s[0:1], |v98|, s9
	v_pk_add_f32 v[124:125], v[94:95], v[122:123] neg_lo:[0,1] neg_hi:[0,1]
	v_pk_add_f32 v[118:119], v[122:123], v[118:119] neg_lo:[0,1] neg_hi:[0,1]
	v_pk_add_f32 v[94:95], v[94:95], v[124:125] neg_lo:[0,1] neg_hi:[0,1]
	s_nop 0
	v_pk_add_f32 v[94:95], v[94:95], v[122:123] neg_lo:[0,1] neg_hi:[0,1]
	s_nop 0
	v_pk_add_f32 v[68:69], v[68:69], v[94:95]
	v_pk_add_f32 v[94:95], v[118:119], v[120:121] neg_lo:[0,1] neg_hi:[0,1]
	s_nop 0
	v_pk_add_f32 v[68:69], v[94:95], v[68:69]
	s_nop 0
	v_pk_add_f32 v[94:95], v[124:125], v[68:69]
	s_nop 0
	v_pk_mul_f32 v[118:119], v[116:117], v[94:95]
	s_nop 0
	v_pk_mul_f32 v[120:121], v[114:115], v[118:119]
	s_nop 0
	v_pk_fma_f32 v[114:115], v[118:119], v[114:115], v[120:121] neg_lo:[0,0,1] neg_hi:[0,0,1]
; __device__ __forceinline__ float softplusf(float x) { return fmaxf(x, 0.f) + log1pf(__expf(-fabsf(x))); }
; __device__ void phaseA_tile(const Params& p, int l, int mt, int nt, char* smem) {
;     ...
;                 for (int j = 0; j < 2; ++j) {
;                     const int c = j * 16 + g4 * 4;
;                     const float4 db = *(const float4*)(p.dt_bias + l * 32 + c);
;                     const f32x4 v = acc[i][j];
;                     *(float4*)(p.dtb + (size_t)row * 32 + c) =
;                         make_float4(softplusf(v[0] + db.x), softplusf(v[1] + db.y), softplusf(v[2] + db.z), softplusf(v[3] + db.w));
;                 }
	s_nop 0
	v_pk_fma_f32 v[110:111], v[118:119], v[110:111], v[114:115]
	v_pk_add_f32 v[114:115], v[124:125], v[94:95] neg_lo:[0,1] neg_hi:[0,1]
	s_nop 0
	v_pk_add_f32 v[68:69], v[68:69], v[114:115]
	v_pk_add_f32 v[114:115], v[120:121], v[110:111]
	s_nop 0
	v_pk_add_f32 v[122:123], v[94:95], v[114:115] neg_lo:[0,1] neg_hi:[0,1]
	v_pk_add_f32 v[120:121], v[114:115], v[120:121] neg_lo:[0,1] neg_hi:[0,1]
	v_pk_add_f32 v[94:95], v[94:95], v[122:123] neg_lo:[0,1] neg_hi:[0,1]
	s_nop 0
	v_pk_add_f32 v[94:95], v[94:95], v[114:115] neg_lo:[0,1] neg_hi:[0,1]
	s_nop 0
	v_pk_add_f32 v[68:69], v[68:69], v[94:95]
	v_pk_add_f32 v[94:95], v[120:121], v[110:111] neg_lo:[0,1] neg_hi:[0,1]
	s_nop 0
	v_pk_add_f32 v[68:69], v[94:95], v[68:69]
	v_pk_add_f32 v[94:95], v[112:113], v[118:119]
	v_pk_add_f32 v[68:69], v[122:123], v[68:69]
	v_pk_add_f32 v[110:111], v[94:95], v[112:113] neg_lo:[0,1] neg_hi:[0,1]
	v_pk_mul_f32 v[68:69], v[116:117], v[68:69]
	v_pk_add_f32 v[110:111], v[118:119], v[110:111] neg_lo:[0,1] neg_hi:[0,1]
	s_nop 0
	v_pk_add_f32 v[68:69], v[110:111], v[68:69]
	s_nop 0
	v_pk_add_f32 v[110:111], v[94:95], v[68:69]
	s_nop 0
	v_pk_add_f32 v[94:95], v[110:111], v[94:95] neg_lo:[0,1] neg_hi:[0,1]
	v_pk_mul_f32 v[114:115], v[110:111], v[110:111]
	v_pk_add_f32 v[68:69], v[68:69], v[94:95] neg_lo:[0,1] neg_hi:[0,1]
	v_pk_fma_f32 v[116:117], v[114:115], s[28:29], v[66:67] op_sel_hi:[1,0,0]
	v_ldexp_f32 v112, v68, 1
	v_ldexp_f32 v103, v69, 1
	v_lshl_add_u64 v[68:69], s[10:11], 0, v[80:81]
	v_cvt_f32_i32_e32 v81, v99
	v_cvt_f32_i32_e32 v80, v88
	v_ldexp_f32 v94, v110, 1
	v_pk_fma_f32 v[116:117], v[114:115], v[116:117], s[30:31] op_sel_hi:[1,1,0]
	v_ldexp_f32 v95, v111, 1
	v_pk_mul_f32 v[110:111], v[110:111], v[114:115]
	v_pk_mul_f32 v[114:115], v[80:81], s[12:13] op_sel_hi:[1,0]
	v_mov_b32_e32 v113, v103
	v_pk_fma_f32 v[118:119], v[80:81], s[12:13], v[114:115] op_sel_hi:[1,0,1] neg_lo:[0,0,1] neg_hi:[0,0,1]
	v_mov_b32_e32 v90, v114
	v_pk_fma_f32 v[80:81], v[80:81], s[14:15], v[118:119] op_sel_hi:[1,0,1]
	v_mov_b32_e32 v125, v115
	v_mov_b32_e32 v88, v80
	v_pk_add_f32 v[90:91], v[90:91], v[88:89]
	v_pk_add_f32 v[88:89], v[82:83], v[84:85]
	v_mov_b32_e32 v85, v93
	v_mov_b32_e32 v83, v89
	v_pk_add_f32 v[118:119], v[114:115], v[80:81]
	v_pk_add_f32 v[82:83], v[82:83], v[84:85]
	v_pk_add_f32 v[84:85], v[92:93], v[88:89]
	v_mov_b32_e32 v129, v119
	v_pk_add_f32 v[120:121], v[118:119], v[84:85]
	v_mov_b32_e32 v126, v84
	v_mov_b32_e32 v127, v121
	v_pk_add_f32 v[126:127], v[126:127], v[128:129] neg_lo:[0,1] neg_hi:[0,1]
	v_mov_b32_e32 v122, v120
	v_mov_b32_e32 v123, v119
	v_mov_b32_e32 v124, v118
	v_mov_b32_e32 v128, v118
	v_mov_b32_e32 v129, v121
	v_mov_b32_e32 v115, v127
	v_pk_add_f32 v[122:123], v[122:123], v[124:125] neg_lo:[0,1] neg_hi:[0,1]
	v_mov_b32_e32 v124, v84
	v_mov_b32_e32 v125, v81
	v_pk_add_f32 v[114:115], v[128:129], v[114:115] neg_lo:[0,1] neg_hi:[0,1]
	v_pk_add_f32 v[124:125], v[124:125], v[122:123] neg_lo:[0,1] neg_hi:[0,1]
	v_mov_b32_e32 v128, v114
	v_mov_b32_e32 v129, v123
	v_mov_b32_e32 v130, v120
	v_mov_b32_e32 v131, v85
	v_mov_b32_e32 v123, v93
	v_pk_add_f32 v[128:129], v[80:81], v[128:129] neg_lo:[0,1] neg_hi:[0,1]
	v_pk_add_f32 v[122:123], v[130:131], v[122:123] neg_lo:[0,1] neg_hi:[0,1]
	v_mov_b32_e32 v81, v119
	v_pk_add_f32 v[84:85], v[84:85], v[92:93] neg_lo:[0,1] neg_hi:[0,1]
	v_pk_add_f32 v[90:91], v[90:91], v[122:123] neg_lo:[0,1] neg_hi:[0,1]
	v_pk_add_f32 v[80:81], v[80:81], v[114:115] neg_lo:[0,1] neg_hi:[0,1]
	v_pk_add_f32 v[82:83], v[82:83], v[126:127] neg_lo:[0,1] neg_hi:[0,1]
	v_pk_add_f32 v[84:85], v[88:89], v[84:85] neg_lo:[0,1] neg_hi:[0,1]
	v_pk_add_f32 v[88:89], v[82:83], v[80:81]
	v_mov_b32_e32 v81, v125
	v_mov_b32_e32 v83, v91
	v_pk_add_f32 v[92:93], v[124:125], v[90:91]
	v_pk_add_f32 v[82:83], v[80:81], v[82:83]
	v_mov_b32_e32 v90, v88
	v_pk_add_f32 v[82:83], v[82:83], v[128:129] neg_lo:[0,1] neg_hi:[0,1]
	v_mov_b32_e32 v91, v93
	v_pk_add_f32 v[90:91], v[90:91], v[82:83] neg_lo:[0,1] neg_hi:[0,1]
	v_pk_add_f32 v[82:83], v[84:85], v[82:83] neg_lo:[0,1] neg_hi:[0,1]
	v_pk_add_f32 v[80:81], v[80:81], v[90:91] neg_lo:[0,1] neg_hi:[0,1]
	v_lshl_add_u64 v[68:69], v[68:69], 0, v[0:1]
	v_pk_add_f32 v[80:81], v[82:83], v[80:81]
	v_pk_add_f32 v[82:83], v[92:93], v[88:89]
	s_nop 0
	v_pk_add_f32 v[84:85], v[120:121], v[82:83]
	s_nop 0
	v_pk_add_f32 v[88:89], v[84:85], v[120:121] neg_lo:[0,1] neg_hi:[0,1]
	s_nop 0
	v_pk_add_f32 v[82:83], v[82:83], v[88:89] neg_lo:[0,1] neg_hi:[0,1]
	s_nop 0
	v_pk_add_f32 v[80:81], v[80:81], v[82:83]
	s_nop 0
	v_pk_add_f32 v[80:81], v[84:85], v[80:81]
	v_pk_mul_f32 v[84:85], v[110:111], v[116:117]
	v_cndmask_b32_e32 v80, v160, v80, vcc
	v_cmp_neq_f32_e32 vcc, s8, v98
	v_pk_add_f32 v[88:89], v[94:95], v[84:85]
	s_nop 0
	v_cndmask_b32_e32 v81, v160, v81, vcc
	v_cmp_ngt_f32_e32 vcc, -1.0, v98
	v_pk_add_f32 v[92:93], v[88:89], v[94:95] neg_lo:[0,1] neg_hi:[0,1]
	v_mov_b32_e32 v116, v88
	v_cndmask_b32_e32 v81, v161, v81, vcc
	v_cmp_ngt_f32_e32 vcc, -1.0, v97
	v_pk_add_f32 v[84:85], v[84:85], v[92:93] neg_lo:[0,1] neg_hi:[0,1]
	s_nop 0
	v_cndmask_b32_e32 v80, v161, v80, vcc
	v_cmp_neq_f32_e32 vcc, -1.0, v97
	v_pk_add_f32 v[94:95], v[112:113], v[84:85]
	v_mov_b32_e32 v93, v85
	v_cndmask_b32_e32 v80, v162, v80, vcc
	v_cmp_neq_f32_e32 vcc, -1.0, v98
	v_mov_b32_e32 v113, v95
	v_mov_b32_e32 v85, v89
	v_cndmask_b32_e32 v81, v162, v81, vcc
	v_cmp_lt_f32_e64 vcc, |v97|, s9
	v_cndmask_b32_e64 v81, v81, v98, s[0:1]
	v_pk_add_f32 v[98:99], v[88:89], v[94:95]
	v_cndmask_b32_e32 v80, v80, v97, vcc
	v_pk_add_f32 v[78:79], v[78:79], v[80:81]
	v_cvt_f32_i32_e32 v81, v132
	v_cvt_f32_i32_e32 v80, v102
	v_mov_b32_e32 v114, v98
; __device__ __forceinline__ float softplusf(float x) { return fmaxf(x, 0.f) + log1pf(__expf(-fabsf(x))); }
; __device__ void phaseA_tile(const Params& p, int l, int mt, int nt, char* smem) {
;     ...
;                 for (int j = 0; j < 2; ++j) {
;                     const int c = j * 16 + g4 * 4;
;                     const float4 db = *(const float4*)(p.dt_bias + l * 32 + c);
;                     const f32x4 v = acc[i][j];
;                     *(float4*)(p.dtb + (size_t)row * 32 + c) =
;                         make_float4(softplusf(v[0] + db.x), softplusf(v[1] + db.y), softplusf(v[2] + db.z), softplusf(v[3] + db.w));
	v_pk_add_f32 v[84:85], v[112:113], v[84:85]
	v_mov_b32_e32 v119, v99
	v_pk_mul_f32 v[82:83], v[80:81], s[12:13] op_sel_hi:[1,0]
	v_cmp_neq_f32_e32 vcc, s8, v100
	v_pk_fma_f32 v[90:91], v[80:81], s[12:13], v[82:83] op_sel_hi:[1,0,1] neg_lo:[0,0,1] neg_hi:[0,0,1]
	v_mov_b32_e32 v92, v82
	v_pk_fma_f32 v[80:81], v[80:81], s[14:15], v[90:91] op_sel_hi:[1,0,1]
	v_mov_b32_e32 v113, v83
	v_pk_add_f32 v[90:91], v[82:83], v[80:81]
	v_mov_b32_e32 v102, v80
	v_pk_add_f32 v[92:93], v[92:93], v[102:103]
	v_pk_add_f32 v[102:103], v[90:91], v[98:99]
	v_mov_b32_e32 v117, v91
	v_mov_b32_e32 v115, v103
	v_pk_add_f32 v[114:115], v[114:115], v[116:117] neg_lo:[0,1] neg_hi:[0,1]
	v_mov_b32_e32 v110, v102
	v_mov_b32_e32 v111, v91
	v_mov_b32_e32 v112, v90
	v_mov_b32_e32 v116, v90
	v_mov_b32_e32 v117, v103
	v_mov_b32_e32 v83, v115
	v_pk_add_f32 v[110:111], v[110:111], v[112:113] neg_lo:[0,1] neg_hi:[0,1]
	v_mov_b32_e32 v112, v98
	v_mov_b32_e32 v113, v81
	v_pk_add_f32 v[82:83], v[116:117], v[82:83] neg_lo:[0,1] neg_hi:[0,1]
	v_pk_add_f32 v[112:113], v[112:113], v[110:111] neg_lo:[0,1] neg_hi:[0,1]
	v_mov_b32_e32 v116, v82
	v_mov_b32_e32 v117, v111
	v_mov_b32_e32 v118, v102
	v_mov_b32_e32 v111, v89
	v_pk_add_f32 v[116:117], v[80:81], v[116:117] neg_lo:[0,1] neg_hi:[0,1]
	v_pk_add_f32 v[110:111], v[118:119], v[110:111] neg_lo:[0,1] neg_hi:[0,1]
	v_mov_b32_e32 v81, v91
	v_pk_add_f32 v[92:93], v[92:93], v[110:111] neg_lo:[0,1] neg_hi:[0,1]
	v_pk_add_f32 v[80:81], v[80:81], v[82:83] neg_lo:[0,1] neg_hi:[0,1]
	v_pk_add_f32 v[82:83], v[84:85], v[114:115] neg_lo:[0,1] neg_hi:[0,1]
	v_pk_add_f32 v[90:91], v[112:113], v[92:93]
	v_pk_add_f32 v[84:85], v[82:83], v[80:81]
	v_mov_b32_e32 v81, v113
	v_mov_b32_e32 v83, v93
	v_pk_add_f32 v[82:83], v[80:81], v[82:83]
	v_pk_add_f32 v[88:89], v[98:99], v[88:89] neg_lo:[0,1] neg_hi:[0,1]
	v_pk_add_f32 v[82:83], v[82:83], v[116:117] neg_lo:[0,1] neg_hi:[0,1]
	v_mov_b32_e32 v92, v84
	v_mov_b32_e32 v93, v91
	v_pk_add_f32 v[88:89], v[94:95], v[88:89] neg_lo:[0,1] neg_hi:[0,1]
	v_pk_add_f32 v[92:93], v[92:93], v[82:83] neg_lo:[0,1] neg_hi:[0,1]
	v_pk_add_f32 v[82:83], v[88:89], v[82:83] neg_lo:[0,1] neg_hi:[0,1]
	v_pk_add_f32 v[80:81], v[80:81], v[92:93] neg_lo:[0,1] neg_hi:[0,1]
	v_cmp_lt_f32_e64 s[0:1], |v101|, s9
	v_pk_add_f32 v[80:81], v[82:83], v[80:81]
	v_pk_add_f32 v[82:83], v[90:91], v[84:85]
	s_nop 0
	v_pk_add_f32 v[84:85], v[102:103], v[82:83]
	s_nop 0
	v_pk_add_f32 v[88:89], v[84:85], v[102:103] neg_lo:[0,1] neg_hi:[0,1]
	s_nop 0
	v_pk_add_f32 v[82:83], v[82:83], v[88:89] neg_lo:[0,1] neg_hi:[0,1]
	s_nop 0
	v_pk_add_f32 v[80:81], v[80:81], v[82:83]
	s_nop 0
	v_pk_add_f32 v[80:81], v[84:85], v[80:81]
	s_nop 0
	v_cndmask_b32_e32 v80, v160, v80, vcc
	v_cmp_neq_f32_e32 vcc, s8, v101
	s_nop 1
	v_cndmask_b32_e32 v81, v160, v81, vcc
	v_cmp_ngt_f32_e32 vcc, -1.0, v101
	s_nop 1
	v_cndmask_b32_e32 v81, v161, v81, vcc
	v_cmp_ngt_f32_e32 vcc, -1.0, v100
	s_nop 1
	v_cndmask_b32_e32 v80, v161, v80, vcc
	v_cmp_neq_f32_e32 vcc, -1.0, v100
	s_nop 1
	v_cndmask_b32_e32 v80, v162, v80, vcc
	v_cmp_neq_f32_e32 vcc, -1.0, v101
	s_nop 1
	v_cndmask_b32_e32 v81, v162, v81, vcc
	v_cmp_lt_f32_e64 vcc, |v100|, s9
	v_cndmask_b32_e64 v81, v81, v101, s[0:1]
	s_nop 0
	v_cndmask_b32_e32 v80, v80, v100, vcc
	v_pk_add_f32 v[80:81], v[86:87], v[80:81]
	global_store_dwordx4 v[68:69], v[78:81], off
	global_load_dwordx4 v[78:81], v0, s[74:75] offset:64
	s_waitcnt vmcnt(0)
	v_add_f32_e32 v82, v58, v78
	v_max_f32_e32 v78, 0, v82
	v_mul_f32_e64 v82, |v82|, s2
	v_exp_f32_e32 v97, v82
	s_nop 0
	v_add_f32_e32 v84, 1.0, v97
	v_add_f32_e32 v82, -1.0, v84
	v_sub_f32_e32 v83, v82, v84
	v_add_f32_e32 v83, 1.0, v83
	v_sub_f32_e32 v82, v97, v82
	v_add_f32_e32 v85, v82, v83
	v_frexp_mant_f32_e32 v82, v84
	v_cmp_gt_f32_e32 vcc, s26, v82
	v_cvt_f64_f32_e32 v[82:83], v84
	v_frexp_exp_i32_f64_e32 v82, v[82:83]
	v_subbrev_co_u32_e32 v120, vcc, 0, v82, vcc
	v_sub_u32_e32 v83, 0, v120
	v_ldexp_f32 v82, v84, v83
	v_ldexp_f32 v84, v85, v83
	v_add_f32_e32 v83, v59, v79
	v_max_f32_e32 v79, 0, v83
	v_mul_f32_e64 v83, |v83|, s2
	v_exp_f32_e32 v128, v83
	s_nop 0
	v_add_f32_e32 v83, 1.0, v128
	v_add_f32_e32 v85, -1.0, v83
	v_sub_f32_e32 v86, v85, v83
	v_add_f32_e32 v86, 1.0, v86
	v_sub_f32_e32 v85, v128, v85
	v_add_f32_e32 v85, v85, v86
	v_frexp_mant_f32_e32 v86, v83
	v_cmp_gt_f32_e32 vcc, s26, v86
	v_cvt_f64_f32_e32 v[86:87], v83
	v_frexp_exp_i32_f64_e32 v86, v[86:87]
	v_subbrev_co_u32_e32 v121, vcc, 0, v86, vcc
	v_sub_u32_e32 v86, 0, v121
	v_ldexp_f32 v83, v83, v86
	v_ldexp_f32 v85, v85, v86
	v_pk_add_f32 v[86:87], v[82:83], 1.0 op_sel_hi:[1,0]
	v_pk_add_f32 v[94:95], v[82:83], -1.0 op_sel_hi:[1,0]
	v_pk_add_f32 v[88:89], v[86:87], -1.0 op_sel_hi:[1,0]
	v_pk_add_f32 v[98:99], v[94:95], 1.0 op_sel_hi:[1,0]
	v_pk_add_f32 v[88:89], v[82:83], v[88:89] neg_lo:[0,1] neg_hi:[0,1]
	v_pk_add_f32 v[82:83], v[82:83], v[98:99] neg_lo:[0,1] neg_hi:[0,1]
	v_pk_add_f32 v[88:89], v[84:85], v[88:89]
	v_pk_add_f32 v[82:83], v[84:85], v[82:83]
	v_pk_add_f32 v[90:91], v[86:87], v[88:89]
	v_pk_add_f32 v[84:85], v[94:95], v[82:83]
	v_rcp_f32_e32 v92, v90
	v_rcp_f32_e32 v93, v91
	v_pk_add_f32 v[86:87], v[90:91], v[86:87] neg_lo:[0,1] neg_hi:[0,1]
	v_pk_add_f32 v[94:95], v[84:85], v[94:95] neg_lo:[0,1] neg_hi:[0,1]
	v_pk_add_f32 v[86:87], v[88:89], v[86:87] neg_lo:[0,1] neg_hi:[0,1]
	v_pk_mul_f32 v[88:89], v[84:85], v[92:93]
	v_pk_add_f32 v[82:83], v[82:83], v[94:95] neg_lo:[0,1] neg_hi:[0,1]
	v_pk_mul_f32 v[94:95], v[90:91], v[88:89]
	v_cmp_lt_f32_e64 s[0:1], |v128|, s9
	v_pk_fma_f32 v[98:99], v[88:89], v[90:91], v[94:95] neg_lo:[0,0,1] neg_hi:[0,0,1]
	s_nop 0
	v_pk_fma_f32 v[98:99], v[88:89], v[86:87], v[98:99]
; __device__ __forceinline__ float softplusf(float x) { return fmaxf(x, 0.f) + log1pf(__expf(-fabsf(x))); }
; __device__ void phaseA_tile(const Params& p, int l, int mt, int nt, char* smem) {
;     ...
;                 for (int j = 0; j < 2; ++j) {
;                     const int c = j * 16 + g4 * 4;
;                     const float4 db = *(const float4*)(p.dt_bias + l * 32 + c);
;                     const f32x4 v = acc[i][j];
;                     *(float4*)(p.dtb + (size_t)row * 32 + c) =
;                         make_float4(softplusf(v[0] + db.x), softplusf(v[1] + db.y), softplusf(v[2] + db.z), softplusf(v[3] + db.w));
	s_nop 0
	v_pk_add_f32 v[100:101], v[94:95], v[98:99]
	s_nop 0
	v_pk_add_f32 v[102:103], v[84:85], v[100:101] neg_lo:[0,1] neg_hi:[0,1]
	v_pk_add_f32 v[94:95], v[100:101], v[94:95] neg_lo:[0,1] neg_hi:[0,1]
	v_pk_add_f32 v[84:85], v[84:85], v[102:103] neg_lo:[0,1] neg_hi:[0,1]
	s_nop 0
	v_pk_add_f32 v[84:85], v[84:85], v[100:101] neg_lo:[0,1] neg_hi:[0,1]
	s_nop 0
	v_pk_add_f32 v[82:83], v[82:83], v[84:85]
	v_pk_add_f32 v[84:85], v[94:95], v[98:99] neg_lo:[0,1] neg_hi:[0,1]
	s_nop 0
	v_pk_add_f32 v[82:83], v[84:85], v[82:83]
	s_nop 0
	v_pk_add_f32 v[84:85], v[102:103], v[82:83]
	s_nop 0
	v_pk_mul_f32 v[94:95], v[92:93], v[84:85]
	s_nop 0
	v_pk_mul_f32 v[98:99], v[90:91], v[94:95]
	s_nop 0
	v_pk_fma_f32 v[90:91], v[94:95], v[90:91], v[98:99] neg_lo:[0,0,1] neg_hi:[0,0,1]
	s_nop 0
	v_pk_fma_f32 v[86:87], v[94:95], v[86:87], v[90:91]
	v_pk_add_f32 v[90:91], v[102:103], v[84:85] neg_lo:[0,1] neg_hi:[0,1]
	s_nop 0
	v_pk_add_f32 v[82:83], v[82:83], v[90:91]
	v_pk_add_f32 v[90:91], v[98:99], v[86:87]
	s_nop 0
	v_pk_add_f32 v[100:101], v[84:85], v[90:91] neg_lo:[0,1] neg_hi:[0,1]
	v_pk_add_f32 v[98:99], v[90:91], v[98:99] neg_lo:[0,1] neg_hi:[0,1]
	v_pk_add_f32 v[84:85], v[84:85], v[100:101] neg_lo:[0,1] neg_hi:[0,1]
	s_nop 0
	v_pk_add_f32 v[84:85], v[84:85], v[90:91] neg_lo:[0,1] neg_hi:[0,1]
	s_nop 0
	v_pk_add_f32 v[82:83], v[82:83], v[84:85]
	v_pk_add_f32 v[84:85], v[98:99], v[86:87] neg_lo:[0,1] neg_hi:[0,1]
	s_nop 0
	v_pk_add_f32 v[82:83], v[84:85], v[82:83]
	v_pk_add_f32 v[84:85], v[88:89], v[94:95]
	v_pk_add_f32 v[82:83], v[100:101], v[82:83]
	v_pk_add_f32 v[86:87], v[84:85], v[88:89] neg_lo:[0,1] neg_hi:[0,1]
	v_pk_mul_f32 v[82:83], v[92:93], v[82:83]
	v_pk_add_f32 v[86:87], v[94:95], v[86:87] neg_lo:[0,1] neg_hi:[0,1]
	s_nop 0
	v_pk_add_f32 v[82:83], v[86:87], v[82:83]
	s_nop 0
	v_pk_add_f32 v[86:87], v[84:85], v[82:83]
	s_nop 0
	v_pk_add_f32 v[84:85], v[86:87], v[84:85] neg_lo:[0,1] neg_hi:[0,1]
	v_pk_mul_f32 v[88:89], v[86:87], v[86:87]
	v_pk_add_f32 v[82:83], v[82:83], v[84:85] neg_lo:[0,1] neg_hi:[0,1]
	v_pk_fma_f32 v[90:91], v[88:89], s[28:29], v[66:67] op_sel_hi:[1,0,0]
	v_ldexp_f32 v93, v83, 1
	v_add_f32_e32 v83, v60, v80
	v_max_f32_e32 v80, 0, v83
	v_mul_f32_e64 v83, |v83|, s2
	v_exp_f32_e32 v129, v83
	v_ldexp_f32 v84, v86, 1
	v_pk_fma_f32 v[90:91], v[88:89], v[90:91], s[30:31] op_sel_hi:[1,1,0]
	v_ldexp_f32 v85, v87, 1
	v_add_f32_e32 v83, 1.0, v129
	v_pk_mul_f32 v[86:87], v[86:87], v[88:89]
	v_add_f32_e32 v88, -1.0, v83
	v_sub_f32_e32 v89, v88, v83
	v_add_f32_e32 v89, 1.0, v89
	v_sub_f32_e32 v88, v129, v88
	v_add_f32_e32 v92, v88, v89
	v_frexp_mant_f32_e32 v88, v83
	v_cmp_gt_f32_e32 vcc, s26, v88
	v_cvt_f64_f32_e32 v[88:89], v83
	v_frexp_exp_i32_f64_e32 v88, v[88:89]
	v_subbrev_co_u32_e32 v130, vcc, 0, v88, vcc
	v_sub_u32_e32 v89, 0, v130
	v_ldexp_f32 v88, v83, v89
	v_add_f32_e32 v83, v61, v81
	v_max_f32_e32 v81, 0, v83
	v_mul_f32_e64 v83, |v83|, s2
	v_exp_f32_e32 v131, v83
	v_ldexp_f32 v94, v92, v89
	v_pk_mul_f32 v[86:87], v[86:87], v[90:91]
	v_ldexp_f32 v82, v82, 1
	v_add_f32_e32 v83, 1.0, v131
	v_add_f32_e32 v89, -1.0, v83
	v_sub_f32_e32 v92, v89, v83
	v_add_f32_e32 v92, 1.0, v92
	v_sub_f32_e32 v89, v131, v89
	v_add_f32_e32 v92, v89, v92
	v_frexp_mant_f32_e32 v89, v83
	v_cvt_f64_f32_e32 v[98:99], v83
	v_cmp_gt_f32_e32 vcc, s26, v89
	v_frexp_exp_i32_f64_e32 v89, v[98:99]
	v_pk_add_f32 v[90:91], v[84:85], v[86:87]
	v_subbrev_co_u32_e32 v132, vcc, 0, v89, vcc
	v_sub_u32_e32 v95, 0, v132
	v_ldexp_f32 v89, v83, v95
	v_pk_add_f32 v[98:99], v[88:89], 1.0 op_sel_hi:[1,0]
	v_ldexp_f32 v95, v92, v95
	v_pk_add_f32 v[100:101], v[98:99], -1.0 op_sel_hi:[1,0]
	v_pk_add_f32 v[112:113], v[88:89], -1.0 op_sel_hi:[1,0]
	v_pk_add_f32 v[100:101], v[88:89], v[100:101] neg_lo:[0,1] neg_hi:[0,1]
	v_pk_add_f32 v[114:115], v[112:113], 1.0 op_sel_hi:[1,0]
	v_pk_add_f32 v[100:101], v[94:95], v[100:101]
	v_pk_add_f32 v[88:89], v[88:89], v[114:115] neg_lo:[0,1] neg_hi:[0,1]
	v_pk_add_f32 v[102:103], v[98:99], v[100:101]
	v_pk_add_f32 v[88:89], v[94:95], v[88:89]
	v_rcp_f32_e32 v110, v102
	v_rcp_f32_e32 v111, v103
	v_pk_add_f32 v[94:95], v[112:113], v[88:89]
	v_pk_add_f32 v[98:99], v[102:103], v[98:99] neg_lo:[0,1] neg_hi:[0,1]
	v_pk_add_f32 v[112:113], v[94:95], v[112:113] neg_lo:[0,1] neg_hi:[0,1]
	v_pk_add_f32 v[98:99], v[100:101], v[98:99] neg_lo:[0,1] neg_hi:[0,1]
	v_pk_mul_f32 v[100:101], v[94:95], v[110:111]
	v_pk_add_f32 v[88:89], v[88:89], v[112:113] neg_lo:[0,1] neg_hi:[0,1]
	v_pk_mul_f32 v[112:113], v[102:103], v[100:101]
	v_pk_add_f32 v[84:85], v[90:91], v[84:85] neg_lo:[0,1] neg_hi:[0,1]
	v_pk_fma_f32 v[114:115], v[100:101], v[102:103], v[112:113] neg_lo:[0,0,1] neg_hi:[0,0,1]
	v_pk_add_f32 v[84:85], v[86:87], v[84:85] neg_lo:[0,1] neg_hi:[0,1]
	v_pk_fma_f32 v[114:115], v[100:101], v[98:99], v[114:115]
	v_mov_b32_e32 v87, v85
	v_pk_add_f32 v[116:117], v[112:113], v[114:115]
	v_mov_b32_e32 v83, v93
	v_pk_add_f32 v[118:119], v[94:95], v[116:117] neg_lo:[0,1] neg_hi:[0,1]
	v_pk_add_f32 v[112:113], v[116:117], v[112:113] neg_lo:[0,1] neg_hi:[0,1]
	v_pk_add_f32 v[94:95], v[94:95], v[118:119] neg_lo:[0,1] neg_hi:[0,1]
	v_mov_b32_e32 v124, v90
	v_pk_add_f32 v[94:95], v[94:95], v[116:117] neg_lo:[0,1] neg_hi:[0,1]
	v_cmp_neq_f32_e32 vcc, s8, v97
	v_pk_add_f32 v[88:89], v[88:89], v[94:95]
	v_pk_add_f32 v[94:95], v[112:113], v[114:115] neg_lo:[0,1] neg_hi:[0,1]
	s_nop 0
	v_pk_add_f32 v[88:89], v[94:95], v[88:89]
	s_nop 0
	v_pk_add_f32 v[94:95], v[118:119], v[88:89]
	s_nop 0
	v_pk_mul_f32 v[112:113], v[110:111], v[94:95]
	s_nop 0
	v_pk_mul_f32 v[114:115], v[102:103], v[112:113]
	s_nop 0
	v_pk_fma_f32 v[102:103], v[112:113], v[102:103], v[114:115] neg_lo:[0,0,1] neg_hi:[0,0,1]
; __device__ __forceinline__ float softplusf(float x) { return fmaxf(x, 0.f) + log1pf(__expf(-fabsf(x))); }
; __device__ void phaseA_tile(const Params& p, int l, int mt, int nt, char* smem) {
;     ...
;                 for (int j = 0; j < 2; ++j) {
;                     const int c = j * 16 + g4 * 4;
;                     const float4 db = *(const float4*)(p.dt_bias + l * 32 + c);
;                     const f32x4 v = acc[i][j];
;                     *(float4*)(p.dtb + (size_t)row * 32 + c) =
;                         make_float4(softplusf(v[0] + db.x), softplusf(v[1] + db.y), softplusf(v[2] + db.z), softplusf(v[3] + db.w));
	s_nop 0
	v_pk_fma_f32 v[98:99], v[112:113], v[98:99], v[102:103]
	v_pk_add_f32 v[102:103], v[118:119], v[94:95] neg_lo:[0,1] neg_hi:[0,1]
	s_nop 0
	v_pk_add_f32 v[88:89], v[88:89], v[102:103]
	v_pk_add_f32 v[102:103], v[114:115], v[98:99]
	s_nop 0
	v_pk_add_f32 v[116:117], v[94:95], v[102:103] neg_lo:[0,1] neg_hi:[0,1]
	v_pk_add_f32 v[114:115], v[102:103], v[114:115] neg_lo:[0,1] neg_hi:[0,1]
	v_pk_add_f32 v[94:95], v[94:95], v[116:117] neg_lo:[0,1] neg_hi:[0,1]
	s_nop 0
	v_pk_add_f32 v[94:95], v[94:95], v[102:103] neg_lo:[0,1] neg_hi:[0,1]
	s_nop 0
	v_pk_add_f32 v[88:89], v[88:89], v[94:95]
	v_pk_add_f32 v[94:95], v[114:115], v[98:99] neg_lo:[0,1] neg_hi:[0,1]
	s_nop 0
	v_pk_add_f32 v[88:89], v[94:95], v[88:89]
	v_pk_add_f32 v[94:95], v[100:101], v[112:113]
	v_pk_add_f32 v[88:89], v[116:117], v[88:89]
	v_pk_add_f32 v[98:99], v[94:95], v[100:101] neg_lo:[0,1] neg_hi:[0,1]
	v_pk_mul_f32 v[88:89], v[110:111], v[88:89]
	v_pk_add_f32 v[98:99], v[112:113], v[98:99] neg_lo:[0,1] neg_hi:[0,1]
	s_nop 0
	v_pk_add_f32 v[88:89], v[98:99], v[88:89]
	s_nop 0
	v_pk_add_f32 v[98:99], v[94:95], v[88:89]
	s_nop 0
	v_pk_mul_f32 v[100:101], v[98:99], v[98:99]
	v_pk_add_f32 v[94:95], v[98:99], v[94:95] neg_lo:[0,1] neg_hi:[0,1]
	v_pk_fma_f32 v[102:103], v[100:101], s[28:29], v[66:67] op_sel_hi:[1,0,0]
	v_pk_add_f32 v[88:89], v[88:89], v[94:95] neg_lo:[0,1] neg_hi:[0,1]
	v_ldexp_f32 v94, v98, 1
	v_pk_fma_f32 v[102:103], v[100:101], v[102:103], s[30:31] op_sel_hi:[1,1,0]
	v_ldexp_f32 v95, v99, 1
	v_pk_mul_f32 v[98:99], v[98:99], v[100:101]
	v_cvt_f32_i32_e32 v101, v121
	v_cvt_f32_i32_e32 v100, v120
	v_ldexp_f32 v111, v89, 1
	v_ldexp_f32 v88, v88, 1
	v_mov_b32_e32 v89, v111
	v_pk_mul_f32 v[112:113], v[100:101], s[12:13] op_sel_hi:[1,0]
	s_nop 0
	v_pk_fma_f32 v[114:115], v[100:101], s[12:13], v[112:113] op_sel_hi:[1,0,1] neg_lo:[0,0,1] neg_hi:[0,0,1]
	v_mov_b32_e32 v86, v112
	v_pk_fma_f32 v[100:101], v[100:101], s[14:15], v[114:115] op_sel_hi:[1,0,1]
	v_mov_b32_e32 v121, v113
	v_mov_b32_e32 v92, v100
	v_pk_add_f32 v[86:87], v[86:87], v[92:93]
	v_pk_add_f32 v[92:93], v[82:83], v[84:85]
	v_mov_b32_e32 v85, v91
	v_mov_b32_e32 v83, v93
	v_pk_add_f32 v[114:115], v[112:113], v[100:101]
	v_pk_add_f32 v[82:83], v[82:83], v[84:85]
	v_pk_add_f32 v[84:85], v[90:91], v[92:93]
	v_mov_b32_e32 v125, v115
	v_pk_add_f32 v[116:117], v[114:115], v[84:85]
	v_mov_b32_e32 v122, v84
	v_mov_b32_e32 v123, v117
	v_pk_add_f32 v[122:123], v[122:123], v[124:125] neg_lo:[0,1] neg_hi:[0,1]
	v_mov_b32_e32 v118, v116
	v_mov_b32_e32 v119, v115
	v_mov_b32_e32 v120, v114
	v_mov_b32_e32 v124, v114
	v_mov_b32_e32 v125, v117
	v_mov_b32_e32 v113, v123
	v_pk_add_f32 v[118:119], v[118:119], v[120:121] neg_lo:[0,1] neg_hi:[0,1]
	v_mov_b32_e32 v120, v84
	v_mov_b32_e32 v121, v101
	v_pk_add_f32 v[112:113], v[124:125], v[112:113] neg_lo:[0,1] neg_hi:[0,1]
	v_pk_add_f32 v[120:121], v[120:121], v[118:119] neg_lo:[0,1] neg_hi:[0,1]
	v_mov_b32_e32 v124, v112
	v_mov_b32_e32 v125, v119
	v_mov_b32_e32 v126, v116
	v_mov_b32_e32 v127, v85
	v_mov_b32_e32 v119, v91
	v_pk_add_f32 v[124:125], v[100:101], v[124:125] neg_lo:[0,1] neg_hi:[0,1]
	v_pk_add_f32 v[118:119], v[126:127], v[118:119] neg_lo:[0,1] neg_hi:[0,1]
	v_mov_b32_e32 v101, v115
	v_pk_add_f32 v[84:85], v[84:85], v[90:91] neg_lo:[0,1] neg_hi:[0,1]
	v_pk_add_f32 v[86:87], v[86:87], v[118:119] neg_lo:[0,1] neg_hi:[0,1]
	v_pk_add_f32 v[90:91], v[100:101], v[112:113] neg_lo:[0,1] neg_hi:[0,1]
	v_pk_add_f32 v[82:83], v[82:83], v[122:123] neg_lo:[0,1] neg_hi:[0,1]
	v_pk_add_f32 v[84:85], v[92:93], v[84:85] neg_lo:[0,1] neg_hi:[0,1]
	v_pk_add_f32 v[92:93], v[82:83], v[90:91]
	v_mov_b32_e32 v91, v121
	v_mov_b32_e32 v83, v87
	v_pk_add_f32 v[100:101], v[120:121], v[86:87]
	v_pk_add_f32 v[82:83], v[90:91], v[82:83]
	v_mov_b32_e32 v86, v92
	v_pk_add_f32 v[82:83], v[82:83], v[124:125] neg_lo:[0,1] neg_hi:[0,1]
	v_mov_b32_e32 v87, v101
	v_pk_add_f32 v[86:87], v[86:87], v[82:83] neg_lo:[0,1] neg_hi:[0,1]
	v_pk_add_f32 v[82:83], v[84:85], v[82:83] neg_lo:[0,1] neg_hi:[0,1]
	v_pk_add_f32 v[86:87], v[90:91], v[86:87] neg_lo:[0,1] neg_hi:[0,1]
	v_pk_add_f32 v[84:85], v[100:101], v[92:93]
	v_pk_add_f32 v[82:83], v[82:83], v[86:87]
	v_pk_add_f32 v[86:87], v[116:117], v[84:85]
	s_nop 0
	v_pk_add_f32 v[90:91], v[86:87], v[116:117] neg_lo:[0,1] neg_hi:[0,1]
	s_nop 0
	v_pk_add_f32 v[84:85], v[84:85], v[90:91] neg_lo:[0,1] neg_hi:[0,1]
	s_nop 0
	v_pk_add_f32 v[82:83], v[82:83], v[84:85]
	s_nop 0
	v_pk_add_f32 v[82:83], v[86:87], v[82:83]
	v_pk_mul_f32 v[86:87], v[98:99], v[102:103]
	v_cndmask_b32_e32 v82, v160, v82, vcc
	v_cmp_neq_f32_e32 vcc, s8, v128
	v_pk_add_f32 v[90:91], v[94:95], v[86:87]
	s_nop 0
	v_cndmask_b32_e32 v83, v160, v83, vcc
	v_cmp_ngt_f32_e32 vcc, -1.0, v128
	v_pk_add_f32 v[94:95], v[90:91], v[94:95] neg_lo:[0,1] neg_hi:[0,1]
	v_mov_b32_e32 v114, v90
	v_cndmask_b32_e32 v83, v161, v83, vcc
	v_cmp_ngt_f32_e32 vcc, -1.0, v97
	v_pk_add_f32 v[86:87], v[86:87], v[94:95] neg_lo:[0,1] neg_hi:[0,1]
	s_nop 0
	v_cndmask_b32_e32 v82, v161, v82, vcc
	v_cmp_neq_f32_e32 vcc, -1.0, v97
	v_pk_add_f32 v[98:99], v[88:89], v[86:87]
	v_mov_b32_e32 v95, v87
	v_cndmask_b32_e32 v82, v162, v82, vcc
	v_cmp_neq_f32_e32 vcc, -1.0, v128
	v_mov_b32_e32 v89, v99
	v_mov_b32_e32 v87, v91
	v_cndmask_b32_e32 v83, v162, v83, vcc
	v_cmp_lt_f32_e64 vcc, |v97|, s9
	v_cndmask_b32_e64 v83, v83, v128, s[0:1]
	v_pk_add_f32 v[86:87], v[88:89], v[86:87]
	v_cndmask_b32_e32 v82, v82, v97, vcc
	v_pk_add_f32 v[78:79], v[78:79], v[82:83]
	v_cvt_f32_i32_e32 v83, v132
	v_cvt_f32_i32_e32 v82, v130
	v_pk_add_f32 v[88:89], v[90:91], v[98:99]
	v_cmp_neq_f32_e32 vcc, s8, v129
	v_mov_b32_e32 v112, v88
; __device__ __forceinline__ float softplusf(float x) { return fmaxf(x, 0.f) + log1pf(__expf(-fabsf(x))); }
; __device__ __forceinline__ float logsigf(float x) { return fminf(x, 0.f) - log1pf(__expf(-fabsf(x))); }
; __device__ void phaseA_tile(const Params& p, int l, int mt, int nt, char* smem) {
;     ...
;                     const float4 db = *(const float4*)(p.dt_bias + l * 32 + c);
;                     const f32x4 v = acc[i][j];
;                     *(float4*)(p.dtb + (size_t)row * 32 + c) =
;                         make_float4(softplusf(v[0] + db.x), softplusf(v[1] + db.y), softplusf(v[2] + db.z), softplusf(v[3] + db.w));
;                 }
;                 {
;                     const int c = g4 * 4;
;                     const float4 fb = *(const float4*)(p.b_f + l * 16 + c);
;                     const f32x4 v = acc[i][2];
;                     float4 lf = make_float4(logsigf(v[0] + fb.x), logsigf(v[1] + fb.y), logsigf(v[2] + fb.z), logsigf(v[3] + fb.w));
	v_pk_mul_f32 v[84:85], v[82:83], s[12:13] op_sel_hi:[1,0]
	v_mov_b32_e32 v117, v89
	v_pk_fma_f32 v[92:93], v[82:83], s[12:13], v[84:85] op_sel_hi:[1,0,1] neg_lo:[0,0,1] neg_hi:[0,0,1]
	v_mov_b32_e32 v94, v84
	v_pk_fma_f32 v[82:83], v[82:83], s[14:15], v[92:93] op_sel_hi:[1,0,1]
	v_cmp_lt_f32_e64 s[0:1], |v131|, s9
	v_pk_add_f32 v[92:93], v[84:85], v[82:83]
	v_mov_b32_e32 v110, v82
	v_pk_add_f32 v[100:101], v[92:93], v[88:89]
	v_mov_b32_e32 v115, v93
	v_mov_b32_e32 v113, v101
	v_pk_add_f32 v[112:113], v[112:113], v[114:115] neg_lo:[0,1] neg_hi:[0,1]
	v_pk_add_f32 v[94:95], v[94:95], v[110:111]
	v_mov_b32_e32 v102, v100
	v_mov_b32_e32 v103, v93
	v_mov_b32_e32 v110, v92
	v_mov_b32_e32 v111, v85
	v_mov_b32_e32 v114, v92
	v_mov_b32_e32 v115, v101
	v_mov_b32_e32 v85, v113
	v_pk_add_f32 v[102:103], v[102:103], v[110:111] neg_lo:[0,1] neg_hi:[0,1]
	v_mov_b32_e32 v110, v88
	v_mov_b32_e32 v111, v83
	v_pk_add_f32 v[84:85], v[114:115], v[84:85] neg_lo:[0,1] neg_hi:[0,1]
	v_pk_add_f32 v[110:111], v[110:111], v[102:103] neg_lo:[0,1] neg_hi:[0,1]
	v_mov_b32_e32 v114, v84
	v_mov_b32_e32 v115, v103
	v_mov_b32_e32 v116, v100
	v_mov_b32_e32 v103, v91
	v_pk_add_f32 v[114:115], v[82:83], v[114:115] neg_lo:[0,1] neg_hi:[0,1]
	v_pk_add_f32 v[102:103], v[116:117], v[102:103] neg_lo:[0,1] neg_hi:[0,1]
	v_mov_b32_e32 v83, v93
	v_pk_add_f32 v[88:89], v[88:89], v[90:91] neg_lo:[0,1] neg_hi:[0,1]
	v_pk_add_f32 v[90:91], v[94:95], v[102:103] neg_lo:[0,1] neg_hi:[0,1]
	v_pk_add_f32 v[82:83], v[82:83], v[84:85] neg_lo:[0,1] neg_hi:[0,1]
	v_pk_add_f32 v[84:85], v[86:87], v[112:113] neg_lo:[0,1] neg_hi:[0,1]
	v_pk_add_f32 v[92:93], v[110:111], v[90:91]
	v_pk_add_f32 v[86:87], v[84:85], v[82:83]
	v_mov_b32_e32 v83, v111
	v_mov_b32_e32 v85, v91
	v_pk_add_f32 v[84:85], v[82:83], v[84:85]
	v_mov_b32_e32 v90, v86
	v_pk_add_f32 v[84:85], v[84:85], v[114:115] neg_lo:[0,1] neg_hi:[0,1]
	v_mov_b32_e32 v91, v93
	v_pk_add_f32 v[88:89], v[98:99], v[88:89] neg_lo:[0,1] neg_hi:[0,1]
	v_pk_add_f32 v[90:91], v[90:91], v[84:85] neg_lo:[0,1] neg_hi:[0,1]
	v_pk_add_f32 v[84:85], v[88:89], v[84:85] neg_lo:[0,1] neg_hi:[0,1]
	v_pk_add_f32 v[82:83], v[82:83], v[90:91] neg_lo:[0,1] neg_hi:[0,1]
	s_nop 0
	v_pk_add_f32 v[82:83], v[84:85], v[82:83]
	v_pk_add_f32 v[84:85], v[92:93], v[86:87]
	s_nop 0
	v_pk_add_f32 v[86:87], v[100:101], v[84:85]
	s_nop 0
	v_pk_add_f32 v[88:89], v[86:87], v[100:101] neg_lo:[0,1] neg_hi:[0,1]
	s_nop 0
	v_pk_add_f32 v[84:85], v[84:85], v[88:89] neg_lo:[0,1] neg_hi:[0,1]
	s_nop 0
	v_pk_add_f32 v[82:83], v[82:83], v[84:85]
	s_nop 0
	v_pk_add_f32 v[82:83], v[86:87], v[82:83]
	s_nop 0
	v_cndmask_b32_e32 v82, v160, v82, vcc
	v_cmp_neq_f32_e32 vcc, s8, v131
	s_nop 1
	v_cndmask_b32_e32 v83, v160, v83, vcc
	v_cmp_ngt_f32_e32 vcc, -1.0, v131
	s_nop 1
	v_cndmask_b32_e32 v83, v161, v83, vcc
	v_cmp_ngt_f32_e32 vcc, -1.0, v129
	s_nop 1
	v_cndmask_b32_e32 v82, v161, v82, vcc
	v_cmp_neq_f32_e32 vcc, -1.0, v129
	s_nop 1
	v_cndmask_b32_e32 v82, v162, v82, vcc
	v_cmp_neq_f32_e32 vcc, -1.0, v131
	s_nop 1
	v_cndmask_b32_e32 v83, v162, v83, vcc
	v_cmp_lt_f32_e64 vcc, |v129|, s9
	v_cndmask_b32_e64 v83, v83, v131, s[0:1]
	s_and_b64 s[0:1], s[60:61], exec
	v_cndmask_b32_e32 v82, v82, v129, vcc
	v_pk_add_f32 v[80:81], v[80:81], v[82:83]
	global_store_dwordx4 v[68:69], v[78:81], off offset:64
	global_load_dwordx4 v[78:81], v0, s[78:79]
	s_cselect_b32 s7, s46, s42
	s_cselect_b32 s6, s43, s59
	s_waitcnt vmcnt(0)
	v_add_f32_e32 v69, v54, v78
	v_min_f32_e32 v68, 0, v69
	v_mul_f32_e64 v69, |v69|, s2
	v_exp_f32_e32 v97, v69
	v_add_f32_e32 v79, v55, v79
	v_add_f32_e32 v81, v57, v81
	v_add_f32_e32 v69, 1.0, v97
	v_add_f32_e32 v78, -1.0, v69
	v_sub_f32_e32 v82, v78, v69
	v_add_f32_e32 v82, 1.0, v82
	v_sub_f32_e32 v78, v97, v78
	v_add_f32_e32 v84, v78, v82
	v_frexp_mant_f32_e32 v78, v69
	v_cvt_f64_f32_e32 v[82:83], v69
	v_cmp_gt_f32_e32 vcc, s26, v78
	v_frexp_exp_i32_f64_e32 v78, v[82:83]
	s_nop 0
	v_subbrev_co_u32_e32 v118, vcc, 0, v78, vcc
	v_sub_u32_e32 v82, 0, v118
	v_ldexp_f32 v78, v69, v82
	v_min_f32_e32 v69, 0, v79
	v_mul_f32_e64 v79, |v79|, s2
	v_exp_f32_e32 v126, v79
	v_ldexp_f32 v82, v84, v82
	v_add_f32_e32 v79, 1.0, v126
	v_add_f32_e32 v83, -1.0, v79
	v_sub_f32_e32 v84, v83, v79
	v_add_f32_e32 v84, 1.0, v84
	v_sub_f32_e32 v83, v126, v83
	v_add_f32_e32 v83, v83, v84
	v_frexp_mant_f32_e32 v84, v79
	v_cmp_gt_f32_e32 vcc, s26, v84
	v_cvt_f64_f32_e32 v[84:85], v79
	v_frexp_exp_i32_f64_e32 v84, v[84:85]
	v_subbrev_co_u32_e32 v119, vcc, 0, v84, vcc
	v_sub_u32_e32 v84, 0, v119
	v_ldexp_f32 v79, v79, v84
	v_ldexp_f32 v83, v83, v84
	v_pk_add_f32 v[84:85], v[78:79], 1.0 op_sel_hi:[1,0]
	v_pk_add_f32 v[92:93], v[78:79], -1.0 op_sel_hi:[1,0]
	v_pk_add_f32 v[86:87], v[84:85], -1.0 op_sel_hi:[1,0]
	v_pk_add_f32 v[94:95], v[92:93], 1.0 op_sel_hi:[1,0]
	v_pk_add_f32 v[86:87], v[78:79], v[86:87] neg_lo:[0,1] neg_hi:[0,1]
	v_pk_add_f32 v[78:79], v[78:79], v[94:95] neg_lo:[0,1] neg_hi:[0,1]
	v_pk_add_f32 v[86:87], v[82:83], v[86:87]
	v_pk_add_f32 v[78:79], v[82:83], v[78:79]
	v_pk_add_f32 v[88:89], v[84:85], v[86:87]
	v_pk_add_f32 v[82:83], v[92:93], v[78:79]
	v_rcp_f32_e32 v90, v88
	v_rcp_f32_e32 v91, v89
	v_pk_add_f32 v[84:85], v[88:89], v[84:85] neg_lo:[0,1] neg_hi:[0,1]
	v_pk_add_f32 v[92:93], v[82:83], v[92:93] neg_lo:[0,1] neg_hi:[0,1]
	v_pk_add_f32 v[84:85], v[86:87], v[84:85] neg_lo:[0,1] neg_hi:[0,1]
	v_pk_mul_f32 v[86:87], v[82:83], v[90:91]
	v_pk_add_f32 v[78:79], v[78:79], v[92:93] neg_lo:[0,1] neg_hi:[0,1]
	v_pk_mul_f32 v[92:93], v[88:89], v[86:87]
	v_cmp_lt_f32_e64 s[0:1], |v126|, s9
	v_pk_fma_f32 v[94:95], v[86:87], v[88:89], v[92:93] neg_lo:[0,0,1] neg_hi:[0,0,1]
	s_nop 0
; __device__ __forceinline__ float logsigf(float x) { return fminf(x, 0.f) - log1pf(__expf(-fabsf(x))); }
; __device__ void phaseA_tile(const Params& p, int l, int mt, int nt, char* smem) {
;     ...
;                     const int c = g4 * 4;
;                     const float4 fb = *(const float4*)(p.b_f + l * 16 + c);
;                     const f32x4 v = acc[i][2];
;                     float4 lf = make_float4(logsigf(v[0] + fb.x), logsigf(v[1] + fb.y), logsigf(v[2] + fb.z), logsigf(v[3] + fb.w));
	v_pk_fma_f32 v[94:95], v[86:87], v[84:85], v[94:95]
	s_nop 0
	v_pk_add_f32 v[98:99], v[92:93], v[94:95]
	s_nop 0
	v_pk_add_f32 v[100:101], v[82:83], v[98:99] neg_lo:[0,1] neg_hi:[0,1]
	v_pk_add_f32 v[92:93], v[98:99], v[92:93] neg_lo:[0,1] neg_hi:[0,1]
	v_pk_add_f32 v[82:83], v[82:83], v[100:101] neg_lo:[0,1] neg_hi:[0,1]
	s_nop 0
	v_pk_add_f32 v[82:83], v[82:83], v[98:99] neg_lo:[0,1] neg_hi:[0,1]
	s_nop 0
	v_pk_add_f32 v[78:79], v[78:79], v[82:83]
	v_pk_add_f32 v[82:83], v[92:93], v[94:95] neg_lo:[0,1] neg_hi:[0,1]
	s_nop 0
	v_pk_add_f32 v[78:79], v[82:83], v[78:79]
	s_nop 0
	v_pk_add_f32 v[82:83], v[100:101], v[78:79]
	s_nop 0
	v_pk_mul_f32 v[92:93], v[90:91], v[82:83]
	s_nop 0
	v_pk_mul_f32 v[94:95], v[88:89], v[92:93]
	s_nop 0
	v_pk_fma_f32 v[88:89], v[92:93], v[88:89], v[94:95] neg_lo:[0,0,1] neg_hi:[0,0,1]
	s_nop 0
	v_pk_fma_f32 v[84:85], v[92:93], v[84:85], v[88:89]
	v_pk_add_f32 v[88:89], v[100:101], v[82:83] neg_lo:[0,1] neg_hi:[0,1]
	s_nop 0
	v_pk_add_f32 v[78:79], v[78:79], v[88:89]
	v_pk_add_f32 v[88:89], v[94:95], v[84:85]
	s_nop 0
	v_pk_add_f32 v[98:99], v[82:83], v[88:89] neg_lo:[0,1] neg_hi:[0,1]
	v_pk_add_f32 v[94:95], v[88:89], v[94:95] neg_lo:[0,1] neg_hi:[0,1]
	v_pk_add_f32 v[82:83], v[82:83], v[98:99] neg_lo:[0,1] neg_hi:[0,1]
	s_nop 0
	v_pk_add_f32 v[82:83], v[82:83], v[88:89] neg_lo:[0,1] neg_hi:[0,1]
	s_nop 0
	v_pk_add_f32 v[78:79], v[78:79], v[82:83]
	v_pk_add_f32 v[82:83], v[94:95], v[84:85] neg_lo:[0,1] neg_hi:[0,1]
	s_nop 0
	v_pk_add_f32 v[78:79], v[82:83], v[78:79]
	v_pk_add_f32 v[82:83], v[86:87], v[92:93]
	v_pk_add_f32 v[78:79], v[98:99], v[78:79]
	v_pk_add_f32 v[84:85], v[82:83], v[86:87] neg_lo:[0,1] neg_hi:[0,1]
	v_pk_mul_f32 v[78:79], v[90:91], v[78:79]
	v_pk_add_f32 v[84:85], v[92:93], v[84:85] neg_lo:[0,1] neg_hi:[0,1]
	s_nop 0
	v_pk_add_f32 v[78:79], v[84:85], v[78:79]
	s_nop 0
	v_pk_add_f32 v[84:85], v[82:83], v[78:79]
	s_nop 0
	v_pk_add_f32 v[82:83], v[84:85], v[82:83] neg_lo:[0,1] neg_hi:[0,1]
	v_pk_mul_f32 v[88:89], v[84:85], v[84:85]
	v_pk_add_f32 v[78:79], v[78:79], v[82:83] neg_lo:[0,1] neg_hi:[0,1]
	v_pk_fma_f32 v[90:91], v[88:89], s[28:29], v[66:67] op_sel_hi:[1,0,0]
	v_ldexp_f32 v93, v79, 1
	v_add_f32_e32 v79, v56, v80
	v_ldexp_f32 v86, v78, 1
	v_min_f32_e32 v78, 0, v79
	v_mul_f32_e64 v79, |v79|, s2
	v_exp_f32_e32 v127, v79
	v_ldexp_f32 v82, v84, 1
	v_pk_fma_f32 v[90:91], v[88:89], v[90:91], s[30:31] op_sel_hi:[1,1,0]
	v_ldexp_f32 v83, v85, 1
	v_add_f32_e32 v79, 1.0, v127
	v_add_f32_e32 v80, -1.0, v79
	v_sub_f32_e32 v87, v80, v79
	v_add_f32_e32 v87, 1.0, v87
	v_sub_f32_e32 v80, v127, v80
	v_pk_mul_f32 v[84:85], v[84:85], v[88:89]
	v_add_f32_e32 v87, v80, v87
	v_frexp_mant_f32_e32 v80, v79
	v_cvt_f64_f32_e32 v[88:89], v79
	v_cmp_gt_f32_e32 vcc, s26, v80
	v_frexp_exp_i32_f64_e32 v80, v[88:89]
	v_pk_mul_f32 v[84:85], v[84:85], v[90:91]
	v_subbrev_co_u32_e32 v128, vcc, 0, v80, vcc
	v_sub_u32_e32 v88, 0, v128
	v_ldexp_f32 v80, v79, v88
	v_min_f32_e32 v79, 0, v81
	v_mul_f32_e64 v81, |v81|, s2
	v_exp_f32_e32 v129, v81
	v_ldexp_f32 v88, v87, v88
	v_pk_add_f32 v[90:91], v[82:83], v[84:85]
	v_add_f32_e32 v81, 1.0, v129
	v_add_f32_e32 v87, -1.0, v81
	v_sub_f32_e32 v89, v87, v81
	v_add_f32_e32 v89, 1.0, v89
	v_sub_f32_e32 v87, v129, v87
	v_add_f32_e32 v87, v87, v89
	v_frexp_mant_f32_e32 v89, v81
	v_cvt_f64_f32_e32 v[94:95], v81
	v_cmp_gt_f32_e32 vcc, s26, v89
	v_frexp_exp_i32_f64_e32 v89, v[94:95]
	v_pk_add_f32 v[82:83], v[90:91], v[82:83] neg_lo:[0,1] neg_hi:[0,1]
	v_subbrev_co_u32_e32 v130, vcc, 0, v89, vcc
	v_sub_u32_e32 v89, 0, v130
	v_ldexp_f32 v81, v81, v89
	v_pk_add_f32 v[94:95], v[80:81], 1.0 op_sel_hi:[1,0]
	v_ldexp_f32 v89, v87, v89
	v_pk_add_f32 v[98:99], v[94:95], -1.0 op_sel_hi:[1,0]
	v_pk_add_f32 v[110:111], v[80:81], -1.0 op_sel_hi:[1,0]
	v_pk_add_f32 v[98:99], v[80:81], v[98:99] neg_lo:[0,1] neg_hi:[0,1]
	v_pk_add_f32 v[112:113], v[110:111], 1.0 op_sel_hi:[1,0]
	v_pk_add_f32 v[98:99], v[88:89], v[98:99]
	v_pk_add_f32 v[80:81], v[80:81], v[112:113] neg_lo:[0,1] neg_hi:[0,1]
	v_pk_add_f32 v[100:101], v[94:95], v[98:99]
	v_pk_add_f32 v[80:81], v[88:89], v[80:81]
	v_rcp_f32_e32 v102, v100
	v_rcp_f32_e32 v103, v101
	v_pk_add_f32 v[88:89], v[110:111], v[80:81]
	v_pk_add_f32 v[94:95], v[100:101], v[94:95] neg_lo:[0,1] neg_hi:[0,1]
	v_pk_add_f32 v[110:111], v[88:89], v[110:111] neg_lo:[0,1] neg_hi:[0,1]
	v_pk_add_f32 v[94:95], v[98:99], v[94:95] neg_lo:[0,1] neg_hi:[0,1]
	v_pk_mul_f32 v[98:99], v[88:89], v[102:103]
	v_pk_add_f32 v[80:81], v[80:81], v[110:111] neg_lo:[0,1] neg_hi:[0,1]
	v_pk_mul_f32 v[110:111], v[100:101], v[98:99]
	v_pk_add_f32 v[82:83], v[84:85], v[82:83] neg_lo:[0,1] neg_hi:[0,1]
	v_pk_fma_f32 v[112:113], v[98:99], v[100:101], v[110:111] neg_lo:[0,0,1] neg_hi:[0,0,1]
	v_mov_b32_e32 v85, v83
	v_pk_fma_f32 v[112:113], v[98:99], v[94:95], v[112:113]
	v_mov_b32_e32 v87, v93
	v_pk_add_f32 v[114:115], v[110:111], v[112:113]
	v_mov_b32_e32 v122, v90
	v_pk_add_f32 v[116:117], v[88:89], v[114:115] neg_lo:[0,1] neg_hi:[0,1]
	v_pk_add_f32 v[110:111], v[114:115], v[110:111] neg_lo:[0,1] neg_hi:[0,1]
	v_pk_add_f32 v[88:89], v[88:89], v[116:117] neg_lo:[0,1] neg_hi:[0,1]
	v_cmp_neq_f32_e32 vcc, s8, v97
	v_pk_add_f32 v[88:89], v[88:89], v[114:115] neg_lo:[0,1] neg_hi:[0,1]
	s_nop 0
	v_pk_add_f32 v[80:81], v[80:81], v[88:89]
	v_pk_add_f32 v[88:89], v[110:111], v[112:113] neg_lo:[0,1] neg_hi:[0,1]
	s_nop 0
	v_pk_add_f32 v[80:81], v[88:89], v[80:81]
	s_nop 0
	v_pk_add_f32 v[88:89], v[116:117], v[80:81]
	s_nop 0
	v_pk_mul_f32 v[110:111], v[102:103], v[88:89]
	s_nop 0
	v_pk_mul_f32 v[112:113], v[100:101], v[110:111]
	s_nop 0
	v_pk_fma_f32 v[100:101], v[110:111], v[100:101], v[112:113] neg_lo:[0,0,1] neg_hi:[0,0,1]
; __device__ __forceinline__ float logsigf(float x) { return fminf(x, 0.f) - log1pf(__expf(-fabsf(x))); }
; __device__ void phaseA_tile(const Params& p, int l, int mt, int nt, char* smem) {
;     ...
;                     const int c = g4 * 4;
;                     const float4 fb = *(const float4*)(p.b_f + l * 16 + c);
;                     const f32x4 v = acc[i][2];
;                     float4 lf = make_float4(logsigf(v[0] + fb.x), logsigf(v[1] + fb.y), logsigf(v[2] + fb.z), logsigf(v[3] + fb.w));
;                     float* o = samp ? (p.out + O_LFS + ((size_t)l * TSM + (row - TP)) * 16 + c)
;                                     : (p.out + O_LFP + ((size_t)l * TP + row) * 16 + c);
;                     *(float4*)o = lf;
	s_nop 0
	v_pk_fma_f32 v[94:95], v[110:111], v[94:95], v[100:101]
	v_pk_add_f32 v[100:101], v[116:117], v[88:89] neg_lo:[0,1] neg_hi:[0,1]
	s_nop 0
	v_pk_add_f32 v[80:81], v[80:81], v[100:101]
	v_pk_add_f32 v[100:101], v[112:113], v[94:95]
	s_nop 0
	v_pk_add_f32 v[114:115], v[88:89], v[100:101] neg_lo:[0,1] neg_hi:[0,1]
	v_pk_add_f32 v[112:113], v[100:101], v[112:113] neg_lo:[0,1] neg_hi:[0,1]
	v_pk_add_f32 v[88:89], v[88:89], v[114:115] neg_lo:[0,1] neg_hi:[0,1]
	s_nop 0
	v_pk_add_f32 v[88:89], v[88:89], v[100:101] neg_lo:[0,1] neg_hi:[0,1]
	s_nop 0
	v_pk_add_f32 v[80:81], v[80:81], v[88:89]
	v_pk_add_f32 v[88:89], v[112:113], v[94:95] neg_lo:[0,1] neg_hi:[0,1]
	s_nop 0
	v_pk_add_f32 v[80:81], v[88:89], v[80:81]
	v_pk_add_f32 v[88:89], v[98:99], v[110:111]
	v_pk_add_f32 v[80:81], v[114:115], v[80:81]
	v_pk_add_f32 v[94:95], v[88:89], v[98:99] neg_lo:[0,1] neg_hi:[0,1]
	v_pk_mul_f32 v[80:81], v[102:103], v[80:81]
	v_pk_add_f32 v[94:95], v[110:111], v[94:95] neg_lo:[0,1] neg_hi:[0,1]
	s_nop 0
	v_pk_add_f32 v[80:81], v[94:95], v[80:81]
	s_nop 0
	v_pk_add_f32 v[94:95], v[88:89], v[80:81]
	s_nop 0
	v_pk_add_f32 v[88:89], v[94:95], v[88:89] neg_lo:[0,1] neg_hi:[0,1]
	v_pk_mul_f32 v[100:101], v[94:95], v[94:95]
	v_pk_add_f32 v[80:81], v[80:81], v[88:89] neg_lo:[0,1] neg_hi:[0,1]
	v_pk_fma_f32 v[102:103], v[100:101], s[28:29], v[66:67] op_sel_hi:[1,0,0]
	v_ldexp_f32 v98, v80, 1
	v_add_u32_e32 v80, 0xffff8000, v76
	v_ldexp_f32 v111, v81, 1
	v_ashrrev_i32_e32 v81, 31, v80
	v_cndmask_b32_e64 v77, v77, v81, s[60:61]
	v_cndmask_b32_e64 v76, v76, v80, s[60:61]
	v_cvt_f32_i32_e32 v81, v119
	v_cvt_f32_i32_e32 v80, v118
	v_ldexp_f32 v88, v94, 1
	v_pk_fma_f32 v[102:103], v[100:101], v[102:103], s[30:31] op_sel_hi:[1,1,0]
	v_ldexp_f32 v89, v95, 1
	v_pk_mul_f32 v[94:95], v[94:95], v[100:101]
	v_pk_mul_f32 v[100:101], v[80:81], s[12:13] op_sel_hi:[1,0]
	v_mov_b32_e32 v99, v111
	v_pk_fma_f32 v[112:113], v[80:81], s[12:13], v[100:101] op_sel_hi:[1,0,1] neg_lo:[0,0,1] neg_hi:[0,0,1]
	v_mov_b32_e32 v84, v100
	v_pk_fma_f32 v[80:81], v[80:81], s[14:15], v[112:113] op_sel_hi:[1,0,1]
	v_mov_b32_e32 v119, v101
	v_mov_b32_e32 v92, v80
	v_pk_add_f32 v[84:85], v[84:85], v[92:93]
	v_pk_add_f32 v[92:93], v[86:87], v[82:83]
	v_mov_b32_e32 v83, v91
	v_mov_b32_e32 v87, v93
	v_pk_add_f32 v[112:113], v[100:101], v[80:81]
	v_pk_add_f32 v[82:83], v[86:87], v[82:83]
	v_pk_add_f32 v[86:87], v[90:91], v[92:93]
	v_mov_b32_e32 v123, v113
	v_pk_add_f32 v[114:115], v[112:113], v[86:87]
	v_mov_b32_e32 v120, v86
	v_mov_b32_e32 v121, v115
	v_pk_add_f32 v[120:121], v[120:121], v[122:123] neg_lo:[0,1] neg_hi:[0,1]
	v_mov_b32_e32 v116, v114
	v_mov_b32_e32 v117, v113
	v_mov_b32_e32 v118, v112
	v_mov_b32_e32 v122, v112
	v_mov_b32_e32 v123, v115
	v_mov_b32_e32 v101, v121
	v_pk_add_f32 v[116:117], v[116:117], v[118:119] neg_lo:[0,1] neg_hi:[0,1]
	v_mov_b32_e32 v118, v86
	v_mov_b32_e32 v119, v81
	v_pk_add_f32 v[100:101], v[122:123], v[100:101] neg_lo:[0,1] neg_hi:[0,1]
	v_pk_add_f32 v[118:119], v[118:119], v[116:117] neg_lo:[0,1] neg_hi:[0,1]
	v_mov_b32_e32 v122, v100
	v_mov_b32_e32 v123, v117
	v_mov_b32_e32 v124, v114
	v_mov_b32_e32 v125, v87
	v_mov_b32_e32 v117, v91
	v_pk_add_f32 v[122:123], v[80:81], v[122:123] neg_lo:[0,1] neg_hi:[0,1]
	v_pk_add_f32 v[116:117], v[124:125], v[116:117] neg_lo:[0,1] neg_hi:[0,1]
	v_mov_b32_e32 v81, v113
	v_pk_add_f32 v[84:85], v[84:85], v[116:117] neg_lo:[0,1] neg_hi:[0,1]
	v_pk_add_f32 v[80:81], v[80:81], v[100:101] neg_lo:[0,1] neg_hi:[0,1]
	v_pk_add_f32 v[82:83], v[82:83], v[120:121] neg_lo:[0,1] neg_hi:[0,1]
	v_pk_add_f32 v[86:87], v[86:87], v[90:91] neg_lo:[0,1] neg_hi:[0,1]
	v_pk_add_f32 v[90:91], v[82:83], v[80:81]
	v_mov_b32_e32 v81, v119
	v_mov_b32_e32 v83, v85
	v_pk_add_f32 v[86:87], v[92:93], v[86:87] neg_lo:[0,1] neg_hi:[0,1]
	v_pk_add_f32 v[92:93], v[118:119], v[84:85]
	v_pk_add_f32 v[82:83], v[80:81], v[82:83]
	v_mov_b32_e32 v84, v90
	v_pk_add_f32 v[82:83], v[82:83], v[122:123] neg_lo:[0,1] neg_hi:[0,1]
	v_mov_b32_e32 v85, v93
	v_pk_add_f32 v[84:85], v[84:85], v[82:83] neg_lo:[0,1] neg_hi:[0,1]
	v_pk_add_f32 v[82:83], v[86:87], v[82:83] neg_lo:[0,1] neg_hi:[0,1]
	v_pk_add_f32 v[80:81], v[80:81], v[84:85] neg_lo:[0,1] neg_hi:[0,1]
	v_lshlrev_b64 v[76:77], 6, v[76:77]
	v_pk_add_f32 v[80:81], v[82:83], v[80:81]
	v_pk_add_f32 v[82:83], v[92:93], v[90:91]
	v_lshl_add_u64 v[76:77], s[6:7], 0, v[76:77]
	v_pk_add_f32 v[84:85], v[114:115], v[82:83]
	v_lshl_add_u64 v[76:77], v[76:77], 0, v[0:1]
	v_pk_add_f32 v[86:87], v[84:85], v[114:115] neg_lo:[0,1] neg_hi:[0,1]
	s_nop 0
	v_pk_add_f32 v[82:83], v[82:83], v[86:87] neg_lo:[0,1] neg_hi:[0,1]
	s_nop 0
	v_pk_add_f32 v[80:81], v[80:81], v[82:83]
	s_nop 0
	v_pk_add_f32 v[80:81], v[84:85], v[80:81]
	v_pk_mul_f32 v[84:85], v[94:95], v[102:103]
	v_cndmask_b32_e32 v80, v160, v80, vcc
	v_cmp_neq_f32_e32 vcc, s8, v126
	v_pk_add_f32 v[86:87], v[88:89], v[84:85]
	s_nop 0
	v_cndmask_b32_e32 v81, v160, v81, vcc
	v_cmp_ngt_f32_e32 vcc, -1.0, v126
	v_pk_add_f32 v[88:89], v[86:87], v[88:89] neg_lo:[0,1] neg_hi:[0,1]
	v_mov_b32_e32 v112, v86
	v_cndmask_b32_e32 v81, v161, v81, vcc
	v_cmp_ngt_f32_e32 vcc, -1.0, v97
	v_pk_add_f32 v[84:85], v[84:85], v[88:89] neg_lo:[0,1] neg_hi:[0,1]
	s_nop 0
	v_cndmask_b32_e32 v80, v161, v80, vcc
	v_cmp_neq_f32_e32 vcc, -1.0, v97
	v_pk_add_f32 v[92:93], v[98:99], v[84:85]
	v_mov_b32_e32 v89, v85
	v_cndmask_b32_e32 v80, v162, v80, vcc
	v_cmp_neq_f32_e32 vcc, -1.0, v126
	v_mov_b32_e32 v99, v93
	v_mov_b32_e32 v85, v87
	v_cndmask_b32_e32 v81, v162, v81, vcc
	v_cmp_lt_f32_e64 vcc, |v97|, s9
	v_cndmask_b32_e64 v81, v81, v126, s[0:1]
	v_pk_add_f32 v[94:95], v[86:87], v[92:93]
	v_cndmask_b32_e32 v80, v80, v97, vcc
; __device__ __forceinline__ float softplusf(float x) { return fmaxf(x, 0.f) + log1pf(__expf(-fabsf(x))); }
; __device__ __forceinline__ float logsigf(float x) { return fminf(x, 0.f) - log1pf(__expf(-fabsf(x))); }
; __device__ void phaseA_tile(const Params& p, int l, int mt, int nt, char* smem) {
;     ...
;             for (int i = 0; i < 4; ++i) {
;                 const int rl = wr * 64 + i * 16 + r;
;                 const int row = m0 + rl;
; #pragma unroll
;                 for (int j = 0; j < 2; ++j) {
;                     const int c = j * 16 + g4 * 4;
;                     const float4 db = *(const float4*)(p.dt_bias + l * 32 + c);
;                     const f32x4 v = acc[i][j];
;                     *(float4*)(p.dtb + (size_t)row * 32 + c) =
;                         make_float4(softplusf(v[0] + db.x), softplusf(v[1] + db.y), softplusf(v[2] + db.z), softplusf(v[3] + db.w));
;     ...
;                     const int c = g4 * 4;
;                     const float4 fb = *(const float4*)(p.b_f + l * 16 + c);
;                     const f32x4 v = acc[i][2];
;                     float4 lf = make_float4(logsigf(v[0] + fb.x), logsigf(v[1] + fb.y), logsigf(v[2] + fb.z), logsigf(v[3] + fb.w));
;                     float* o = samp ? (p.out + O_LFS + ((size_t)l * TSM + (row - TP)) * 16 + c)
;                                     : (p.out + O_LFP + ((size_t)l * TP + row) * 16 + c);
;                     *(float4*)o = lf;
;                     *(float4*)(lf_s + rl * 16 + c) = lf;
	v_pk_add_f32 v[80:81], v[68:69], v[80:81] neg_lo:[0,1] neg_hi:[0,1]
	v_cvt_f32_i32_e32 v69, v130
	v_cvt_f32_i32_e32 v68, v128
	v_pk_add_f32 v[84:85], v[98:99], v[84:85]
	v_mov_b32_e32 v115, v95
	v_cmp_neq_f32_e32 vcc, s8, v127
	v_pk_mul_f32 v[82:83], v[68:69], s[12:13] op_sel_hi:[1,0]
	v_cmp_lt_f32_e64 s[0:1], |v129|, s9
	v_pk_fma_f32 v[90:91], v[68:69], s[12:13], v[82:83] op_sel_hi:[1,0,1] neg_lo:[0,0,1] neg_hi:[0,0,1]
	v_mov_b32_e32 v88, v82
	v_pk_fma_f32 v[68:69], v[68:69], s[14:15], v[90:91] op_sel_hi:[1,0,1]
	v_mov_b32_e32 v103, v83
	v_pk_add_f32 v[90:91], v[82:83], v[68:69]
	v_mov_b32_e32 v110, v68
	v_pk_add_f32 v[98:99], v[90:91], v[94:95]
	v_pk_add_f32 v[88:89], v[88:89], v[110:111]
	v_mov_b32_e32 v110, v94
	v_mov_b32_e32 v111, v99
	v_mov_b32_e32 v113, v91
	v_pk_add_f32 v[110:111], v[110:111], v[112:113] neg_lo:[0,1] neg_hi:[0,1]
	v_mov_b32_e32 v100, v98
	v_mov_b32_e32 v101, v91
	v_mov_b32_e32 v102, v90
	v_mov_b32_e32 v112, v90
	v_mov_b32_e32 v113, v99
	v_mov_b32_e32 v83, v111
	v_pk_add_f32 v[100:101], v[100:101], v[102:103] neg_lo:[0,1] neg_hi:[0,1]
	v_mov_b32_e32 v102, v94
	v_mov_b32_e32 v103, v69
	v_pk_add_f32 v[82:83], v[112:113], v[82:83] neg_lo:[0,1] neg_hi:[0,1]
	v_pk_add_f32 v[102:103], v[102:103], v[100:101] neg_lo:[0,1] neg_hi:[0,1]
	v_mov_b32_e32 v112, v82
	v_mov_b32_e32 v113, v101
	v_mov_b32_e32 v114, v98
	v_mov_b32_e32 v101, v87
	v_pk_add_f32 v[112:113], v[68:69], v[112:113] neg_lo:[0,1] neg_hi:[0,1]
	v_pk_add_f32 v[100:101], v[114:115], v[100:101] neg_lo:[0,1] neg_hi:[0,1]
	v_mov_b32_e32 v69, v91
	v_pk_add_f32 v[88:89], v[88:89], v[100:101] neg_lo:[0,1] neg_hi:[0,1]
	v_pk_add_f32 v[68:69], v[68:69], v[82:83] neg_lo:[0,1] neg_hi:[0,1]
	v_pk_add_f32 v[82:83], v[84:85], v[110:111] neg_lo:[0,1] neg_hi:[0,1]
	v_pk_add_f32 v[90:91], v[102:103], v[88:89]
	v_pk_add_f32 v[84:85], v[82:83], v[68:69]
	v_mov_b32_e32 v69, v103
	v_mov_b32_e32 v83, v89
	v_pk_add_f32 v[82:83], v[68:69], v[82:83]
	v_pk_add_f32 v[86:87], v[94:95], v[86:87] neg_lo:[0,1] neg_hi:[0,1]
	v_pk_add_f32 v[82:83], v[82:83], v[112:113] neg_lo:[0,1] neg_hi:[0,1]
	v_mov_b32_e32 v88, v84
	v_mov_b32_e32 v89, v91
	v_pk_add_f32 v[86:87], v[92:93], v[86:87] neg_lo:[0,1] neg_hi:[0,1]
	v_pk_add_f32 v[88:89], v[88:89], v[82:83] neg_lo:[0,1] neg_hi:[0,1]
	v_pk_add_f32 v[82:83], v[86:87], v[82:83] neg_lo:[0,1] neg_hi:[0,1]
	v_pk_add_f32 v[68:69], v[68:69], v[88:89] neg_lo:[0,1] neg_hi:[0,1]
	s_nop 0
	v_pk_add_f32 v[68:69], v[82:83], v[68:69]
	v_pk_add_f32 v[82:83], v[90:91], v[84:85]
	s_nop 0
	v_pk_add_f32 v[84:85], v[98:99], v[82:83]
	s_nop 0
	v_pk_add_f32 v[86:87], v[84:85], v[98:99] neg_lo:[0,1] neg_hi:[0,1]
	s_nop 0
	v_pk_add_f32 v[82:83], v[82:83], v[86:87] neg_lo:[0,1] neg_hi:[0,1]
	s_nop 0
	v_pk_add_f32 v[68:69], v[68:69], v[82:83]
	s_nop 0
	v_pk_add_f32 v[68:69], v[84:85], v[68:69]
	s_nop 0
	v_cndmask_b32_e32 v68, v160, v68, vcc
	v_cmp_neq_f32_e32 vcc, s8, v129
	s_nop 1
	v_cndmask_b32_e32 v69, v160, v69, vcc
	v_cmp_ngt_f32_e32 vcc, -1.0, v129
	s_nop 1
	v_cndmask_b32_e32 v69, v161, v69, vcc
	v_cmp_ngt_f32_e32 vcc, -1.0, v127
	s_nop 1
	v_cndmask_b32_e32 v68, v161, v68, vcc
	v_cmp_neq_f32_e32 vcc, -1.0, v127
	s_nop 1
	v_cndmask_b32_e32 v68, v162, v68, vcc
	v_cmp_neq_f32_e32 vcc, -1.0, v129
	s_nop 1
	v_cndmask_b32_e32 v69, v162, v69, vcc
	v_cmp_lt_f32_e64 vcc, |v127|, s9
	v_cndmask_b32_e64 v69, v69, v129, s[0:1]
	s_nop 0
	v_cndmask_b32_e32 v68, v68, v127, vcc
	v_pk_add_f32 v[82:83], v[78:79], v[68:69] neg_lo:[0,1] neg_hi:[0,1]
	global_store_dwordx4 v[76:77], v[80:83], off
	v_lshl_or_b32 v68, v71, 6, v0
	ds_write_b128 v68, v[80:83]
	global_load_dwordx4 v[78:81], v0, s[74:75]
	v_or_b32_e32 v82, 16, v71
	v_add_u32_e32 v68, s54, v82
	v_ashrrev_i32_e32 v69, 31, v68
	v_lshlrev_b64 v[76:77], 7, v[68:69]
	v_lshl_add_u64 v[76:77], s[10:11], 0, v[76:77]
	v_lshl_add_u64 v[76:77], v[76:77], 0, v[0:1]
	s_waitcnt vmcnt(0)
	v_add_f32_e32 v83, v46, v78
	v_max_f32_e32 v78, 0, v83
	v_mul_f32_e64 v83, |v83|, s2
	v_exp_f32_e32 v83, v83
	s_nop 0
	v_add_f32_e32 v86, 1.0, v83
	v_add_f32_e32 v84, -1.0, v86
	v_sub_f32_e32 v85, v84, v86
	v_add_f32_e32 v85, 1.0, v85
	v_sub_f32_e32 v84, v83, v84
	v_add_f32_e32 v87, v84, v85
	v_frexp_mant_f32_e32 v84, v86
	v_cmp_gt_f32_e32 vcc, s26, v84
	v_cvt_f64_f32_e32 v[84:85], v86
	v_frexp_exp_i32_f64_e32 v84, v[84:85]
	v_subbrev_co_u32_e32 v97, vcc, 0, v84, vcc
	v_sub_u32_e32 v85, 0, v97
	v_ldexp_f32 v84, v86, v85
	v_ldexp_f32 v86, v87, v85
	v_add_f32_e32 v85, v47, v79
	v_max_f32_e32 v79, 0, v85
	v_mul_f32_e64 v85, |v85|, s2
	v_exp_f32_e32 v130, v85
	s_nop 0
	v_add_f32_e32 v85, 1.0, v130
	v_add_f32_e32 v87, -1.0, v85
	v_sub_f32_e32 v88, v87, v85
	v_add_f32_e32 v88, 1.0, v88
	v_sub_f32_e32 v87, v130, v87
	v_add_f32_e32 v87, v87, v88
	v_frexp_mant_f32_e32 v88, v85
	v_cmp_gt_f32_e32 vcc, s26, v88
	v_cvt_f64_f32_e32 v[88:89], v85
	v_frexp_exp_i32_f64_e32 v88, v[88:89]
	v_subbrev_co_u32_e32 v122, vcc, 0, v88, vcc
	v_sub_u32_e32 v88, 0, v122
	v_ldexp_f32 v85, v85, v88
	v_ldexp_f32 v87, v87, v88
	v_pk_add_f32 v[88:89], v[84:85], 1.0 op_sel_hi:[1,0]
	v_pk_add_f32 v[98:99], v[84:85], -1.0 op_sel_hi:[1,0]
	v_pk_add_f32 v[90:91], v[88:89], -1.0 op_sel_hi:[1,0]
	v_pk_add_f32 v[100:101], v[98:99], 1.0 op_sel_hi:[1,0]
	v_pk_add_f32 v[90:91], v[84:85], v[90:91] neg_lo:[0,1] neg_hi:[0,1]
	v_pk_add_f32 v[84:85], v[84:85], v[100:101] neg_lo:[0,1] neg_hi:[0,1]
	v_pk_add_f32 v[90:91], v[86:87], v[90:91]
	v_pk_add_f32 v[84:85], v[86:87], v[84:85]
	v_pk_add_f32 v[92:93], v[88:89], v[90:91]
	v_pk_add_f32 v[86:87], v[98:99], v[84:85]
	v_rcp_f32_e32 v94, v92
	v_rcp_f32_e32 v95, v93
	v_pk_add_f32 v[88:89], v[92:93], v[88:89] neg_lo:[0,1] neg_hi:[0,1]
; __device__ __forceinline__ float softplusf(float x) { return fmaxf(x, 0.f) + log1pf(__expf(-fabsf(x))); }
; __device__ void phaseA_tile(const Params& p, int l, int mt, int nt, char* smem) {
;     ...
;                 for (int j = 0; j < 2; ++j) {
;                     const int c = j * 16 + g4 * 4;
;                     const float4 db = *(const float4*)(p.dt_bias + l * 32 + c);
;                     const f32x4 v = acc[i][j];
;                     *(float4*)(p.dtb + (size_t)row * 32 + c) =
;                         make_float4(softplusf(v[0] + db.x), softplusf(v[1] + db.y), softplusf(v[2] + db.z), softplusf(v[3] + db.w));
	v_pk_add_f32 v[98:99], v[86:87], v[98:99] neg_lo:[0,1] neg_hi:[0,1]
	v_pk_add_f32 v[88:89], v[90:91], v[88:89] neg_lo:[0,1] neg_hi:[0,1]
	v_pk_mul_f32 v[90:91], v[86:87], v[94:95]
	v_pk_add_f32 v[84:85], v[84:85], v[98:99] neg_lo:[0,1] neg_hi:[0,1]
	v_pk_mul_f32 v[98:99], v[92:93], v[90:91]
	v_cmp_lt_f32_e64 s[0:1], |v130|, s9
	v_pk_fma_f32 v[100:101], v[90:91], v[92:93], v[98:99] neg_lo:[0,0,1] neg_hi:[0,0,1]
	s_nop 0
	v_pk_fma_f32 v[100:101], v[90:91], v[88:89], v[100:101]
	s_nop 0
	v_pk_add_f32 v[102:103], v[98:99], v[100:101]
	s_nop 0
	v_pk_add_f32 v[110:111], v[86:87], v[102:103] neg_lo:[0,1] neg_hi:[0,1]
	v_pk_add_f32 v[98:99], v[102:103], v[98:99] neg_lo:[0,1] neg_hi:[0,1]
	v_pk_add_f32 v[86:87], v[86:87], v[110:111] neg_lo:[0,1] neg_hi:[0,1]
	s_nop 0
	v_pk_add_f32 v[86:87], v[86:87], v[102:103] neg_lo:[0,1] neg_hi:[0,1]
	s_nop 0
	v_pk_add_f32 v[84:85], v[84:85], v[86:87]
	v_pk_add_f32 v[86:87], v[98:99], v[100:101] neg_lo:[0,1] neg_hi:[0,1]
	s_nop 0
	v_pk_add_f32 v[84:85], v[86:87], v[84:85]
	s_nop 0
	v_pk_add_f32 v[86:87], v[110:111], v[84:85]
	s_nop 0
	v_pk_mul_f32 v[98:99], v[94:95], v[86:87]
	s_nop 0
	v_pk_mul_f32 v[100:101], v[92:93], v[98:99]
	s_nop 0
	v_pk_fma_f32 v[92:93], v[98:99], v[92:93], v[100:101] neg_lo:[0,0,1] neg_hi:[0,0,1]
	s_nop 0
	v_pk_fma_f32 v[88:89], v[98:99], v[88:89], v[92:93]
	v_pk_add_f32 v[92:93], v[110:111], v[86:87] neg_lo:[0,1] neg_hi:[0,1]
	s_nop 0
	v_pk_add_f32 v[84:85], v[84:85], v[92:93]
	v_pk_add_f32 v[92:93], v[100:101], v[88:89]
	s_nop 0
	v_pk_add_f32 v[102:103], v[86:87], v[92:93] neg_lo:[0,1] neg_hi:[0,1]
	v_pk_add_f32 v[100:101], v[92:93], v[100:101] neg_lo:[0,1] neg_hi:[0,1]
	v_pk_add_f32 v[86:87], v[86:87], v[102:103] neg_lo:[0,1] neg_hi:[0,1]
	s_nop 0
	v_pk_add_f32 v[86:87], v[86:87], v[92:93] neg_lo:[0,1] neg_hi:[0,1]
	s_nop 0
	v_pk_add_f32 v[84:85], v[84:85], v[86:87]
	v_pk_add_f32 v[86:87], v[100:101], v[88:89] neg_lo:[0,1] neg_hi:[0,1]
	s_nop 0
	v_pk_add_f32 v[84:85], v[86:87], v[84:85]
	v_pk_add_f32 v[86:87], v[90:91], v[98:99]
	v_pk_add_f32 v[84:85], v[102:103], v[84:85]
	v_pk_add_f32 v[88:89], v[86:87], v[90:91] neg_lo:[0,1] neg_hi:[0,1]
	v_pk_mul_f32 v[84:85], v[94:95], v[84:85]
	v_pk_add_f32 v[88:89], v[98:99], v[88:89] neg_lo:[0,1] neg_hi:[0,1]
	s_nop 0
	v_pk_add_f32 v[84:85], v[88:89], v[84:85]
	s_nop 0
	v_pk_add_f32 v[88:89], v[86:87], v[84:85]
	s_nop 0
	v_pk_add_f32 v[86:87], v[88:89], v[86:87] neg_lo:[0,1] neg_hi:[0,1]
	v_pk_mul_f32 v[90:91], v[88:89], v[88:89]
	v_pk_add_f32 v[84:85], v[84:85], v[86:87] neg_lo:[0,1] neg_hi:[0,1]
	v_pk_fma_f32 v[92:93], v[90:91], s[28:29], v[66:67] op_sel_hi:[1,0,0]
	v_ldexp_f32 v95, v85, 1
	v_add_f32_e32 v85, v48, v80
	v_max_f32_e32 v80, 0, v85
	v_mul_f32_e64 v85, |v85|, s2
	v_exp_f32_e32 v131, v85
	v_ldexp_f32 v86, v88, 1
	v_pk_fma_f32 v[92:93], v[90:91], v[92:93], s[30:31] op_sel_hi:[1,1,0]
	v_ldexp_f32 v87, v89, 1
	v_add_f32_e32 v85, 1.0, v131
	v_pk_mul_f32 v[88:89], v[88:89], v[90:91]
	v_add_f32_e32 v90, -1.0, v85
	v_sub_f32_e32 v91, v90, v85
	v_add_f32_e32 v91, 1.0, v91
	v_sub_f32_e32 v90, v131, v90
	v_add_f32_e32 v94, v90, v91
	v_frexp_mant_f32_e32 v90, v85
	v_cmp_gt_f32_e32 vcc, s26, v90
	v_cvt_f64_f32_e32 v[90:91], v85
	v_frexp_exp_i32_f64_e32 v90, v[90:91]
	v_subbrev_co_u32_e32 v132, vcc, 0, v90, vcc
	v_sub_u32_e32 v91, 0, v132
	v_ldexp_f32 v90, v85, v91
	v_add_f32_e32 v85, v49, v81
	v_max_f32_e32 v81, 0, v85
	v_mul_f32_e64 v85, |v85|, s2
	v_exp_f32_e32 v133, v85
	v_ldexp_f32 v98, v94, v91
	v_pk_mul_f32 v[88:89], v[88:89], v[92:93]
	v_ldexp_f32 v84, v84, 1
	v_add_f32_e32 v85, 1.0, v133
	v_add_f32_e32 v91, -1.0, v85
	v_sub_f32_e32 v94, v91, v85
	v_add_f32_e32 v94, 1.0, v94
	v_sub_f32_e32 v91, v133, v91
	v_add_f32_e32 v94, v91, v94
	v_frexp_mant_f32_e32 v91, v85
	v_cvt_f64_f32_e32 v[100:101], v85
	v_cmp_gt_f32_e32 vcc, s26, v91
	v_frexp_exp_i32_f64_e32 v91, v[100:101]
	v_pk_add_f32 v[92:93], v[86:87], v[88:89]
	v_subbrev_co_u32_e32 v134, vcc, 0, v91, vcc
	v_sub_u32_e32 v99, 0, v134
	v_ldexp_f32 v91, v85, v99
	v_pk_add_f32 v[100:101], v[90:91], 1.0 op_sel_hi:[1,0]
	v_ldexp_f32 v99, v94, v99
	v_pk_add_f32 v[102:103], v[100:101], -1.0 op_sel_hi:[1,0]
	v_pk_add_f32 v[114:115], v[90:91], -1.0 op_sel_hi:[1,0]
	v_pk_add_f32 v[102:103], v[90:91], v[102:103] neg_lo:[0,1] neg_hi:[0,1]
	v_pk_add_f32 v[116:117], v[114:115], 1.0 op_sel_hi:[1,0]
	v_pk_add_f32 v[102:103], v[98:99], v[102:103]
	v_pk_add_f32 v[90:91], v[90:91], v[116:117] neg_lo:[0,1] neg_hi:[0,1]
	v_pk_add_f32 v[110:111], v[100:101], v[102:103]
	v_pk_add_f32 v[90:91], v[98:99], v[90:91]
	v_rcp_f32_e32 v112, v110
	v_rcp_f32_e32 v113, v111
	v_pk_add_f32 v[98:99], v[114:115], v[90:91]
	v_pk_add_f32 v[100:101], v[110:111], v[100:101] neg_lo:[0,1] neg_hi:[0,1]
	v_pk_add_f32 v[114:115], v[98:99], v[114:115] neg_lo:[0,1] neg_hi:[0,1]
	v_pk_add_f32 v[100:101], v[102:103], v[100:101] neg_lo:[0,1] neg_hi:[0,1]
	v_pk_mul_f32 v[102:103], v[98:99], v[112:113]
	v_pk_add_f32 v[90:91], v[90:91], v[114:115] neg_lo:[0,1] neg_hi:[0,1]
	v_pk_mul_f32 v[114:115], v[110:111], v[102:103]
	v_pk_add_f32 v[86:87], v[92:93], v[86:87] neg_lo:[0,1] neg_hi:[0,1]
	v_pk_fma_f32 v[116:117], v[102:103], v[110:111], v[114:115] neg_lo:[0,0,1] neg_hi:[0,0,1]
	v_pk_add_f32 v[86:87], v[88:89], v[86:87] neg_lo:[0,1] neg_hi:[0,1]
	v_pk_fma_f32 v[116:117], v[102:103], v[100:101], v[116:117]
	v_mov_b32_e32 v89, v87
	v_pk_add_f32 v[118:119], v[114:115], v[116:117]
	v_mov_b32_e32 v85, v95
	v_pk_add_f32 v[120:121], v[98:99], v[118:119] neg_lo:[0,1] neg_hi:[0,1]
	v_pk_add_f32 v[114:115], v[118:119], v[114:115] neg_lo:[0,1] neg_hi:[0,1]
	v_pk_add_f32 v[98:99], v[98:99], v[120:121] neg_lo:[0,1] neg_hi:[0,1]
	v_mov_b32_e32 v126, v92
; __device__ __forceinline__ float softplusf(float x) { return fmaxf(x, 0.f) + log1pf(__expf(-fabsf(x))); }
; __device__ void phaseA_tile(const Params& p, int l, int mt, int nt, char* smem) {
;     ...
;                 for (int j = 0; j < 2; ++j) {
;                     const int c = j * 16 + g4 * 4;
;                     const float4 db = *(const float4*)(p.dt_bias + l * 32 + c);
;                     const f32x4 v = acc[i][j];
;                     *(float4*)(p.dtb + (size_t)row * 32 + c) =
;                         make_float4(softplusf(v[0] + db.x), softplusf(v[1] + db.y), softplusf(v[2] + db.z), softplusf(v[3] + db.w));
	v_pk_add_f32 v[98:99], v[98:99], v[118:119] neg_lo:[0,1] neg_hi:[0,1]
	v_cmp_neq_f32_e32 vcc, s8, v83
	v_pk_add_f32 v[90:91], v[90:91], v[98:99]
	v_pk_add_f32 v[98:99], v[114:115], v[116:117] neg_lo:[0,1] neg_hi:[0,1]
	s_nop 0
	v_pk_add_f32 v[90:91], v[98:99], v[90:91]
	s_nop 0
	v_pk_add_f32 v[98:99], v[120:121], v[90:91]
	s_nop 0
	v_pk_mul_f32 v[114:115], v[112:113], v[98:99]
	s_nop 0
	v_pk_mul_f32 v[116:117], v[110:111], v[114:115]
	s_nop 0
	v_pk_fma_f32 v[110:111], v[114:115], v[110:111], v[116:117] neg_lo:[0,0,1] neg_hi:[0,0,1]
	s_nop 0
	v_pk_fma_f32 v[100:101], v[114:115], v[100:101], v[110:111]
	v_pk_add_f32 v[110:111], v[120:121], v[98:99] neg_lo:[0,1] neg_hi:[0,1]
	s_nop 0
	v_pk_add_f32 v[90:91], v[90:91], v[110:111]
	v_pk_add_f32 v[110:111], v[116:117], v[100:101]
	s_nop 0
	v_pk_add_f32 v[118:119], v[98:99], v[110:111] neg_lo:[0,1] neg_hi:[0,1]
	v_pk_add_f32 v[116:117], v[110:111], v[116:117] neg_lo:[0,1] neg_hi:[0,1]
	v_pk_add_f32 v[98:99], v[98:99], v[118:119] neg_lo:[0,1] neg_hi:[0,1]
	s_nop 0
	v_pk_add_f32 v[98:99], v[98:99], v[110:111] neg_lo:[0,1] neg_hi:[0,1]
	s_nop 0
	v_pk_add_f32 v[90:91], v[90:91], v[98:99]
	v_pk_add_f32 v[98:99], v[116:117], v[100:101] neg_lo:[0,1] neg_hi:[0,1]
	s_nop 0
	v_pk_add_f32 v[90:91], v[98:99], v[90:91]
	v_pk_add_f32 v[98:99], v[102:103], v[114:115]
	v_pk_add_f32 v[90:91], v[118:119], v[90:91]
	v_pk_add_f32 v[100:101], v[98:99], v[102:103] neg_lo:[0,1] neg_hi:[0,1]
	v_pk_mul_f32 v[90:91], v[112:113], v[90:91]
	v_pk_add_f32 v[100:101], v[114:115], v[100:101] neg_lo:[0,1] neg_hi:[0,1]
	s_nop 0
	v_pk_add_f32 v[90:91], v[100:101], v[90:91]
	s_nop 0
	v_pk_add_f32 v[100:101], v[98:99], v[90:91]
	s_nop 0
	v_pk_mul_f32 v[102:103], v[100:101], v[100:101]
	v_pk_add_f32 v[98:99], v[100:101], v[98:99] neg_lo:[0,1] neg_hi:[0,1]
	v_pk_fma_f32 v[110:111], v[102:103], s[28:29], v[66:67] op_sel_hi:[1,0,0]
	v_pk_add_f32 v[90:91], v[90:91], v[98:99] neg_lo:[0,1] neg_hi:[0,1]
	v_ldexp_f32 v98, v100, 1
	v_pk_fma_f32 v[110:111], v[102:103], v[110:111], s[30:31] op_sel_hi:[1,1,0]
	v_ldexp_f32 v99, v101, 1
	v_pk_mul_f32 v[100:101], v[100:101], v[102:103]
	v_cvt_f32_i32_e32 v103, v122
	v_cvt_f32_i32_e32 v102, v97
	v_ldexp_f32 v113, v91, 1
	v_ldexp_f32 v90, v90, 1
	v_mov_b32_e32 v91, v113
	v_pk_mul_f32 v[114:115], v[102:103], s[12:13] op_sel_hi:[1,0]
	s_nop 0
	v_pk_fma_f32 v[116:117], v[102:103], s[12:13], v[114:115] op_sel_hi:[1,0,1] neg_lo:[0,0,1] neg_hi:[0,0,1]
	v_mov_b32_e32 v88, v114
	v_pk_fma_f32 v[102:103], v[102:103], s[14:15], v[116:117] op_sel_hi:[1,0,1]
	v_mov_b32_e32 v123, v115
	v_mov_b32_e32 v94, v102
	v_pk_add_f32 v[88:89], v[88:89], v[94:95]
	v_pk_add_f32 v[94:95], v[84:85], v[86:87]
	v_mov_b32_e32 v87, v93
	v_mov_b32_e32 v85, v95
	v_pk_add_f32 v[116:117], v[114:115], v[102:103]
	v_pk_add_f32 v[84:85], v[84:85], v[86:87]
	v_pk_add_f32 v[86:87], v[92:93], v[94:95]
	v_mov_b32_e32 v127, v117
	v_pk_add_f32 v[118:119], v[116:117], v[86:87]
	v_mov_b32_e32 v124, v86
	v_mov_b32_e32 v125, v119
	v_pk_add_f32 v[124:125], v[124:125], v[126:127] neg_lo:[0,1] neg_hi:[0,1]
	v_mov_b32_e32 v120, v118
	v_mov_b32_e32 v121, v117
	v_mov_b32_e32 v122, v116
	v_mov_b32_e32 v126, v116
	v_mov_b32_e32 v127, v119
	v_mov_b32_e32 v115, v125
	v_pk_add_f32 v[120:121], v[120:121], v[122:123] neg_lo:[0,1] neg_hi:[0,1]
	v_mov_b32_e32 v122, v86
	v_mov_b32_e32 v123, v103
	v_pk_add_f32 v[114:115], v[126:127], v[114:115] neg_lo:[0,1] neg_hi:[0,1]
	v_pk_add_f32 v[122:123], v[122:123], v[120:121] neg_lo:[0,1] neg_hi:[0,1]
	v_mov_b32_e32 v126, v114
	v_mov_b32_e32 v127, v121
	v_mov_b32_e32 v128, v118
	v_mov_b32_e32 v129, v87
	v_mov_b32_e32 v121, v93
	v_pk_add_f32 v[126:127], v[102:103], v[126:127] neg_lo:[0,1] neg_hi:[0,1]
	v_pk_add_f32 v[120:121], v[128:129], v[120:121] neg_lo:[0,1] neg_hi:[0,1]
	v_mov_b32_e32 v103, v117
	v_pk_add_f32 v[86:87], v[86:87], v[92:93] neg_lo:[0,1] neg_hi:[0,1]
	v_pk_add_f32 v[88:89], v[88:89], v[120:121] neg_lo:[0,1] neg_hi:[0,1]
	v_pk_add_f32 v[92:93], v[102:103], v[114:115] neg_lo:[0,1] neg_hi:[0,1]
	v_pk_add_f32 v[84:85], v[84:85], v[124:125] neg_lo:[0,1] neg_hi:[0,1]
	v_pk_add_f32 v[86:87], v[94:95], v[86:87] neg_lo:[0,1] neg_hi:[0,1]
	v_pk_add_f32 v[94:95], v[84:85], v[92:93]
	v_mov_b32_e32 v93, v123
	v_mov_b32_e32 v85, v89
	v_pk_add_f32 v[102:103], v[122:123], v[88:89]
	v_pk_add_f32 v[84:85], v[92:93], v[84:85]
	v_mov_b32_e32 v88, v94
	v_pk_add_f32 v[84:85], v[84:85], v[126:127] neg_lo:[0,1] neg_hi:[0,1]
	v_mov_b32_e32 v89, v103
	v_pk_add_f32 v[88:89], v[88:89], v[84:85] neg_lo:[0,1] neg_hi:[0,1]
	v_pk_add_f32 v[84:85], v[86:87], v[84:85] neg_lo:[0,1] neg_hi:[0,1]
	v_pk_add_f32 v[88:89], v[92:93], v[88:89] neg_lo:[0,1] neg_hi:[0,1]
	v_pk_add_f32 v[86:87], v[102:103], v[94:95]
	v_pk_add_f32 v[84:85], v[84:85], v[88:89]
	v_pk_add_f32 v[88:89], v[118:119], v[86:87]
	s_nop 0
	v_pk_add_f32 v[92:93], v[88:89], v[118:119] neg_lo:[0,1] neg_hi:[0,1]
	s_nop 0
	v_pk_add_f32 v[86:87], v[86:87], v[92:93] neg_lo:[0,1] neg_hi:[0,1]
	s_nop 0
	v_pk_add_f32 v[84:85], v[84:85], v[86:87]
	s_nop 0
	v_pk_add_f32 v[84:85], v[88:89], v[84:85]
	v_pk_mul_f32 v[88:89], v[100:101], v[110:111]
	v_cndmask_b32_e32 v84, v160, v84, vcc
	v_cmp_neq_f32_e32 vcc, s8, v130
	v_pk_add_f32 v[92:93], v[98:99], v[88:89]
	s_nop 0
	v_cndmask_b32_e32 v85, v160, v85, vcc
	v_cmp_ngt_f32_e32 vcc, -1.0, v130
	v_pk_add_f32 v[98:99], v[92:93], v[98:99] neg_lo:[0,1] neg_hi:[0,1]
	v_mov_b32_e32 v116, v92
	v_cndmask_b32_e32 v85, v161, v85, vcc
	v_cmp_ngt_f32_e32 vcc, -1.0, v83
	v_pk_add_f32 v[88:89], v[88:89], v[98:99] neg_lo:[0,1] neg_hi:[0,1]
	s_nop 0
	v_cndmask_b32_e32 v84, v161, v84, vcc
	v_cmp_neq_f32_e32 vcc, -1.0, v83
	v_pk_add_f32 v[100:101], v[90:91], v[88:89]
; __device__ __forceinline__ float softplusf(float x) { return fmaxf(x, 0.f) + log1pf(__expf(-fabsf(x))); }
; __device__ void phaseA_tile(const Params& p, int l, int mt, int nt, char* smem) {
;     ...
;                 for (int j = 0; j < 2; ++j) {
;                     const int c = j * 16 + g4 * 4;
;                     const float4 db = *(const float4*)(p.dt_bias + l * 32 + c);
;                     const f32x4 v = acc[i][j];
;                     *(float4*)(p.dtb + (size_t)row * 32 + c) =
;                         make_float4(softplusf(v[0] + db.x), softplusf(v[1] + db.y), softplusf(v[2] + db.z), softplusf(v[3] + db.w));
	v_mov_b32_e32 v99, v89
	v_cndmask_b32_e32 v84, v162, v84, vcc
	v_cmp_neq_f32_e32 vcc, -1.0, v130
	v_mov_b32_e32 v91, v101
	v_mov_b32_e32 v89, v93
	v_cndmask_b32_e32 v85, v162, v85, vcc
	v_cmp_lt_f32_e64 vcc, |v83|, s9
	v_cndmask_b32_e64 v85, v85, v130, s[0:1]
	v_pk_add_f32 v[88:89], v[90:91], v[88:89]
	v_cndmask_b32_e32 v84, v84, v83, vcc
	v_pk_add_f32 v[78:79], v[78:79], v[84:85]
	v_cvt_f32_i32_e32 v85, v134
	v_cvt_f32_i32_e32 v84, v132
	v_pk_add_f32 v[90:91], v[92:93], v[100:101]
	v_cmp_neq_f32_e32 vcc, s8, v131
	v_mov_b32_e32 v114, v90
	v_pk_mul_f32 v[86:87], v[84:85], s[12:13] op_sel_hi:[1,0]
	v_mov_b32_e32 v119, v91
	v_pk_fma_f32 v[94:95], v[84:85], s[12:13], v[86:87] op_sel_hi:[1,0,1] neg_lo:[0,0,1] neg_hi:[0,0,1]
	v_mov_b32_e32 v98, v86
	v_pk_fma_f32 v[84:85], v[84:85], s[14:15], v[94:95] op_sel_hi:[1,0,1]
	v_cmp_lt_f32_e64 s[0:1], |v133|, s9
	v_pk_add_f32 v[94:95], v[86:87], v[84:85]
	v_mov_b32_e32 v112, v84
	v_pk_add_f32 v[102:103], v[94:95], v[90:91]
	v_mov_b32_e32 v117, v95
	v_mov_b32_e32 v115, v103
	v_pk_add_f32 v[114:115], v[114:115], v[116:117] neg_lo:[0,1] neg_hi:[0,1]
	v_pk_add_f32 v[98:99], v[98:99], v[112:113]
	v_mov_b32_e32 v110, v102
	v_mov_b32_e32 v111, v95
	v_mov_b32_e32 v112, v94
	v_mov_b32_e32 v113, v87
	v_mov_b32_e32 v116, v94
	v_mov_b32_e32 v117, v103
	v_mov_b32_e32 v87, v115
	v_pk_add_f32 v[110:111], v[110:111], v[112:113] neg_lo:[0,1] neg_hi:[0,1]
	v_mov_b32_e32 v112, v90
	v_mov_b32_e32 v113, v85
	v_pk_add_f32 v[86:87], v[116:117], v[86:87] neg_lo:[0,1] neg_hi:[0,1]
	v_pk_add_f32 v[112:113], v[112:113], v[110:111] neg_lo:[0,1] neg_hi:[0,1]
	v_mov_b32_e32 v116, v86
	v_mov_b32_e32 v117, v111
	v_mov_b32_e32 v118, v102
	v_mov_b32_e32 v111, v93
	v_pk_add_f32 v[116:117], v[84:85], v[116:117] neg_lo:[0,1] neg_hi:[0,1]
	v_pk_add_f32 v[110:111], v[118:119], v[110:111] neg_lo:[0,1] neg_hi:[0,1]
	v_mov_b32_e32 v85, v95
	v_pk_add_f32 v[90:91], v[90:91], v[92:93] neg_lo:[0,1] neg_hi:[0,1]
	v_pk_add_f32 v[92:93], v[98:99], v[110:111] neg_lo:[0,1] neg_hi:[0,1]
	v_pk_add_f32 v[84:85], v[84:85], v[86:87] neg_lo:[0,1] neg_hi:[0,1]
	v_pk_add_f32 v[86:87], v[88:89], v[114:115] neg_lo:[0,1] neg_hi:[0,1]
	v_pk_add_f32 v[94:95], v[112:113], v[92:93]
	v_pk_add_f32 v[88:89], v[86:87], v[84:85]
	v_mov_b32_e32 v85, v113
	v_mov_b32_e32 v87, v93
	v_pk_add_f32 v[86:87], v[84:85], v[86:87]
	v_mov_b32_e32 v92, v88
	v_pk_add_f32 v[86:87], v[86:87], v[116:117] neg_lo:[0,1] neg_hi:[0,1]
	v_mov_b32_e32 v93, v95
	v_pk_add_f32 v[90:91], v[100:101], v[90:91] neg_lo:[0,1] neg_hi:[0,1]
	v_pk_add_f32 v[92:93], v[92:93], v[86:87] neg_lo:[0,1] neg_hi:[0,1]
	v_pk_add_f32 v[86:87], v[90:91], v[86:87] neg_lo:[0,1] neg_hi:[0,1]
	v_pk_add_f32 v[84:85], v[84:85], v[92:93] neg_lo:[0,1] neg_hi:[0,1]
	s_nop 0
	v_pk_add_f32 v[84:85], v[86:87], v[84:85]
	v_pk_add_f32 v[86:87], v[94:95], v[88:89]
	s_nop 0
	v_pk_add_f32 v[88:89], v[102:103], v[86:87]
	s_nop 0
	v_pk_add_f32 v[90:91], v[88:89], v[102:103] neg_lo:[0,1] neg_hi:[0,1]
	s_nop 0
	v_pk_add_f32 v[86:87], v[86:87], v[90:91] neg_lo:[0,1] neg_hi:[0,1]
	s_nop 0
	v_pk_add_f32 v[84:85], v[84:85], v[86:87]
	s_nop 0
	v_pk_add_f32 v[84:85], v[88:89], v[84:85]
	s_nop 0
	v_cndmask_b32_e32 v83, v160, v84, vcc
	v_cmp_neq_f32_e32 vcc, s8, v133
	s_nop 1
	v_cndmask_b32_e32 v84, v160, v85, vcc
	v_cmp_ngt_f32_e32 vcc, -1.0, v133
	s_nop 1
	v_cndmask_b32_e32 v84, v161, v84, vcc
	v_cmp_ngt_f32_e32 vcc, -1.0, v131
	s_nop 1
	v_cndmask_b32_e32 v83, v161, v83, vcc
	v_cmp_neq_f32_e32 vcc, -1.0, v131
	s_nop 1
	v_cndmask_b32_e32 v83, v162, v83, vcc
	v_cmp_neq_f32_e32 vcc, -1.0, v133
	s_nop 1
	v_cndmask_b32_e32 v84, v162, v84, vcc
	v_cmp_lt_f32_e64 vcc, |v131|, s9
	v_cndmask_b32_e64 v85, v84, v133, s[0:1]
	s_nop 0
	v_cndmask_b32_e32 v84, v83, v131, vcc
	v_pk_add_f32 v[80:81], v[80:81], v[84:85]
	global_store_dwordx4 v[76:77], v[78:81], off
	global_load_dwordx4 v[78:81], v0, s[74:75] offset:64
	s_waitcnt vmcnt(0)
	v_add_f32_e32 v83, v42, v78
	v_max_f32_e32 v78, 0, v83
	v_mul_f32_e64 v83, |v83|, s2
	v_exp_f32_e32 v83, v83
	s_nop 0
	v_add_f32_e32 v86, 1.0, v83
	v_add_f32_e32 v84, -1.0, v86
	v_sub_f32_e32 v85, v84, v86
	v_add_f32_e32 v85, 1.0, v85
	v_sub_f32_e32 v84, v83, v84
	v_add_f32_e32 v87, v84, v85
	v_frexp_mant_f32_e32 v84, v86
	v_cmp_gt_f32_e32 vcc, s26, v84
	v_cvt_f64_f32_e32 v[84:85], v86
	v_frexp_exp_i32_f64_e32 v84, v[84:85]
	v_subbrev_co_u32_e32 v97, vcc, 0, v84, vcc
	v_sub_u32_e32 v85, 0, v97
	v_ldexp_f32 v84, v86, v85
	v_ldexp_f32 v86, v87, v85
	v_add_f32_e32 v85, v43, v79
	v_max_f32_e32 v79, 0, v85
	v_mul_f32_e64 v85, |v85|, s2
	v_exp_f32_e32 v130, v85
	s_nop 0
	v_add_f32_e32 v85, 1.0, v130
	v_add_f32_e32 v87, -1.0, v85
	v_sub_f32_e32 v88, v87, v85
	v_add_f32_e32 v88, 1.0, v88
	v_sub_f32_e32 v87, v130, v87
	v_add_f32_e32 v87, v87, v88
	v_frexp_mant_f32_e32 v88, v85
	v_cmp_gt_f32_e32 vcc, s26, v88
	v_cvt_f64_f32_e32 v[88:89], v85
	v_frexp_exp_i32_f64_e32 v88, v[88:89]
	v_subbrev_co_u32_e32 v122, vcc, 0, v88, vcc
	v_sub_u32_e32 v88, 0, v122
	v_ldexp_f32 v85, v85, v88
	v_ldexp_f32 v87, v87, v88
	v_pk_add_f32 v[88:89], v[84:85], 1.0 op_sel_hi:[1,0]
	v_pk_add_f32 v[98:99], v[84:85], -1.0 op_sel_hi:[1,0]
	v_pk_add_f32 v[90:91], v[88:89], -1.0 op_sel_hi:[1,0]
	v_pk_add_f32 v[100:101], v[98:99], 1.0 op_sel_hi:[1,0]
	v_pk_add_f32 v[90:91], v[84:85], v[90:91] neg_lo:[0,1] neg_hi:[0,1]
	v_pk_add_f32 v[84:85], v[84:85], v[100:101] neg_lo:[0,1] neg_hi:[0,1]
	v_pk_add_f32 v[90:91], v[86:87], v[90:91]
	v_pk_add_f32 v[84:85], v[86:87], v[84:85]
	v_pk_add_f32 v[92:93], v[88:89], v[90:91]
	v_pk_add_f32 v[86:87], v[98:99], v[84:85]
	v_rcp_f32_e32 v94, v92
	v_rcp_f32_e32 v95, v93
	v_pk_add_f32 v[88:89], v[92:93], v[88:89] neg_lo:[0,1] neg_hi:[0,1]
; __device__ __forceinline__ float softplusf(float x) { return fmaxf(x, 0.f) + log1pf(__expf(-fabsf(x))); }
; __device__ void phaseA_tile(const Params& p, int l, int mt, int nt, char* smem) {
;     ...
;                 for (int j = 0; j < 2; ++j) {
;                     const int c = j * 16 + g4 * 4;
;                     const float4 db = *(const float4*)(p.dt_bias + l * 32 + c);
;                     const f32x4 v = acc[i][j];
;                     *(float4*)(p.dtb + (size_t)row * 32 + c) =
;                         make_float4(softplusf(v[0] + db.x), softplusf(v[1] + db.y), softplusf(v[2] + db.z), softplusf(v[3] + db.w));
	v_pk_add_f32 v[98:99], v[86:87], v[98:99] neg_lo:[0,1] neg_hi:[0,1]
	v_pk_add_f32 v[88:89], v[90:91], v[88:89] neg_lo:[0,1] neg_hi:[0,1]
	v_pk_mul_f32 v[90:91], v[86:87], v[94:95]
	v_pk_add_f32 v[84:85], v[84:85], v[98:99] neg_lo:[0,1] neg_hi:[0,1]
	v_pk_mul_f32 v[98:99], v[92:93], v[90:91]
	v_cmp_lt_f32_e64 s[0:1], |v130|, s9
	v_pk_fma_f32 v[100:101], v[90:91], v[92:93], v[98:99] neg_lo:[0,0,1] neg_hi:[0,0,1]
	s_nop 0
	v_pk_fma_f32 v[100:101], v[90:91], v[88:89], v[100:101]
	s_nop 0
	v_pk_add_f32 v[102:103], v[98:99], v[100:101]
	s_nop 0
	v_pk_add_f32 v[110:111], v[86:87], v[102:103] neg_lo:[0,1] neg_hi:[0,1]
	v_pk_add_f32 v[98:99], v[102:103], v[98:99] neg_lo:[0,1] neg_hi:[0,1]
	v_pk_add_f32 v[86:87], v[86:87], v[110:111] neg_lo:[0,1] neg_hi:[0,1]
	s_nop 0
	v_pk_add_f32 v[86:87], v[86:87], v[102:103] neg_lo:[0,1] neg_hi:[0,1]
	s_nop 0
	v_pk_add_f32 v[84:85], v[84:85], v[86:87]
	v_pk_add_f32 v[86:87], v[98:99], v[100:101] neg_lo:[0,1] neg_hi:[0,1]
	s_nop 0
	v_pk_add_f32 v[84:85], v[86:87], v[84:85]
	s_nop 0
	v_pk_add_f32 v[86:87], v[110:111], v[84:85]
	s_nop 0
	v_pk_mul_f32 v[98:99], v[94:95], v[86:87]
	s_nop 0
	v_pk_mul_f32 v[100:101], v[92:93], v[98:99]
	s_nop 0
	v_pk_fma_f32 v[92:93], v[98:99], v[92:93], v[100:101] neg_lo:[0,0,1] neg_hi:[0,0,1]
	s_nop 0
	v_pk_fma_f32 v[88:89], v[98:99], v[88:89], v[92:93]
	v_pk_add_f32 v[92:93], v[110:111], v[86:87] neg_lo:[0,1] neg_hi:[0,1]
	s_nop 0
	v_pk_add_f32 v[84:85], v[84:85], v[92:93]
	v_pk_add_f32 v[92:93], v[100:101], v[88:89]
	s_nop 0
	v_pk_add_f32 v[102:103], v[86:87], v[92:93] neg_lo:[0,1] neg_hi:[0,1]
	v_pk_add_f32 v[100:101], v[92:93], v[100:101] neg_lo:[0,1] neg_hi:[0,1]
	v_pk_add_f32 v[86:87], v[86:87], v[102:103] neg_lo:[0,1] neg_hi:[0,1]
	s_nop 0
	v_pk_add_f32 v[86:87], v[86:87], v[92:93] neg_lo:[0,1] neg_hi:[0,1]
	s_nop 0
	v_pk_add_f32 v[84:85], v[84:85], v[86:87]
	v_pk_add_f32 v[86:87], v[100:101], v[88:89] neg_lo:[0,1] neg_hi:[0,1]
	s_nop 0
	v_pk_add_f32 v[84:85], v[86:87], v[84:85]
	v_pk_add_f32 v[86:87], v[90:91], v[98:99]
	v_pk_add_f32 v[84:85], v[102:103], v[84:85]
	v_pk_add_f32 v[88:89], v[86:87], v[90:91] neg_lo:[0,1] neg_hi:[0,1]
	v_pk_mul_f32 v[84:85], v[94:95], v[84:85]
	v_pk_add_f32 v[88:89], v[98:99], v[88:89] neg_lo:[0,1] neg_hi:[0,1]
	s_nop 0
	v_pk_add_f32 v[84:85], v[88:89], v[84:85]
	s_nop 0
	v_pk_add_f32 v[88:89], v[86:87], v[84:85]
	s_nop 0
	v_pk_add_f32 v[86:87], v[88:89], v[86:87] neg_lo:[0,1] neg_hi:[0,1]
	v_pk_mul_f32 v[90:91], v[88:89], v[88:89]
	v_pk_add_f32 v[84:85], v[84:85], v[86:87] neg_lo:[0,1] neg_hi:[0,1]
	v_pk_fma_f32 v[92:93], v[90:91], s[28:29], v[66:67] op_sel_hi:[1,0,0]
	v_ldexp_f32 v95, v85, 1
	v_add_f32_e32 v85, v44, v80
	v_max_f32_e32 v80, 0, v85
	v_mul_f32_e64 v85, |v85|, s2
	v_exp_f32_e32 v131, v85
	v_ldexp_f32 v86, v88, 1
	v_pk_fma_f32 v[92:93], v[90:91], v[92:93], s[30:31] op_sel_hi:[1,1,0]
	v_ldexp_f32 v87, v89, 1
	v_add_f32_e32 v85, 1.0, v131
	v_pk_mul_f32 v[88:89], v[88:89], v[90:91]
	v_add_f32_e32 v90, -1.0, v85
	v_sub_f32_e32 v91, v90, v85
	v_add_f32_e32 v91, 1.0, v91
	v_sub_f32_e32 v90, v131, v90
	v_add_f32_e32 v94, v90, v91
	v_frexp_mant_f32_e32 v90, v85
	v_cmp_gt_f32_e32 vcc, s26, v90
	v_cvt_f64_f32_e32 v[90:91], v85
	v_frexp_exp_i32_f64_e32 v90, v[90:91]
	v_subbrev_co_u32_e32 v132, vcc, 0, v90, vcc
	v_sub_u32_e32 v91, 0, v132
	v_ldexp_f32 v90, v85, v91
	v_add_f32_e32 v85, v45, v81
	v_max_f32_e32 v81, 0, v85
	v_mul_f32_e64 v85, |v85|, s2
	v_exp_f32_e32 v133, v85
	v_ldexp_f32 v98, v94, v91
	v_pk_mul_f32 v[88:89], v[88:89], v[92:93]
	v_ldexp_f32 v84, v84, 1
	v_add_f32_e32 v85, 1.0, v133
	v_add_f32_e32 v91, -1.0, v85
	v_sub_f32_e32 v94, v91, v85
	v_add_f32_e32 v94, 1.0, v94
	v_sub_f32_e32 v91, v133, v91
	v_add_f32_e32 v94, v91, v94
	v_frexp_mant_f32_e32 v91, v85
	v_cvt_f64_f32_e32 v[100:101], v85
	v_cmp_gt_f32_e32 vcc, s26, v91
	v_frexp_exp_i32_f64_e32 v91, v[100:101]
	v_pk_add_f32 v[92:93], v[86:87], v[88:89]
	v_subbrev_co_u32_e32 v134, vcc, 0, v91, vcc
	v_sub_u32_e32 v99, 0, v134
	v_ldexp_f32 v91, v85, v99
	v_pk_add_f32 v[100:101], v[90:91], 1.0 op_sel_hi:[1,0]
	v_ldexp_f32 v99, v94, v99
	v_pk_add_f32 v[102:103], v[100:101], -1.0 op_sel_hi:[1,0]
	v_pk_add_f32 v[114:115], v[90:91], -1.0 op_sel_hi:[1,0]
	v_pk_add_f32 v[102:103], v[90:91], v[102:103] neg_lo:[0,1] neg_hi:[0,1]
	v_pk_add_f32 v[116:117], v[114:115], 1.0 op_sel_hi:[1,0]
	v_pk_add_f32 v[102:103], v[98:99], v[102:103]
	v_pk_add_f32 v[90:91], v[90:91], v[116:117] neg_lo:[0,1] neg_hi:[0,1]
	v_pk_add_f32 v[110:111], v[100:101], v[102:103]
	v_pk_add_f32 v[90:91], v[98:99], v[90:91]
	v_rcp_f32_e32 v112, v110
	v_rcp_f32_e32 v113, v111
	v_pk_add_f32 v[98:99], v[114:115], v[90:91]
	v_pk_add_f32 v[100:101], v[110:111], v[100:101] neg_lo:[0,1] neg_hi:[0,1]
	v_pk_add_f32 v[114:115], v[98:99], v[114:115] neg_lo:[0,1] neg_hi:[0,1]
	v_pk_add_f32 v[100:101], v[102:103], v[100:101] neg_lo:[0,1] neg_hi:[0,1]
	v_pk_mul_f32 v[102:103], v[98:99], v[112:113]
	v_pk_add_f32 v[90:91], v[90:91], v[114:115] neg_lo:[0,1] neg_hi:[0,1]
	v_pk_mul_f32 v[114:115], v[110:111], v[102:103]
	v_pk_add_f32 v[86:87], v[92:93], v[86:87] neg_lo:[0,1] neg_hi:[0,1]
	v_pk_fma_f32 v[116:117], v[102:103], v[110:111], v[114:115] neg_lo:[0,0,1] neg_hi:[0,0,1]
	v_pk_add_f32 v[86:87], v[88:89], v[86:87] neg_lo:[0,1] neg_hi:[0,1]
	v_pk_fma_f32 v[116:117], v[102:103], v[100:101], v[116:117]
	v_mov_b32_e32 v89, v87
	v_pk_add_f32 v[118:119], v[114:115], v[116:117]
	v_mov_b32_e32 v85, v95
	v_pk_add_f32 v[120:121], v[98:99], v[118:119] neg_lo:[0,1] neg_hi:[0,1]
	v_pk_add_f32 v[114:115], v[118:119], v[114:115] neg_lo:[0,1] neg_hi:[0,1]
	v_pk_add_f32 v[98:99], v[98:99], v[120:121] neg_lo:[0,1] neg_hi:[0,1]
	v_mov_b32_e32 v126, v92
; __device__ __forceinline__ float softplusf(float x) { return fmaxf(x, 0.f) + log1pf(__expf(-fabsf(x))); }
; __device__ void phaseA_tile(const Params& p, int l, int mt, int nt, char* smem) {
;     ...
;                 for (int j = 0; j < 2; ++j) {
;                     const int c = j * 16 + g4 * 4;
;                     const float4 db = *(const float4*)(p.dt_bias + l * 32 + c);
;                     const f32x4 v = acc[i][j];
;                     *(float4*)(p.dtb + (size_t)row * 32 + c) =
;                         make_float4(softplusf(v[0] + db.x), softplusf(v[1] + db.y), softplusf(v[2] + db.z), softplusf(v[3] + db.w));
	v_pk_add_f32 v[98:99], v[98:99], v[118:119] neg_lo:[0,1] neg_hi:[0,1]
	v_cmp_neq_f32_e32 vcc, s8, v83
	v_pk_add_f32 v[90:91], v[90:91], v[98:99]
	v_pk_add_f32 v[98:99], v[114:115], v[116:117] neg_lo:[0,1] neg_hi:[0,1]
	s_nop 0
	v_pk_add_f32 v[90:91], v[98:99], v[90:91]
	s_nop 0
	v_pk_add_f32 v[98:99], v[120:121], v[90:91]
	s_nop 0
	v_pk_mul_f32 v[114:115], v[112:113], v[98:99]
	s_nop 0
	v_pk_mul_f32 v[116:117], v[110:111], v[114:115]
	s_nop 0
	v_pk_fma_f32 v[110:111], v[114:115], v[110:111], v[116:117] neg_lo:[0,0,1] neg_hi:[0,0,1]
	s_nop 0
	v_pk_fma_f32 v[100:101], v[114:115], v[100:101], v[110:111]
	v_pk_add_f32 v[110:111], v[120:121], v[98:99] neg_lo:[0,1] neg_hi:[0,1]
	s_nop 0
	v_pk_add_f32 v[90:91], v[90:91], v[110:111]
	v_pk_add_f32 v[110:111], v[116:117], v[100:101]
	s_nop 0
	v_pk_add_f32 v[118:119], v[98:99], v[110:111] neg_lo:[0,1] neg_hi:[0,1]
	v_pk_add_f32 v[116:117], v[110:111], v[116:117] neg_lo:[0,1] neg_hi:[0,1]
	v_pk_add_f32 v[98:99], v[98:99], v[118:119] neg_lo:[0,1] neg_hi:[0,1]
	s_nop 0
	v_pk_add_f32 v[98:99], v[98:99], v[110:111] neg_lo:[0,1] neg_hi:[0,1]
	s_nop 0
	v_pk_add_f32 v[90:91], v[90:91], v[98:99]
	v_pk_add_f32 v[98:99], v[116:117], v[100:101] neg_lo:[0,1] neg_hi:[0,1]
	s_nop 0
	v_pk_add_f32 v[90:91], v[98:99], v[90:91]
	v_pk_add_f32 v[98:99], v[102:103], v[114:115]
	v_pk_add_f32 v[90:91], v[118:119], v[90:91]
	v_pk_add_f32 v[100:101], v[98:99], v[102:103] neg_lo:[0,1] neg_hi:[0,1]
	v_pk_mul_f32 v[90:91], v[112:113], v[90:91]
	v_pk_add_f32 v[100:101], v[114:115], v[100:101] neg_lo:[0,1] neg_hi:[0,1]
	s_nop 0
	v_pk_add_f32 v[90:91], v[100:101], v[90:91]
	s_nop 0
	v_pk_add_f32 v[100:101], v[98:99], v[90:91]
	s_nop 0
	v_pk_mul_f32 v[102:103], v[100:101], v[100:101]
	v_pk_add_f32 v[98:99], v[100:101], v[98:99] neg_lo:[0,1] neg_hi:[0,1]
	v_pk_fma_f32 v[110:111], v[102:103], s[28:29], v[66:67] op_sel_hi:[1,0,0]
	v_pk_add_f32 v[90:91], v[90:91], v[98:99] neg_lo:[0,1] neg_hi:[0,1]
	v_ldexp_f32 v98, v100, 1
	v_pk_fma_f32 v[110:111], v[102:103], v[110:111], s[30:31] op_sel_hi:[1,1,0]
	v_ldexp_f32 v99, v101, 1
	v_pk_mul_f32 v[100:101], v[100:101], v[102:103]
	v_cvt_f32_i32_e32 v103, v122
	v_cvt_f32_i32_e32 v102, v97
	v_ldexp_f32 v113, v91, 1
	v_ldexp_f32 v90, v90, 1
	v_mov_b32_e32 v91, v113
	v_pk_mul_f32 v[114:115], v[102:103], s[12:13] op_sel_hi:[1,0]
	s_nop 0
	v_pk_fma_f32 v[116:117], v[102:103], s[12:13], v[114:115] op_sel_hi:[1,0,1] neg_lo:[0,0,1] neg_hi:[0,0,1]
	v_mov_b32_e32 v88, v114
	v_pk_fma_f32 v[102:103], v[102:103], s[14:15], v[116:117] op_sel_hi:[1,0,1]
	v_mov_b32_e32 v123, v115
	v_mov_b32_e32 v94, v102
	v_pk_add_f32 v[88:89], v[88:89], v[94:95]
	v_pk_add_f32 v[94:95], v[84:85], v[86:87]
	v_mov_b32_e32 v87, v93
	v_mov_b32_e32 v85, v95
	v_pk_add_f32 v[116:117], v[114:115], v[102:103]
	v_pk_add_f32 v[84:85], v[84:85], v[86:87]
	v_pk_add_f32 v[86:87], v[92:93], v[94:95]
	v_mov_b32_e32 v127, v117
	v_pk_add_f32 v[118:119], v[116:117], v[86:87]
	v_mov_b32_e32 v124, v86
	v_mov_b32_e32 v125, v119
	v_pk_add_f32 v[124:125], v[124:125], v[126:127] neg_lo:[0,1] neg_hi:[0,1]
	v_mov_b32_e32 v120, v118
	v_mov_b32_e32 v121, v117
	v_mov_b32_e32 v122, v116
	v_mov_b32_e32 v126, v116
	v_mov_b32_e32 v127, v119
	v_mov_b32_e32 v115, v125
	v_pk_add_f32 v[120:121], v[120:121], v[122:123] neg_lo:[0,1] neg_hi:[0,1]
	v_mov_b32_e32 v122, v86
	v_mov_b32_e32 v123, v103
	v_pk_add_f32 v[114:115], v[126:127], v[114:115] neg_lo:[0,1] neg_hi:[0,1]
	v_pk_add_f32 v[122:123], v[122:123], v[120:121] neg_lo:[0,1] neg_hi:[0,1]
	v_mov_b32_e32 v126, v114
	v_mov_b32_e32 v127, v121
	v_mov_b32_e32 v128, v118
	v_mov_b32_e32 v129, v87
	v_mov_b32_e32 v121, v93
	v_pk_add_f32 v[126:127], v[102:103], v[126:127] neg_lo:[0,1] neg_hi:[0,1]
	v_pk_add_f32 v[120:121], v[128:129], v[120:121] neg_lo:[0,1] neg_hi:[0,1]
	v_mov_b32_e32 v103, v117
	v_pk_add_f32 v[86:87], v[86:87], v[92:93] neg_lo:[0,1] neg_hi:[0,1]
	v_pk_add_f32 v[88:89], v[88:89], v[120:121] neg_lo:[0,1] neg_hi:[0,1]
	v_pk_add_f32 v[92:93], v[102:103], v[114:115] neg_lo:[0,1] neg_hi:[0,1]
	v_pk_add_f32 v[84:85], v[84:85], v[124:125] neg_lo:[0,1] neg_hi:[0,1]
	v_pk_add_f32 v[86:87], v[94:95], v[86:87] neg_lo:[0,1] neg_hi:[0,1]
	v_pk_add_f32 v[94:95], v[84:85], v[92:93]
	v_mov_b32_e32 v93, v123
	v_mov_b32_e32 v85, v89
	v_pk_add_f32 v[102:103], v[122:123], v[88:89]
	v_pk_add_f32 v[84:85], v[92:93], v[84:85]
	v_mov_b32_e32 v88, v94
	v_pk_add_f32 v[84:85], v[84:85], v[126:127] neg_lo:[0,1] neg_hi:[0,1]
	v_mov_b32_e32 v89, v103
	v_pk_add_f32 v[88:89], v[88:89], v[84:85] neg_lo:[0,1] neg_hi:[0,1]
	v_pk_add_f32 v[84:85], v[86:87], v[84:85] neg_lo:[0,1] neg_hi:[0,1]
	v_pk_add_f32 v[88:89], v[92:93], v[88:89] neg_lo:[0,1] neg_hi:[0,1]
	v_pk_add_f32 v[86:87], v[102:103], v[94:95]
	v_pk_add_f32 v[84:85], v[84:85], v[88:89]
	v_pk_add_f32 v[88:89], v[118:119], v[86:87]
	s_nop 0
	v_pk_add_f32 v[92:93], v[88:89], v[118:119] neg_lo:[0,1] neg_hi:[0,1]
	s_nop 0
	v_pk_add_f32 v[86:87], v[86:87], v[92:93] neg_lo:[0,1] neg_hi:[0,1]
	s_nop 0
	v_pk_add_f32 v[84:85], v[84:85], v[86:87]
	s_nop 0
	v_pk_add_f32 v[84:85], v[88:89], v[84:85]
	v_pk_mul_f32 v[88:89], v[100:101], v[110:111]
	v_cndmask_b32_e32 v84, v160, v84, vcc
	v_cmp_neq_f32_e32 vcc, s8, v130
	v_pk_add_f32 v[92:93], v[98:99], v[88:89]
	s_nop 0
	v_cndmask_b32_e32 v85, v160, v85, vcc
	v_cmp_ngt_f32_e32 vcc, -1.0, v130
	v_pk_add_f32 v[98:99], v[92:93], v[98:99] neg_lo:[0,1] neg_hi:[0,1]
	v_mov_b32_e32 v116, v92
	v_cndmask_b32_e32 v85, v161, v85, vcc
	v_cmp_ngt_f32_e32 vcc, -1.0, v83
	v_pk_add_f32 v[88:89], v[88:89], v[98:99] neg_lo:[0,1] neg_hi:[0,1]
	s_nop 0
	v_cndmask_b32_e32 v84, v161, v84, vcc
	v_cmp_neq_f32_e32 vcc, -1.0, v83
	v_pk_add_f32 v[100:101], v[90:91], v[88:89]
; __device__ __forceinline__ float softplusf(float x) { return fmaxf(x, 0.f) + log1pf(__expf(-fabsf(x))); }
; __device__ __forceinline__ float logsigf(float x) { return fminf(x, 0.f) - log1pf(__expf(-fabsf(x))); }
; __device__ void phaseA_tile(const Params& p, int l, int mt, int nt, char* smem) {
;     ...
;                 for (int j = 0; j < 2; ++j) {
;                     const int c = j * 16 + g4 * 4;
;                     const float4 db = *(const float4*)(p.dt_bias + l * 32 + c);
;                     const f32x4 v = acc[i][j];
;                     *(float4*)(p.dtb + (size_t)row * 32 + c) =
;                         make_float4(softplusf(v[0] + db.x), softplusf(v[1] + db.y), softplusf(v[2] + db.z), softplusf(v[3] + db.w));
;                 }
;                 {
;                     const int c = g4 * 4;
;                     const float4 fb = *(const float4*)(p.b_f + l * 16 + c);
;                     const f32x4 v = acc[i][2];
;                     float4 lf = make_float4(logsigf(v[0] + fb.x), logsigf(v[1] + fb.y), logsigf(v[2] + fb.z), logsigf(v[3] + fb.w));
	v_mov_b32_e32 v99, v89
	v_cndmask_b32_e32 v84, v162, v84, vcc
	v_cmp_neq_f32_e32 vcc, -1.0, v130
	v_mov_b32_e32 v91, v101
	v_mov_b32_e32 v89, v93
	v_cndmask_b32_e32 v85, v162, v85, vcc
	v_cmp_lt_f32_e64 vcc, |v83|, s9
	v_cndmask_b32_e64 v85, v85, v130, s[0:1]
	v_pk_add_f32 v[88:89], v[90:91], v[88:89]
	v_cndmask_b32_e32 v84, v84, v83, vcc
	v_pk_add_f32 v[78:79], v[78:79], v[84:85]
	v_cvt_f32_i32_e32 v85, v134
	v_cvt_f32_i32_e32 v84, v132
	v_pk_add_f32 v[90:91], v[92:93], v[100:101]
	v_cmp_neq_f32_e32 vcc, s8, v131
	v_mov_b32_e32 v114, v90
	v_pk_mul_f32 v[86:87], v[84:85], s[12:13] op_sel_hi:[1,0]
	v_mov_b32_e32 v119, v91
	v_pk_fma_f32 v[94:95], v[84:85], s[12:13], v[86:87] op_sel_hi:[1,0,1] neg_lo:[0,0,1] neg_hi:[0,0,1]
	v_mov_b32_e32 v98, v86
	v_pk_fma_f32 v[84:85], v[84:85], s[14:15], v[94:95] op_sel_hi:[1,0,1]
	v_cmp_lt_f32_e64 s[0:1], |v133|, s9
	v_pk_add_f32 v[94:95], v[86:87], v[84:85]
	v_mov_b32_e32 v112, v84
	v_pk_add_f32 v[102:103], v[94:95], v[90:91]
	v_mov_b32_e32 v117, v95
	v_mov_b32_e32 v115, v103
	v_pk_add_f32 v[114:115], v[114:115], v[116:117] neg_lo:[0,1] neg_hi:[0,1]
	v_pk_add_f32 v[98:99], v[98:99], v[112:113]
	v_mov_b32_e32 v110, v102
	v_mov_b32_e32 v111, v95
	v_mov_b32_e32 v112, v94
	v_mov_b32_e32 v113, v87
	v_mov_b32_e32 v116, v94
	v_mov_b32_e32 v117, v103
	v_mov_b32_e32 v87, v115
	v_pk_add_f32 v[110:111], v[110:111], v[112:113] neg_lo:[0,1] neg_hi:[0,1]
	v_mov_b32_e32 v112, v90
	v_mov_b32_e32 v113, v85
	v_pk_add_f32 v[86:87], v[116:117], v[86:87] neg_lo:[0,1] neg_hi:[0,1]
	v_pk_add_f32 v[112:113], v[112:113], v[110:111] neg_lo:[0,1] neg_hi:[0,1]
	v_mov_b32_e32 v116, v86
	v_mov_b32_e32 v117, v111
	v_mov_b32_e32 v118, v102
	v_mov_b32_e32 v111, v93
	v_pk_add_f32 v[116:117], v[84:85], v[116:117] neg_lo:[0,1] neg_hi:[0,1]
	v_pk_add_f32 v[110:111], v[118:119], v[110:111] neg_lo:[0,1] neg_hi:[0,1]
	v_mov_b32_e32 v85, v95
	v_pk_add_f32 v[90:91], v[90:91], v[92:93] neg_lo:[0,1] neg_hi:[0,1]
	v_pk_add_f32 v[92:93], v[98:99], v[110:111] neg_lo:[0,1] neg_hi:[0,1]
	v_pk_add_f32 v[84:85], v[84:85], v[86:87] neg_lo:[0,1] neg_hi:[0,1]
	v_pk_add_f32 v[86:87], v[88:89], v[114:115] neg_lo:[0,1] neg_hi:[0,1]
	v_pk_add_f32 v[94:95], v[112:113], v[92:93]
	v_pk_add_f32 v[88:89], v[86:87], v[84:85]
	v_mov_b32_e32 v85, v113
	v_mov_b32_e32 v87, v93
	v_pk_add_f32 v[86:87], v[84:85], v[86:87]
	v_mov_b32_e32 v92, v88
	v_pk_add_f32 v[86:87], v[86:87], v[116:117] neg_lo:[0,1] neg_hi:[0,1]
	v_mov_b32_e32 v93, v95
	v_pk_add_f32 v[90:91], v[100:101], v[90:91] neg_lo:[0,1] neg_hi:[0,1]
	v_pk_add_f32 v[92:93], v[92:93], v[86:87] neg_lo:[0,1] neg_hi:[0,1]
	v_pk_add_f32 v[86:87], v[90:91], v[86:87] neg_lo:[0,1] neg_hi:[0,1]
	v_pk_add_f32 v[84:85], v[84:85], v[92:93] neg_lo:[0,1] neg_hi:[0,1]
	s_nop 0
	v_pk_add_f32 v[84:85], v[86:87], v[84:85]
	v_pk_add_f32 v[86:87], v[94:95], v[88:89]
	s_nop 0
	v_pk_add_f32 v[88:89], v[102:103], v[86:87]
	s_nop 0
	v_pk_add_f32 v[90:91], v[88:89], v[102:103] neg_lo:[0,1] neg_hi:[0,1]
	s_nop 0
	v_pk_add_f32 v[86:87], v[86:87], v[90:91] neg_lo:[0,1] neg_hi:[0,1]
	s_nop 0
	v_pk_add_f32 v[84:85], v[84:85], v[86:87]
	s_nop 0
	v_pk_add_f32 v[84:85], v[88:89], v[84:85]
	s_nop 0
	v_cndmask_b32_e32 v83, v160, v84, vcc
	v_cmp_neq_f32_e32 vcc, s8, v133
	s_nop 1
	v_cndmask_b32_e32 v84, v160, v85, vcc
	v_cmp_ngt_f32_e32 vcc, -1.0, v133
	s_nop 1
	v_cndmask_b32_e32 v84, v161, v84, vcc
	v_cmp_ngt_f32_e32 vcc, -1.0, v131
	s_nop 1
	v_cndmask_b32_e32 v83, v161, v83, vcc
	v_cmp_neq_f32_e32 vcc, -1.0, v131
	s_nop 1
	v_cndmask_b32_e32 v83, v162, v83, vcc
	v_cmp_neq_f32_e32 vcc, -1.0, v133
	s_nop 1
	v_cndmask_b32_e32 v84, v162, v84, vcc
	v_cmp_lt_f32_e64 vcc, |v131|, s9
	v_cndmask_b32_e64 v85, v84, v133, s[0:1]
	s_nop 0
	v_cndmask_b32_e32 v84, v83, v131, vcc
	v_pk_add_f32 v[80:81], v[80:81], v[84:85]
	global_store_dwordx4 v[76:77], v[78:81], off offset:64
	global_load_dwordx4 v[76:79], v0, s[78:79]
	s_waitcnt vmcnt(0)
	v_add_f32_e32 v80, v38, v76
	v_min_f32_e32 v76, 0, v80
	v_mul_f32_e64 v80, |v80|, s2
	v_exp_f32_e32 v83, v80
	s_nop 0
	v_add_f32_e32 v84, 1.0, v83
	v_add_f32_e32 v80, -1.0, v84
	v_sub_f32_e32 v81, v80, v84
	v_add_f32_e32 v81, 1.0, v81
	v_sub_f32_e32 v80, v83, v80
	v_add_f32_e32 v85, v80, v81
	v_frexp_mant_f32_e32 v80, v84
	v_cmp_gt_f32_e32 vcc, s26, v80
	v_cvt_f64_f32_e32 v[80:81], v84
	v_frexp_exp_i32_f64_e32 v80, v[80:81]
	v_subbrev_co_u32_e32 v97, vcc, 0, v80, vcc
	v_sub_u32_e32 v81, 0, v97
	v_ldexp_f32 v80, v84, v81
	v_ldexp_f32 v84, v85, v81
	v_add_f32_e32 v81, v39, v77
	v_min_f32_e32 v77, 0, v81
	v_mul_f32_e64 v81, |v81|, s2
	v_exp_f32_e32 v128, v81
	s_nop 0
	v_add_f32_e32 v81, 1.0, v128
	v_add_f32_e32 v85, -1.0, v81
	v_sub_f32_e32 v86, v85, v81
	v_add_f32_e32 v86, 1.0, v86
	v_sub_f32_e32 v85, v128, v85
	v_add_f32_e32 v85, v85, v86
	v_frexp_mant_f32_e32 v86, v81
	v_cmp_gt_f32_e32 vcc, s26, v86
	v_cvt_f64_f32_e32 v[86:87], v81
	v_frexp_exp_i32_f64_e32 v86, v[86:87]
	v_subbrev_co_u32_e32 v120, vcc, 0, v86, vcc
	v_sub_u32_e32 v86, 0, v120
	v_ldexp_f32 v81, v81, v86
	v_ldexp_f32 v85, v85, v86
	v_pk_add_f32 v[86:87], v[80:81], 1.0 op_sel_hi:[1,0]
	v_pk_add_f32 v[94:95], v[80:81], -1.0 op_sel_hi:[1,0]
	v_pk_add_f32 v[88:89], v[86:87], -1.0 op_sel_hi:[1,0]
	v_pk_add_f32 v[98:99], v[94:95], 1.0 op_sel_hi:[1,0]
	v_pk_add_f32 v[88:89], v[80:81], v[88:89] neg_lo:[0,1] neg_hi:[0,1]
	v_pk_add_f32 v[80:81], v[80:81], v[98:99] neg_lo:[0,1] neg_hi:[0,1]
	v_pk_add_f32 v[88:89], v[84:85], v[88:89]
	v_pk_add_f32 v[80:81], v[84:85], v[80:81]
	v_pk_add_f32 v[90:91], v[86:87], v[88:89]
	v_pk_add_f32 v[84:85], v[94:95], v[80:81]
	v_rcp_f32_e32 v92, v90
	v_rcp_f32_e32 v93, v91
	v_pk_add_f32 v[86:87], v[90:91], v[86:87] neg_lo:[0,1] neg_hi:[0,1]
; __device__ __forceinline__ float logsigf(float x) { return fminf(x, 0.f) - log1pf(__expf(-fabsf(x))); }
; __device__ void phaseA_tile(const Params& p, int l, int mt, int nt, char* smem) {
;     ...
;                     const int c = g4 * 4;
;                     const float4 fb = *(const float4*)(p.b_f + l * 16 + c);
;                     const f32x4 v = acc[i][2];
;                     float4 lf = make_float4(logsigf(v[0] + fb.x), logsigf(v[1] + fb.y), logsigf(v[2] + fb.z), logsigf(v[3] + fb.w));
;                     float* o = samp ? (p.out + O_LFS + ((size_t)l * TSM + (row - TP)) * 16 + c)
;                                     : (p.out + O_LFP + ((size_t)l * TP + row) * 16 + c);
;                     *(float4*)o = lf;
	v_pk_add_f32 v[94:95], v[84:85], v[94:95] neg_lo:[0,1] neg_hi:[0,1]
	v_pk_add_f32 v[86:87], v[88:89], v[86:87] neg_lo:[0,1] neg_hi:[0,1]
	v_pk_mul_f32 v[88:89], v[84:85], v[92:93]
	v_pk_add_f32 v[80:81], v[80:81], v[94:95] neg_lo:[0,1] neg_hi:[0,1]
	v_pk_mul_f32 v[94:95], v[90:91], v[88:89]
	v_cmp_lt_f32_e64 s[0:1], |v128|, s9
	v_pk_fma_f32 v[98:99], v[88:89], v[90:91], v[94:95] neg_lo:[0,0,1] neg_hi:[0,0,1]
	s_nop 0
	v_pk_fma_f32 v[98:99], v[88:89], v[86:87], v[98:99]
	s_nop 0
	v_pk_add_f32 v[100:101], v[94:95], v[98:99]
	s_nop 0
	v_pk_add_f32 v[102:103], v[84:85], v[100:101] neg_lo:[0,1] neg_hi:[0,1]
	v_pk_add_f32 v[94:95], v[100:101], v[94:95] neg_lo:[0,1] neg_hi:[0,1]
	v_pk_add_f32 v[84:85], v[84:85], v[102:103] neg_lo:[0,1] neg_hi:[0,1]
	s_nop 0
	v_pk_add_f32 v[84:85], v[84:85], v[100:101] neg_lo:[0,1] neg_hi:[0,1]
	s_nop 0
	v_pk_add_f32 v[80:81], v[80:81], v[84:85]
	v_pk_add_f32 v[84:85], v[94:95], v[98:99] neg_lo:[0,1] neg_hi:[0,1]
	s_nop 0
	v_pk_add_f32 v[80:81], v[84:85], v[80:81]
	s_nop 0
	v_pk_add_f32 v[84:85], v[102:103], v[80:81]
	s_nop 0
	v_pk_mul_f32 v[94:95], v[92:93], v[84:85]
	s_nop 0
	v_pk_mul_f32 v[98:99], v[90:91], v[94:95]
	s_nop 0
	v_pk_fma_f32 v[90:91], v[94:95], v[90:91], v[98:99] neg_lo:[0,0,1] neg_hi:[0,0,1]
	s_nop 0
	v_pk_fma_f32 v[86:87], v[94:95], v[86:87], v[90:91]
	v_pk_add_f32 v[90:91], v[102:103], v[84:85] neg_lo:[0,1] neg_hi:[0,1]
	s_nop 0
	v_pk_add_f32 v[80:81], v[80:81], v[90:91]
	v_pk_add_f32 v[90:91], v[98:99], v[86:87]
	s_nop 0
	v_pk_add_f32 v[100:101], v[84:85], v[90:91] neg_lo:[0,1] neg_hi:[0,1]
	v_pk_add_f32 v[98:99], v[90:91], v[98:99] neg_lo:[0,1] neg_hi:[0,1]
	v_pk_add_f32 v[84:85], v[84:85], v[100:101] neg_lo:[0,1] neg_hi:[0,1]
	s_nop 0
	v_pk_add_f32 v[84:85], v[84:85], v[90:91] neg_lo:[0,1] neg_hi:[0,1]
	s_nop 0
	v_pk_add_f32 v[80:81], v[80:81], v[84:85]
	v_pk_add_f32 v[84:85], v[98:99], v[86:87] neg_lo:[0,1] neg_hi:[0,1]
	s_nop 0
	v_pk_add_f32 v[80:81], v[84:85], v[80:81]
	v_pk_add_f32 v[84:85], v[88:89], v[94:95]
	v_pk_add_f32 v[80:81], v[100:101], v[80:81]
	v_pk_add_f32 v[86:87], v[84:85], v[88:89] neg_lo:[0,1] neg_hi:[0,1]
	v_pk_mul_f32 v[80:81], v[92:93], v[80:81]
	v_pk_add_f32 v[86:87], v[94:95], v[86:87] neg_lo:[0,1] neg_hi:[0,1]
	s_nop 0
	v_pk_add_f32 v[80:81], v[86:87], v[80:81]
	s_nop 0
	v_pk_add_f32 v[86:87], v[84:85], v[80:81]
	s_nop 0
	v_pk_add_f32 v[84:85], v[86:87], v[84:85] neg_lo:[0,1] neg_hi:[0,1]
	v_pk_mul_f32 v[88:89], v[86:87], v[86:87]
	v_pk_add_f32 v[80:81], v[80:81], v[84:85] neg_lo:[0,1] neg_hi:[0,1]
	v_pk_fma_f32 v[90:91], v[88:89], s[28:29], v[66:67] op_sel_hi:[1,0,0]
	v_ldexp_f32 v93, v81, 1
	v_add_f32_e32 v81, v40, v78
	v_min_f32_e32 v78, 0, v81
	v_mul_f32_e64 v81, |v81|, s2
	v_exp_f32_e32 v129, v81
	v_ldexp_f32 v84, v86, 1
	v_pk_fma_f32 v[90:91], v[88:89], v[90:91], s[30:31] op_sel_hi:[1,1,0]
	v_ldexp_f32 v85, v87, 1
	v_add_f32_e32 v81, 1.0, v129
	v_pk_mul_f32 v[86:87], v[86:87], v[88:89]
	v_add_f32_e32 v88, -1.0, v81
	v_sub_f32_e32 v89, v88, v81
	v_add_f32_e32 v89, 1.0, v89
	v_sub_f32_e32 v88, v129, v88
	v_add_f32_e32 v92, v88, v89
	v_frexp_mant_f32_e32 v88, v81
	v_cmp_gt_f32_e32 vcc, s26, v88
	v_cvt_f64_f32_e32 v[88:89], v81
	v_frexp_exp_i32_f64_e32 v88, v[88:89]
	v_subbrev_co_u32_e32 v130, vcc, 0, v88, vcc
	v_sub_u32_e32 v89, 0, v130
	v_ldexp_f32 v88, v81, v89
	v_add_f32_e32 v81, v41, v79
	v_min_f32_e32 v79, 0, v81
	v_mul_f32_e64 v81, |v81|, s2
	v_exp_f32_e32 v131, v81
	v_ldexp_f32 v94, v92, v89
	v_pk_mul_f32 v[86:87], v[86:87], v[90:91]
	v_ldexp_f32 v80, v80, 1
	v_add_f32_e32 v81, 1.0, v131
	v_add_f32_e32 v89, -1.0, v81
	v_sub_f32_e32 v92, v89, v81
	v_add_f32_e32 v92, 1.0, v92
	v_sub_f32_e32 v89, v131, v89
	v_add_f32_e32 v92, v89, v92
	v_frexp_mant_f32_e32 v89, v81
	v_cvt_f64_f32_e32 v[98:99], v81
	v_cmp_gt_f32_e32 vcc, s26, v89
	v_frexp_exp_i32_f64_e32 v89, v[98:99]
	v_pk_add_f32 v[90:91], v[84:85], v[86:87]
	v_subbrev_co_u32_e32 v132, vcc, 0, v89, vcc
	v_sub_u32_e32 v95, 0, v132
	v_ldexp_f32 v89, v81, v95
	v_pk_add_f32 v[98:99], v[88:89], 1.0 op_sel_hi:[1,0]
	v_ldexp_f32 v95, v92, v95
	v_pk_add_f32 v[100:101], v[98:99], -1.0 op_sel_hi:[1,0]
	v_pk_add_f32 v[112:113], v[88:89], -1.0 op_sel_hi:[1,0]
	v_pk_add_f32 v[100:101], v[88:89], v[100:101] neg_lo:[0,1] neg_hi:[0,1]
	v_pk_add_f32 v[114:115], v[112:113], 1.0 op_sel_hi:[1,0]
	v_pk_add_f32 v[100:101], v[94:95], v[100:101]
	v_pk_add_f32 v[88:89], v[88:89], v[114:115] neg_lo:[0,1] neg_hi:[0,1]
	v_pk_add_f32 v[102:103], v[98:99], v[100:101]
	v_pk_add_f32 v[88:89], v[94:95], v[88:89]
	v_rcp_f32_e32 v110, v102
	v_rcp_f32_e32 v111, v103
	v_pk_add_f32 v[94:95], v[112:113], v[88:89]
	v_pk_add_f32 v[98:99], v[102:103], v[98:99] neg_lo:[0,1] neg_hi:[0,1]
	v_pk_add_f32 v[112:113], v[94:95], v[112:113] neg_lo:[0,1] neg_hi:[0,1]
	v_pk_add_f32 v[98:99], v[100:101], v[98:99] neg_lo:[0,1] neg_hi:[0,1]
	v_pk_mul_f32 v[100:101], v[94:95], v[110:111]
	v_pk_add_f32 v[88:89], v[88:89], v[112:113] neg_lo:[0,1] neg_hi:[0,1]
	v_pk_mul_f32 v[112:113], v[102:103], v[100:101]
	v_pk_add_f32 v[84:85], v[90:91], v[84:85] neg_lo:[0,1] neg_hi:[0,1]
	v_pk_fma_f32 v[114:115], v[100:101], v[102:103], v[112:113] neg_lo:[0,0,1] neg_hi:[0,0,1]
	v_add_u32_e32 v81, 0xffff8000, v68
	v_pk_fma_f32 v[114:115], v[100:101], v[98:99], v[114:115]
	v_pk_add_f32 v[84:85], v[86:87], v[84:85] neg_lo:[0,1] neg_hi:[0,1]
	v_pk_add_f32 v[116:117], v[112:113], v[114:115]
	v_cndmask_b32_e64 v68, v68, v81, s[60:61]
	v_pk_add_f32 v[118:119], v[94:95], v[116:117] neg_lo:[0,1] neg_hi:[0,1]
	v_pk_add_f32 v[112:113], v[116:117], v[112:113] neg_lo:[0,1] neg_hi:[0,1]
	v_pk_add_f32 v[94:95], v[94:95], v[118:119] neg_lo:[0,1] neg_hi:[0,1]
	v_mov_b32_e32 v87, v85
; __device__ __forceinline__ float logsigf(float x) { return fminf(x, 0.f) - log1pf(__expf(-fabsf(x))); }
; __device__ void phaseA_tile(const Params& p, int l, int mt, int nt, char* smem) {
;     ...
;                     const int c = g4 * 4;
;                     const float4 fb = *(const float4*)(p.b_f + l * 16 + c);
;                     const f32x4 v = acc[i][2];
;                     float4 lf = make_float4(logsigf(v[0] + fb.x), logsigf(v[1] + fb.y), logsigf(v[2] + fb.z), logsigf(v[3] + fb.w));
;                     float* o = samp ? (p.out + O_LFS + ((size_t)l * TSM + (row - TP)) * 16 + c)
;                                     : (p.out + O_LFP + ((size_t)l * TP + row) * 16 + c);
;                     *(float4*)o = lf;
	v_pk_add_f32 v[94:95], v[94:95], v[116:117] neg_lo:[0,1] neg_hi:[0,1]
	v_mov_b32_e32 v124, v90
	v_pk_add_f32 v[88:89], v[88:89], v[94:95]
	v_pk_add_f32 v[94:95], v[112:113], v[114:115] neg_lo:[0,1] neg_hi:[0,1]
	v_cmp_neq_f32_e32 vcc, s8, v83
	v_pk_add_f32 v[88:89], v[94:95], v[88:89]
	s_nop 0
	v_pk_add_f32 v[94:95], v[118:119], v[88:89]
	s_nop 0
	v_pk_mul_f32 v[112:113], v[110:111], v[94:95]
	s_nop 0
	v_pk_mul_f32 v[114:115], v[102:103], v[112:113]
	s_nop 0
	v_pk_fma_f32 v[102:103], v[112:113], v[102:103], v[114:115] neg_lo:[0,0,1] neg_hi:[0,0,1]
	s_nop 0
	v_pk_fma_f32 v[98:99], v[112:113], v[98:99], v[102:103]
	v_pk_add_f32 v[102:103], v[118:119], v[94:95] neg_lo:[0,1] neg_hi:[0,1]
	s_nop 0
	v_pk_add_f32 v[88:89], v[88:89], v[102:103]
	v_pk_add_f32 v[102:103], v[114:115], v[98:99]
	s_nop 0
	v_pk_add_f32 v[116:117], v[94:95], v[102:103] neg_lo:[0,1] neg_hi:[0,1]
	v_pk_add_f32 v[114:115], v[102:103], v[114:115] neg_lo:[0,1] neg_hi:[0,1]
	v_pk_add_f32 v[94:95], v[94:95], v[116:117] neg_lo:[0,1] neg_hi:[0,1]
	s_nop 0
	v_pk_add_f32 v[94:95], v[94:95], v[102:103] neg_lo:[0,1] neg_hi:[0,1]
	s_nop 0
	v_pk_add_f32 v[88:89], v[88:89], v[94:95]
	v_pk_add_f32 v[94:95], v[114:115], v[98:99] neg_lo:[0,1] neg_hi:[0,1]
	s_nop 0
	v_pk_add_f32 v[88:89], v[94:95], v[88:89]
	v_pk_add_f32 v[94:95], v[100:101], v[112:113]
	v_pk_add_f32 v[88:89], v[116:117], v[88:89]
	v_pk_add_f32 v[98:99], v[94:95], v[100:101] neg_lo:[0,1] neg_hi:[0,1]
	v_pk_mul_f32 v[88:89], v[110:111], v[88:89]
	v_pk_add_f32 v[98:99], v[112:113], v[98:99] neg_lo:[0,1] neg_hi:[0,1]
	s_nop 0
	v_pk_add_f32 v[88:89], v[98:99], v[88:89]
	s_nop 0
	v_pk_add_f32 v[98:99], v[94:95], v[88:89]
	s_nop 0
	v_pk_mul_f32 v[100:101], v[98:99], v[98:99]
	v_pk_add_f32 v[94:95], v[98:99], v[94:95] neg_lo:[0,1] neg_hi:[0,1]
	v_pk_fma_f32 v[102:103], v[100:101], s[28:29], v[66:67] op_sel_hi:[1,0,0]
	v_pk_add_f32 v[88:89], v[88:89], v[94:95] neg_lo:[0,1] neg_hi:[0,1]
	v_ldexp_f32 v94, v98, 1
	v_pk_fma_f32 v[102:103], v[100:101], v[102:103], s[30:31] op_sel_hi:[1,1,0]
	v_ldexp_f32 v95, v99, 1
	v_pk_mul_f32 v[98:99], v[98:99], v[100:101]
	v_cvt_f32_i32_e32 v101, v120
	v_cvt_f32_i32_e32 v100, v97
	v_ldexp_f32 v111, v89, 1
	v_ashrrev_i32_e32 v89, 31, v81
	v_mov_b32_e32 v81, v93
	v_pk_mul_f32 v[112:113], v[100:101], s[12:13] op_sel_hi:[1,0]
	v_ldexp_f32 v88, v88, 1
	v_pk_fma_f32 v[114:115], v[100:101], s[12:13], v[112:113] op_sel_hi:[1,0,1] neg_lo:[0,0,1] neg_hi:[0,0,1]
	v_mov_b32_e32 v86, v112
	v_pk_fma_f32 v[100:101], v[100:101], s[14:15], v[114:115] op_sel_hi:[1,0,1]
	v_mov_b32_e32 v121, v113
	v_mov_b32_e32 v92, v100
	v_pk_add_f32 v[86:87], v[86:87], v[92:93]
	v_pk_add_f32 v[92:93], v[80:81], v[84:85]
	v_mov_b32_e32 v85, v91
	v_mov_b32_e32 v81, v93
	v_pk_add_f32 v[114:115], v[112:113], v[100:101]
	v_pk_add_f32 v[80:81], v[80:81], v[84:85]
	v_pk_add_f32 v[84:85], v[90:91], v[92:93]
	v_mov_b32_e32 v125, v115
	v_pk_add_f32 v[116:117], v[114:115], v[84:85]
	v_mov_b32_e32 v122, v84
	v_mov_b32_e32 v123, v117
	v_pk_add_f32 v[122:123], v[122:123], v[124:125] neg_lo:[0,1] neg_hi:[0,1]
	v_mov_b32_e32 v118, v116
	v_mov_b32_e32 v119, v115
	v_mov_b32_e32 v120, v114
	v_mov_b32_e32 v124, v114
	v_mov_b32_e32 v125, v117
	v_mov_b32_e32 v113, v123
	v_pk_add_f32 v[118:119], v[118:119], v[120:121] neg_lo:[0,1] neg_hi:[0,1]
	v_mov_b32_e32 v120, v84
	v_mov_b32_e32 v121, v101
	v_pk_add_f32 v[112:113], v[124:125], v[112:113] neg_lo:[0,1] neg_hi:[0,1]
	v_pk_add_f32 v[120:121], v[120:121], v[118:119] neg_lo:[0,1] neg_hi:[0,1]
	v_mov_b32_e32 v124, v112
	v_mov_b32_e32 v125, v119
	v_mov_b32_e32 v126, v116
	v_mov_b32_e32 v127, v85
	v_mov_b32_e32 v119, v91
	v_pk_add_f32 v[124:125], v[100:101], v[124:125] neg_lo:[0,1] neg_hi:[0,1]
	v_pk_add_f32 v[118:119], v[126:127], v[118:119] neg_lo:[0,1] neg_hi:[0,1]
	v_mov_b32_e32 v101, v115
	v_pk_add_f32 v[84:85], v[84:85], v[90:91] neg_lo:[0,1] neg_hi:[0,1]
	v_pk_add_f32 v[86:87], v[86:87], v[118:119] neg_lo:[0,1] neg_hi:[0,1]
	v_pk_add_f32 v[90:91], v[100:101], v[112:113] neg_lo:[0,1] neg_hi:[0,1]
	v_pk_add_f32 v[80:81], v[80:81], v[122:123] neg_lo:[0,1] neg_hi:[0,1]
	v_pk_add_f32 v[84:85], v[92:93], v[84:85] neg_lo:[0,1] neg_hi:[0,1]
	v_pk_add_f32 v[92:93], v[80:81], v[90:91]
	v_mov_b32_e32 v91, v121
	v_mov_b32_e32 v81, v87
	v_pk_add_f32 v[100:101], v[120:121], v[86:87]
	v_pk_add_f32 v[80:81], v[90:91], v[80:81]
	v_mov_b32_e32 v86, v92
	v_pk_add_f32 v[80:81], v[80:81], v[124:125] neg_lo:[0,1] neg_hi:[0,1]
	v_mov_b32_e32 v87, v101
	v_pk_add_f32 v[86:87], v[86:87], v[80:81] neg_lo:[0,1] neg_hi:[0,1]
	v_pk_add_f32 v[80:81], v[84:85], v[80:81] neg_lo:[0,1] neg_hi:[0,1]
	v_pk_add_f32 v[86:87], v[90:91], v[86:87] neg_lo:[0,1] neg_hi:[0,1]
	v_pk_add_f32 v[84:85], v[100:101], v[92:93]
	v_pk_add_f32 v[80:81], v[80:81], v[86:87]
	v_pk_add_f32 v[86:87], v[116:117], v[84:85]
	v_cndmask_b32_e64 v69, v69, v89, s[60:61]
	v_pk_add_f32 v[90:91], v[86:87], v[116:117] neg_lo:[0,1] neg_hi:[0,1]
	v_mov_b32_e32 v89, v111
	v_pk_add_f32 v[84:85], v[84:85], v[90:91] neg_lo:[0,1] neg_hi:[0,1]
	v_lshlrev_b64 v[68:69], 6, v[68:69]
	v_pk_add_f32 v[80:81], v[80:81], v[84:85]
	v_lshl_add_u64 v[68:69], s[6:7], 0, v[68:69]
	v_pk_add_f32 v[80:81], v[86:87], v[80:81]
	v_pk_mul_f32 v[86:87], v[98:99], v[102:103]
	v_cndmask_b32_e32 v80, v160, v80, vcc
	v_cmp_neq_f32_e32 vcc, s8, v128
	v_pk_add_f32 v[90:91], v[94:95], v[86:87]
	v_lshl_add_u64 v[68:69], v[68:69], 0, v[0:1]
	v_cndmask_b32_e32 v81, v160, v81, vcc
	v_cmp_ngt_f32_e32 vcc, -1.0, v128
	v_pk_add_f32 v[94:95], v[90:91], v[94:95] neg_lo:[0,1] neg_hi:[0,1]
	v_mov_b32_e32 v114, v90
	v_cndmask_b32_e32 v81, v161, v81, vcc
	v_cmp_ngt_f32_e32 vcc, -1.0, v83
; __device__ __forceinline__ float logsigf(float x) { return fminf(x, 0.f) - log1pf(__expf(-fabsf(x))); }
; __device__ void phaseA_tile(const Params& p, int l, int mt, int nt, char* smem) {
;     ...
;             for (int i = 0; i < 4; ++i) {
;                 const int rl = wr * 64 + i * 16 + r;
;                 const int row = m0 + rl;
; #pragma unroll
;                 for (int j = 0; j < 2; ++j) {
;                     const int c = j * 16 + g4 * 4;
;                     const float4 db = *(const float4*)(p.dt_bias + l * 32 + c);
;     ...
;                     const int c = g4 * 4;
;                     const float4 fb = *(const float4*)(p.b_f + l * 16 + c);
;                     const f32x4 v = acc[i][2];
;                     float4 lf = make_float4(logsigf(v[0] + fb.x), logsigf(v[1] + fb.y), logsigf(v[2] + fb.z), logsigf(v[3] + fb.w));
;                     float* o = samp ? (p.out + O_LFS + ((size_t)l * TSM + (row - TP)) * 16 + c)
;                                     : (p.out + O_LFP + ((size_t)l * TP + row) * 16 + c);
;                     *(float4*)o = lf;
;                     *(float4*)(lf_s + rl * 16 + c) = lf;
	v_pk_add_f32 v[86:87], v[86:87], v[94:95] neg_lo:[0,1] neg_hi:[0,1]
	s_nop 0
	v_cndmask_b32_e32 v80, v161, v80, vcc
	v_cmp_neq_f32_e32 vcc, -1.0, v83
	v_pk_add_f32 v[98:99], v[88:89], v[86:87]
	v_mov_b32_e32 v95, v87
	v_cndmask_b32_e32 v80, v162, v80, vcc
	v_cmp_neq_f32_e32 vcc, -1.0, v128
	v_mov_b32_e32 v89, v99
	v_mov_b32_e32 v87, v91
	v_cndmask_b32_e32 v81, v162, v81, vcc
	v_cmp_lt_f32_e64 vcc, |v83|, s9
	v_cndmask_b32_e64 v81, v81, v128, s[0:1]
	v_pk_add_f32 v[86:87], v[88:89], v[86:87]
	v_cndmask_b32_e32 v80, v80, v83, vcc
	v_pk_add_f32 v[76:77], v[76:77], v[80:81] neg_lo:[0,1] neg_hi:[0,1]
	v_cvt_f32_i32_e32 v81, v132
	v_cvt_f32_i32_e32 v80, v130
	v_pk_add_f32 v[88:89], v[90:91], v[98:99]
	v_cmp_neq_f32_e32 vcc, s8, v129
	v_mov_b32_e32 v112, v88
	v_pk_mul_f32 v[84:85], v[80:81], s[12:13] op_sel_hi:[1,0]
	v_mov_b32_e32 v117, v89
	v_pk_fma_f32 v[92:93], v[80:81], s[12:13], v[84:85] op_sel_hi:[1,0,1] neg_lo:[0,0,1] neg_hi:[0,0,1]
	v_mov_b32_e32 v94, v84
	v_pk_fma_f32 v[80:81], v[80:81], s[14:15], v[92:93] op_sel_hi:[1,0,1]
	v_cmp_lt_f32_e64 s[0:1], |v131|, s9
	v_pk_add_f32 v[92:93], v[84:85], v[80:81]
	v_mov_b32_e32 v110, v80
	v_pk_add_f32 v[100:101], v[92:93], v[88:89]
	v_mov_b32_e32 v115, v93
	v_mov_b32_e32 v113, v101
	v_pk_add_f32 v[112:113], v[112:113], v[114:115] neg_lo:[0,1] neg_hi:[0,1]
	v_pk_add_f32 v[94:95], v[94:95], v[110:111]
	v_mov_b32_e32 v102, v100
	v_mov_b32_e32 v103, v93
	v_mov_b32_e32 v110, v92
	v_mov_b32_e32 v111, v85
	v_mov_b32_e32 v114, v92
	v_mov_b32_e32 v115, v101
	v_mov_b32_e32 v85, v113
	v_pk_add_f32 v[102:103], v[102:103], v[110:111] neg_lo:[0,1] neg_hi:[0,1]
	v_mov_b32_e32 v110, v88
	v_mov_b32_e32 v111, v81
	v_pk_add_f32 v[84:85], v[114:115], v[84:85] neg_lo:[0,1] neg_hi:[0,1]
	v_pk_add_f32 v[110:111], v[110:111], v[102:103] neg_lo:[0,1] neg_hi:[0,1]
	v_mov_b32_e32 v114, v84
	v_mov_b32_e32 v115, v103
	v_mov_b32_e32 v116, v100
	v_mov_b32_e32 v103, v91
	v_pk_add_f32 v[114:115], v[80:81], v[114:115] neg_lo:[0,1] neg_hi:[0,1]
	v_pk_add_f32 v[102:103], v[116:117], v[102:103] neg_lo:[0,1] neg_hi:[0,1]
	v_mov_b32_e32 v81, v93
	v_pk_add_f32 v[88:89], v[88:89], v[90:91] neg_lo:[0,1] neg_hi:[0,1]
	v_pk_add_f32 v[90:91], v[94:95], v[102:103] neg_lo:[0,1] neg_hi:[0,1]
	v_pk_add_f32 v[80:81], v[80:81], v[84:85] neg_lo:[0,1] neg_hi:[0,1]
	v_pk_add_f32 v[84:85], v[86:87], v[112:113] neg_lo:[0,1] neg_hi:[0,1]
	v_pk_add_f32 v[92:93], v[110:111], v[90:91]
	v_pk_add_f32 v[86:87], v[84:85], v[80:81]
	v_mov_b32_e32 v81, v111
	v_mov_b32_e32 v85, v91
	v_pk_add_f32 v[84:85], v[80:81], v[84:85]
	v_mov_b32_e32 v90, v86
	v_pk_add_f32 v[84:85], v[84:85], v[114:115] neg_lo:[0,1] neg_hi:[0,1]
	v_mov_b32_e32 v91, v93
	v_pk_add_f32 v[88:89], v[98:99], v[88:89] neg_lo:[0,1] neg_hi:[0,1]
	v_pk_add_f32 v[90:91], v[90:91], v[84:85] neg_lo:[0,1] neg_hi:[0,1]
	v_pk_add_f32 v[84:85], v[88:89], v[84:85] neg_lo:[0,1] neg_hi:[0,1]
	v_pk_add_f32 v[80:81], v[80:81], v[90:91] neg_lo:[0,1] neg_hi:[0,1]
	s_nop 0
	v_pk_add_f32 v[80:81], v[84:85], v[80:81]
	v_pk_add_f32 v[84:85], v[92:93], v[86:87]
	s_nop 0
	v_pk_add_f32 v[86:87], v[100:101], v[84:85]
	s_nop 0
	v_pk_add_f32 v[88:89], v[86:87], v[100:101] neg_lo:[0,1] neg_hi:[0,1]
	s_nop 0
	v_pk_add_f32 v[84:85], v[84:85], v[88:89] neg_lo:[0,1] neg_hi:[0,1]
	s_nop 0
	v_pk_add_f32 v[80:81], v[80:81], v[84:85]
	s_nop 0
	v_pk_add_f32 v[80:81], v[86:87], v[80:81]
	s_nop 0
	v_cndmask_b32_e32 v80, v160, v80, vcc
	v_cmp_neq_f32_e32 vcc, s8, v131
	s_nop 1
	v_cndmask_b32_e32 v81, v160, v81, vcc
	v_cmp_ngt_f32_e32 vcc, -1.0, v131
	s_nop 1
	v_cndmask_b32_e32 v81, v161, v81, vcc
	v_cmp_ngt_f32_e32 vcc, -1.0, v129
	s_nop 1
	v_cndmask_b32_e32 v80, v161, v80, vcc
	v_cmp_neq_f32_e32 vcc, -1.0, v129
	s_nop 1
	v_cndmask_b32_e32 v80, v162, v80, vcc
	v_cmp_neq_f32_e32 vcc, -1.0, v131
	s_nop 1
	v_cndmask_b32_e32 v81, v162, v81, vcc
	v_cmp_lt_f32_e64 vcc, |v129|, s9
	v_cndmask_b32_e64 v81, v81, v131, s[0:1]
	s_nop 0
	v_cndmask_b32_e32 v80, v80, v129, vcc
	v_pk_add_f32 v[78:79], v[78:79], v[80:81] neg_lo:[0,1] neg_hi:[0,1]
	global_store_dwordx4 v[68:69], v[76:79], off
	v_lshl_or_b32 v68, v82, 6, v0
	ds_write_b128 v68, v[76:79]
	global_load_dwordx4 v[78:81], v0, s[74:75]
	v_or_b32_e32 v82, 32, v71
	v_add_u32_e32 v68, s54, v82
	v_ashrrev_i32_e32 v69, 31, v68
	v_lshlrev_b64 v[76:77], 7, v[68:69]
	v_lshl_add_u64 v[76:77], s[10:11], 0, v[76:77]
	v_lshl_add_u64 v[76:77], v[76:77], 0, v[0:1]
	v_or_b32_e32 v71, 48, v71
	s_waitcnt vmcnt(0)
; __device__ __forceinline__ float softplusf(float x) { return fmaxf(x, 0.f) + log1pf(__expf(-fabsf(x))); }
; __device__ void phaseA_tile(const Params& p, int l, int mt, int nt, char* smem) {
;     ...
;                 for (int j = 0; j < 2; ++j) {
;                     const int c = j * 16 + g4 * 4;
;                     const float4 db = *(const float4*)(p.dt_bias + l * 32 + c);
;                     const f32x4 v = acc[i][j];
;                     *(float4*)(p.dtb + (size_t)row * 32 + c) =
;                         make_float4(softplusf(v[0] + db.x), softplusf(v[1] + db.y), softplusf(v[2] + db.z), softplusf(v[3] + db.w));
	v_add_f32_e32 v83, v30, v78
	v_max_f32_e32 v78, 0, v83
	v_mul_f32_e64 v83, |v83|, s2
	v_exp_f32_e32 v83, v83
	s_nop 0
	v_add_f32_e32 v86, 1.0, v83
	v_add_f32_e32 v84, -1.0, v86
	v_sub_f32_e32 v85, v84, v86
	v_add_f32_e32 v85, 1.0, v85
	v_sub_f32_e32 v84, v83, v84
	v_add_f32_e32 v87, v84, v85
	v_frexp_mant_f32_e32 v84, v86
	v_cmp_gt_f32_e32 vcc, s26, v84
	v_cvt_f64_f32_e32 v[84:85], v86
	v_frexp_exp_i32_f64_e32 v84, v[84:85]
	v_subbrev_co_u32_e32 v97, vcc, 0, v84, vcc
	v_sub_u32_e32 v85, 0, v97
	v_ldexp_f32 v84, v86, v85
	v_ldexp_f32 v86, v87, v85
	v_add_f32_e32 v85, v31, v79
	v_max_f32_e32 v79, 0, v85
	v_mul_f32_e64 v85, |v85|, s2
	v_exp_f32_e32 v130, v85
	s_nop 0
	v_add_f32_e32 v85, 1.0, v130
	v_add_f32_e32 v87, -1.0, v85
	v_sub_f32_e32 v88, v87, v85
	v_add_f32_e32 v88, 1.0, v88
	v_sub_f32_e32 v87, v130, v87
	v_add_f32_e32 v87, v87, v88
	v_frexp_mant_f32_e32 v88, v85
	v_cmp_gt_f32_e32 vcc, s26, v88
	v_cvt_f64_f32_e32 v[88:89], v85
	v_frexp_exp_i32_f64_e32 v88, v[88:89]
	v_subbrev_co_u32_e32 v122, vcc, 0, v88, vcc
	v_sub_u32_e32 v88, 0, v122
	v_ldexp_f32 v85, v85, v88
	v_ldexp_f32 v87, v87, v88
	v_pk_add_f32 v[88:89], v[84:85], 1.0 op_sel_hi:[1,0]
	v_pk_add_f32 v[98:99], v[84:85], -1.0 op_sel_hi:[1,0]
	v_pk_add_f32 v[90:91], v[88:89], -1.0 op_sel_hi:[1,0]
	v_pk_add_f32 v[100:101], v[98:99], 1.0 op_sel_hi:[1,0]
	v_pk_add_f32 v[90:91], v[84:85], v[90:91] neg_lo:[0,1] neg_hi:[0,1]
	v_pk_add_f32 v[84:85], v[84:85], v[100:101] neg_lo:[0,1] neg_hi:[0,1]
	v_pk_add_f32 v[90:91], v[86:87], v[90:91]
	v_pk_add_f32 v[84:85], v[86:87], v[84:85]
	v_pk_add_f32 v[92:93], v[88:89], v[90:91]
	v_pk_add_f32 v[86:87], v[98:99], v[84:85]
	v_rcp_f32_e32 v94, v92
	v_rcp_f32_e32 v95, v93
	v_pk_add_f32 v[88:89], v[92:93], v[88:89] neg_lo:[0,1] neg_hi:[0,1]
	v_pk_add_f32 v[98:99], v[86:87], v[98:99] neg_lo:[0,1] neg_hi:[0,1]
	v_pk_add_f32 v[88:89], v[90:91], v[88:89] neg_lo:[0,1] neg_hi:[0,1]
	v_pk_mul_f32 v[90:91], v[86:87], v[94:95]
	v_pk_add_f32 v[84:85], v[84:85], v[98:99] neg_lo:[0,1] neg_hi:[0,1]
	v_pk_mul_f32 v[98:99], v[92:93], v[90:91]
	v_cmp_lt_f32_e64 s[0:1], |v130|, s9
	v_pk_fma_f32 v[100:101], v[90:91], v[92:93], v[98:99] neg_lo:[0,0,1] neg_hi:[0,0,1]
	s_nop 0
	v_pk_fma_f32 v[100:101], v[90:91], v[88:89], v[100:101]
	s_nop 0
	v_pk_add_f32 v[102:103], v[98:99], v[100:101]
	s_nop 0
	v_pk_add_f32 v[110:111], v[86:87], v[102:103] neg_lo:[0,1] neg_hi:[0,1]
	v_pk_add_f32 v[98:99], v[102:103], v[98:99] neg_lo:[0,1] neg_hi:[0,1]
	v_pk_add_f32 v[86:87], v[86:87], v[110:111] neg_lo:[0,1] neg_hi:[0,1]
	s_nop 0
	v_pk_add_f32 v[86:87], v[86:87], v[102:103] neg_lo:[0,1] neg_hi:[0,1]
	s_nop 0
	v_pk_add_f32 v[84:85], v[84:85], v[86:87]
	v_pk_add_f32 v[86:87], v[98:99], v[100:101] neg_lo:[0,1] neg_hi:[0,1]
	s_nop 0
	v_pk_add_f32 v[84:85], v[86:87], v[84:85]
	s_nop 0
	v_pk_add_f32 v[86:87], v[110:111], v[84:85]
	s_nop 0
	v_pk_mul_f32 v[98:99], v[94:95], v[86:87]
	s_nop 0
	v_pk_mul_f32 v[100:101], v[92:93], v[98:99]
	s_nop 0
	v_pk_fma_f32 v[92:93], v[98:99], v[92:93], v[100:101] neg_lo:[0,0,1] neg_hi:[0,0,1]
	s_nop 0
	v_pk_fma_f32 v[88:89], v[98:99], v[88:89], v[92:93]
	v_pk_add_f32 v[92:93], v[110:111], v[86:87] neg_lo:[0,1] neg_hi:[0,1]
	s_nop 0
	v_pk_add_f32 v[84:85], v[84:85], v[92:93]
	v_pk_add_f32 v[92:93], v[100:101], v[88:89]
	s_nop 0
	v_pk_add_f32 v[102:103], v[86:87], v[92:93] neg_lo:[0,1] neg_hi:[0,1]
	v_pk_add_f32 v[100:101], v[92:93], v[100:101] neg_lo:[0,1] neg_hi:[0,1]
	v_pk_add_f32 v[86:87], v[86:87], v[102:103] neg_lo:[0,1] neg_hi:[0,1]
	s_nop 0
	v_pk_add_f32 v[86:87], v[86:87], v[92:93] neg_lo:[0,1] neg_hi:[0,1]
	s_nop 0
	v_pk_add_f32 v[84:85], v[84:85], v[86:87]
	v_pk_add_f32 v[86:87], v[100:101], v[88:89] neg_lo:[0,1] neg_hi:[0,1]
	s_nop 0
	v_pk_add_f32 v[84:85], v[86:87], v[84:85]
	v_pk_add_f32 v[86:87], v[90:91], v[98:99]
	v_pk_add_f32 v[84:85], v[102:103], v[84:85]
	v_pk_add_f32 v[88:89], v[86:87], v[90:91] neg_lo:[0,1] neg_hi:[0,1]
	v_pk_mul_f32 v[84:85], v[94:95], v[84:85]
	v_pk_add_f32 v[88:89], v[98:99], v[88:89] neg_lo:[0,1] neg_hi:[0,1]
	s_nop 0
	v_pk_add_f32 v[84:85], v[88:89], v[84:85]
	s_nop 0
	v_pk_add_f32 v[88:89], v[86:87], v[84:85]
	s_nop 0
	v_pk_add_f32 v[86:87], v[88:89], v[86:87] neg_lo:[0,1] neg_hi:[0,1]
	v_pk_mul_f32 v[90:91], v[88:89], v[88:89]
	v_pk_add_f32 v[84:85], v[84:85], v[86:87] neg_lo:[0,1] neg_hi:[0,1]
	v_pk_fma_f32 v[92:93], v[90:91], s[28:29], v[66:67] op_sel_hi:[1,0,0]
	v_ldexp_f32 v95, v85, 1
	v_add_f32_e32 v85, v32, v80
	v_max_f32_e32 v80, 0, v85
	v_mul_f32_e64 v85, |v85|, s2
	v_exp_f32_e32 v131, v85
	v_ldexp_f32 v86, v88, 1
	v_pk_fma_f32 v[92:93], v[90:91], v[92:93], s[30:31] op_sel_hi:[1,1,0]
	v_ldexp_f32 v87, v89, 1
	v_add_f32_e32 v85, 1.0, v131
	v_pk_mul_f32 v[88:89], v[88:89], v[90:91]
	v_add_f32_e32 v90, -1.0, v85
	v_sub_f32_e32 v91, v90, v85
	v_add_f32_e32 v91, 1.0, v91
	v_sub_f32_e32 v90, v131, v90
	v_add_f32_e32 v94, v90, v91
	v_frexp_mant_f32_e32 v90, v85
	v_cmp_gt_f32_e32 vcc, s26, v90
	v_cvt_f64_f32_e32 v[90:91], v85
	v_frexp_exp_i32_f64_e32 v90, v[90:91]
	v_subbrev_co_u32_e32 v132, vcc, 0, v90, vcc
	v_sub_u32_e32 v91, 0, v132
	v_ldexp_f32 v90, v85, v91
	v_add_f32_e32 v85, v33, v81
	v_max_f32_e32 v81, 0, v85
	v_mul_f32_e64 v85, |v85|, s2
	v_exp_f32_e32 v133, v85
	v_ldexp_f32 v98, v94, v91
	v_pk_mul_f32 v[88:89], v[88:89], v[92:93]
	v_ldexp_f32 v84, v84, 1
	v_add_f32_e32 v85, 1.0, v133
	v_add_f32_e32 v91, -1.0, v85
	v_sub_f32_e32 v94, v91, v85
	v_add_f32_e32 v94, 1.0, v94
	v_sub_f32_e32 v91, v133, v91
	v_add_f32_e32 v94, v91, v94
	v_frexp_mant_f32_e32 v91, v85
	v_cvt_f64_f32_e32 v[100:101], v85
	v_cmp_gt_f32_e32 vcc, s26, v91
	v_frexp_exp_i32_f64_e32 v91, v[100:101]
	v_pk_add_f32 v[92:93], v[86:87], v[88:89]
; __device__ __forceinline__ float softplusf(float x) { return fmaxf(x, 0.f) + log1pf(__expf(-fabsf(x))); }
; __device__ void phaseA_tile(const Params& p, int l, int mt, int nt, char* smem) {
;     ...
;                 for (int j = 0; j < 2; ++j) {
;                     const int c = j * 16 + g4 * 4;
;                     const float4 db = *(const float4*)(p.dt_bias + l * 32 + c);
;                     const f32x4 v = acc[i][j];
;                     *(float4*)(p.dtb + (size_t)row * 32 + c) =
;                         make_float4(softplusf(v[0] + db.x), softplusf(v[1] + db.y), softplusf(v[2] + db.z), softplusf(v[3] + db.w));
	v_subbrev_co_u32_e32 v134, vcc, 0, v91, vcc
	v_sub_u32_e32 v99, 0, v134
	v_ldexp_f32 v91, v85, v99
	v_pk_add_f32 v[100:101], v[90:91], 1.0 op_sel_hi:[1,0]
	v_ldexp_f32 v99, v94, v99
	v_pk_add_f32 v[102:103], v[100:101], -1.0 op_sel_hi:[1,0]
	v_pk_add_f32 v[114:115], v[90:91], -1.0 op_sel_hi:[1,0]
	v_pk_add_f32 v[102:103], v[90:91], v[102:103] neg_lo:[0,1] neg_hi:[0,1]
	v_pk_add_f32 v[116:117], v[114:115], 1.0 op_sel_hi:[1,0]
	v_pk_add_f32 v[102:103], v[98:99], v[102:103]
	v_pk_add_f32 v[90:91], v[90:91], v[116:117] neg_lo:[0,1] neg_hi:[0,1]
	v_pk_add_f32 v[110:111], v[100:101], v[102:103]
	v_pk_add_f32 v[90:91], v[98:99], v[90:91]
	v_rcp_f32_e32 v112, v110
	v_rcp_f32_e32 v113, v111
	v_pk_add_f32 v[98:99], v[114:115], v[90:91]
	v_pk_add_f32 v[100:101], v[110:111], v[100:101] neg_lo:[0,1] neg_hi:[0,1]
	v_pk_add_f32 v[114:115], v[98:99], v[114:115] neg_lo:[0,1] neg_hi:[0,1]
	v_pk_add_f32 v[100:101], v[102:103], v[100:101] neg_lo:[0,1] neg_hi:[0,1]
	v_pk_mul_f32 v[102:103], v[98:99], v[112:113]
	v_pk_add_f32 v[90:91], v[90:91], v[114:115] neg_lo:[0,1] neg_hi:[0,1]
	v_pk_mul_f32 v[114:115], v[110:111], v[102:103]
	v_pk_add_f32 v[86:87], v[92:93], v[86:87] neg_lo:[0,1] neg_hi:[0,1]
	v_pk_fma_f32 v[116:117], v[102:103], v[110:111], v[114:115] neg_lo:[0,0,1] neg_hi:[0,0,1]
	v_pk_add_f32 v[86:87], v[88:89], v[86:87] neg_lo:[0,1] neg_hi:[0,1]
	v_pk_fma_f32 v[116:117], v[102:103], v[100:101], v[116:117]
	v_mov_b32_e32 v89, v87
	v_pk_add_f32 v[118:119], v[114:115], v[116:117]
	v_mov_b32_e32 v85, v95
	v_pk_add_f32 v[120:121], v[98:99], v[118:119] neg_lo:[0,1] neg_hi:[0,1]
	v_pk_add_f32 v[114:115], v[118:119], v[114:115] neg_lo:[0,1] neg_hi:[0,1]
	v_pk_add_f32 v[98:99], v[98:99], v[120:121] neg_lo:[0,1] neg_hi:[0,1]
	v_mov_b32_e32 v126, v92
	v_pk_add_f32 v[98:99], v[98:99], v[118:119] neg_lo:[0,1] neg_hi:[0,1]
	v_cmp_neq_f32_e32 vcc, s8, v83
	v_pk_add_f32 v[90:91], v[90:91], v[98:99]
	v_pk_add_f32 v[98:99], v[114:115], v[116:117] neg_lo:[0,1] neg_hi:[0,1]
	s_nop 0
	v_pk_add_f32 v[90:91], v[98:99], v[90:91]
	s_nop 0
	v_pk_add_f32 v[98:99], v[120:121], v[90:91]
	s_nop 0
	v_pk_mul_f32 v[114:115], v[112:113], v[98:99]
	s_nop 0
	v_pk_mul_f32 v[116:117], v[110:111], v[114:115]
	s_nop 0
	v_pk_fma_f32 v[110:111], v[114:115], v[110:111], v[116:117] neg_lo:[0,0,1] neg_hi:[0,0,1]
	s_nop 0
	v_pk_fma_f32 v[100:101], v[114:115], v[100:101], v[110:111]
	v_pk_add_f32 v[110:111], v[120:121], v[98:99] neg_lo:[0,1] neg_hi:[0,1]
	s_nop 0
	v_pk_add_f32 v[90:91], v[90:91], v[110:111]
	v_pk_add_f32 v[110:111], v[116:117], v[100:101]
	s_nop 0
	v_pk_add_f32 v[118:119], v[98:99], v[110:111] neg_lo:[0,1] neg_hi:[0,1]
	v_pk_add_f32 v[116:117], v[110:111], v[116:117] neg_lo:[0,1] neg_hi:[0,1]
	v_pk_add_f32 v[98:99], v[98:99], v[118:119] neg_lo:[0,1] neg_hi:[0,1]
	s_nop 0
	v_pk_add_f32 v[98:99], v[98:99], v[110:111] neg_lo:[0,1] neg_hi:[0,1]
	s_nop 0
	v_pk_add_f32 v[90:91], v[90:91], v[98:99]
	v_pk_add_f32 v[98:99], v[116:117], v[100:101] neg_lo:[0,1] neg_hi:[0,1]
	s_nop 0
	v_pk_add_f32 v[90:91], v[98:99], v[90:91]
	v_pk_add_f32 v[98:99], v[102:103], v[114:115]
	v_pk_add_f32 v[90:91], v[118:119], v[90:91]
	v_pk_add_f32 v[100:101], v[98:99], v[102:103] neg_lo:[0,1] neg_hi:[0,1]
	v_pk_mul_f32 v[90:91], v[112:113], v[90:91]
	v_pk_add_f32 v[100:101], v[114:115], v[100:101] neg_lo:[0,1] neg_hi:[0,1]
	s_nop 0
	v_pk_add_f32 v[90:91], v[100:101], v[90:91]
	s_nop 0
	v_pk_add_f32 v[100:101], v[98:99], v[90:91]
	s_nop 0
	v_pk_mul_f32 v[102:103], v[100:101], v[100:101]
	v_pk_add_f32 v[98:99], v[100:101], v[98:99] neg_lo:[0,1] neg_hi:[0,1]
	v_pk_fma_f32 v[110:111], v[102:103], s[28:29], v[66:67] op_sel_hi:[1,0,0]
	v_pk_add_f32 v[90:91], v[90:91], v[98:99] neg_lo:[0,1] neg_hi:[0,1]
	v_ldexp_f32 v98, v100, 1
	v_pk_fma_f32 v[110:111], v[102:103], v[110:111], s[30:31] op_sel_hi:[1,1,0]
	v_ldexp_f32 v99, v101, 1
	v_pk_mul_f32 v[100:101], v[100:101], v[102:103]
	v_cvt_f32_i32_e32 v103, v122
	v_cvt_f32_i32_e32 v102, v97
	v_ldexp_f32 v113, v91, 1
	v_ldexp_f32 v90, v90, 1
	v_mov_b32_e32 v91, v113
	v_pk_mul_f32 v[114:115], v[102:103], s[12:13] op_sel_hi:[1,0]
	s_nop 0
	v_pk_fma_f32 v[116:117], v[102:103], s[12:13], v[114:115] op_sel_hi:[1,0,1] neg_lo:[0,0,1] neg_hi:[0,0,1]
	v_mov_b32_e32 v88, v114
	v_pk_fma_f32 v[102:103], v[102:103], s[14:15], v[116:117] op_sel_hi:[1,0,1]
	v_mov_b32_e32 v123, v115
	v_mov_b32_e32 v94, v102
	v_pk_add_f32 v[88:89], v[88:89], v[94:95]
	v_pk_add_f32 v[94:95], v[84:85], v[86:87]
	v_mov_b32_e32 v87, v93
	v_mov_b32_e32 v85, v95
	v_pk_add_f32 v[116:117], v[114:115], v[102:103]
	v_pk_add_f32 v[84:85], v[84:85], v[86:87]
	v_pk_add_f32 v[86:87], v[92:93], v[94:95]
	v_mov_b32_e32 v127, v117
	v_pk_add_f32 v[118:119], v[116:117], v[86:87]
	v_mov_b32_e32 v124, v86
	v_mov_b32_e32 v125, v119
	v_pk_add_f32 v[124:125], v[124:125], v[126:127] neg_lo:[0,1] neg_hi:[0,1]
	v_mov_b32_e32 v120, v118
	v_mov_b32_e32 v121, v117
	v_mov_b32_e32 v122, v116
	v_mov_b32_e32 v126, v116
	v_mov_b32_e32 v127, v119
	v_mov_b32_e32 v115, v125
	v_pk_add_f32 v[120:121], v[120:121], v[122:123] neg_lo:[0,1] neg_hi:[0,1]
	v_mov_b32_e32 v122, v86
	v_mov_b32_e32 v123, v103
	v_pk_add_f32 v[114:115], v[126:127], v[114:115] neg_lo:[0,1] neg_hi:[0,1]
	v_pk_add_f32 v[122:123], v[122:123], v[120:121] neg_lo:[0,1] neg_hi:[0,1]
	v_mov_b32_e32 v126, v114
	v_mov_b32_e32 v127, v121
	v_mov_b32_e32 v128, v118
	v_mov_b32_e32 v129, v87
	v_mov_b32_e32 v121, v93
	v_pk_add_f32 v[126:127], v[102:103], v[126:127] neg_lo:[0,1] neg_hi:[0,1]
	v_pk_add_f32 v[120:121], v[128:129], v[120:121] neg_lo:[0,1] neg_hi:[0,1]
	v_mov_b32_e32 v103, v117
	v_pk_add_f32 v[86:87], v[86:87], v[92:93] neg_lo:[0,1] neg_hi:[0,1]
; __device__ __forceinline__ float softplusf(float x) { return fmaxf(x, 0.f) + log1pf(__expf(-fabsf(x))); }
; __device__ void phaseA_tile(const Params& p, int l, int mt, int nt, char* smem) {
;     ...
;                 for (int j = 0; j < 2; ++j) {
;                     const int c = j * 16 + g4 * 4;
;                     const float4 db = *(const float4*)(p.dt_bias + l * 32 + c);
;                     const f32x4 v = acc[i][j];
;                     *(float4*)(p.dtb + (size_t)row * 32 + c) =
;                         make_float4(softplusf(v[0] + db.x), softplusf(v[1] + db.y), softplusf(v[2] + db.z), softplusf(v[3] + db.w));
	v_pk_add_f32 v[88:89], v[88:89], v[120:121] neg_lo:[0,1] neg_hi:[0,1]
	v_pk_add_f32 v[92:93], v[102:103], v[114:115] neg_lo:[0,1] neg_hi:[0,1]
	v_pk_add_f32 v[84:85], v[84:85], v[124:125] neg_lo:[0,1] neg_hi:[0,1]
	v_pk_add_f32 v[86:87], v[94:95], v[86:87] neg_lo:[0,1] neg_hi:[0,1]
	v_pk_add_f32 v[94:95], v[84:85], v[92:93]
	v_mov_b32_e32 v93, v123
	v_mov_b32_e32 v85, v89
	v_pk_add_f32 v[102:103], v[122:123], v[88:89]
	v_pk_add_f32 v[84:85], v[92:93], v[84:85]
	v_mov_b32_e32 v88, v94
	v_pk_add_f32 v[84:85], v[84:85], v[126:127] neg_lo:[0,1] neg_hi:[0,1]
	v_mov_b32_e32 v89, v103
	v_pk_add_f32 v[88:89], v[88:89], v[84:85] neg_lo:[0,1] neg_hi:[0,1]
	v_pk_add_f32 v[84:85], v[86:87], v[84:85] neg_lo:[0,1] neg_hi:[0,1]
	v_pk_add_f32 v[88:89], v[92:93], v[88:89] neg_lo:[0,1] neg_hi:[0,1]
	v_pk_add_f32 v[86:87], v[102:103], v[94:95]
	v_pk_add_f32 v[84:85], v[84:85], v[88:89]
	v_pk_add_f32 v[88:89], v[118:119], v[86:87]
	s_nop 0
	v_pk_add_f32 v[92:93], v[88:89], v[118:119] neg_lo:[0,1] neg_hi:[0,1]
	s_nop 0
	v_pk_add_f32 v[86:87], v[86:87], v[92:93] neg_lo:[0,1] neg_hi:[0,1]
	s_nop 0
	v_pk_add_f32 v[84:85], v[84:85], v[86:87]
	s_nop 0
	v_pk_add_f32 v[84:85], v[88:89], v[84:85]
	v_pk_mul_f32 v[88:89], v[100:101], v[110:111]
	v_cndmask_b32_e32 v84, v160, v84, vcc
	v_cmp_neq_f32_e32 vcc, s8, v130
	v_pk_add_f32 v[92:93], v[98:99], v[88:89]
	s_nop 0
	v_cndmask_b32_e32 v85, v160, v85, vcc
	v_cmp_ngt_f32_e32 vcc, -1.0, v130
	v_pk_add_f32 v[98:99], v[92:93], v[98:99] neg_lo:[0,1] neg_hi:[0,1]
	v_mov_b32_e32 v116, v92
	v_cndmask_b32_e32 v85, v161, v85, vcc
	v_cmp_ngt_f32_e32 vcc, -1.0, v83
	v_pk_add_f32 v[88:89], v[88:89], v[98:99] neg_lo:[0,1] neg_hi:[0,1]
	s_nop 0
	v_cndmask_b32_e32 v84, v161, v84, vcc
	v_cmp_neq_f32_e32 vcc, -1.0, v83
	v_pk_add_f32 v[100:101], v[90:91], v[88:89]
	v_mov_b32_e32 v99, v89
	v_cndmask_b32_e32 v84, v162, v84, vcc
	v_cmp_neq_f32_e32 vcc, -1.0, v130
	v_mov_b32_e32 v91, v101
	v_mov_b32_e32 v89, v93
	v_cndmask_b32_e32 v85, v162, v85, vcc
	v_cmp_lt_f32_e64 vcc, |v83|, s9
	v_cndmask_b32_e64 v85, v85, v130, s[0:1]
	v_pk_add_f32 v[88:89], v[90:91], v[88:89]
	v_cndmask_b32_e32 v84, v84, v83, vcc
	v_pk_add_f32 v[78:79], v[78:79], v[84:85]
	v_cvt_f32_i32_e32 v85, v134
	v_cvt_f32_i32_e32 v84, v132
	v_pk_add_f32 v[90:91], v[92:93], v[100:101]
	v_cmp_neq_f32_e32 vcc, s8, v131
	v_mov_b32_e32 v114, v90
	v_pk_mul_f32 v[86:87], v[84:85], s[12:13] op_sel_hi:[1,0]
	v_mov_b32_e32 v119, v91
	v_pk_fma_f32 v[94:95], v[84:85], s[12:13], v[86:87] op_sel_hi:[1,0,1] neg_lo:[0,0,1] neg_hi:[0,0,1]
	v_mov_b32_e32 v98, v86
	v_pk_fma_f32 v[84:85], v[84:85], s[14:15], v[94:95] op_sel_hi:[1,0,1]
	v_cmp_lt_f32_e64 s[0:1], |v133|, s9
	v_pk_add_f32 v[94:95], v[86:87], v[84:85]
	v_mov_b32_e32 v112, v84
	v_pk_add_f32 v[102:103], v[94:95], v[90:91]
	v_mov_b32_e32 v117, v95
	v_mov_b32_e32 v115, v103
	v_pk_add_f32 v[114:115], v[114:115], v[116:117] neg_lo:[0,1] neg_hi:[0,1]
	v_pk_add_f32 v[98:99], v[98:99], v[112:113]
	v_mov_b32_e32 v110, v102
	v_mov_b32_e32 v111, v95
	v_mov_b32_e32 v112, v94
	v_mov_b32_e32 v113, v87
	v_mov_b32_e32 v116, v94
	v_mov_b32_e32 v117, v103
	v_mov_b32_e32 v87, v115
	v_pk_add_f32 v[110:111], v[110:111], v[112:113] neg_lo:[0,1] neg_hi:[0,1]
	v_mov_b32_e32 v112, v90
	v_mov_b32_e32 v113, v85
	v_pk_add_f32 v[86:87], v[116:117], v[86:87] neg_lo:[0,1] neg_hi:[0,1]
	v_pk_add_f32 v[112:113], v[112:113], v[110:111] neg_lo:[0,1] neg_hi:[0,1]
	v_mov_b32_e32 v116, v86
	v_mov_b32_e32 v117, v111
	v_mov_b32_e32 v118, v102
	v_mov_b32_e32 v111, v93
	v_pk_add_f32 v[116:117], v[84:85], v[116:117] neg_lo:[0,1] neg_hi:[0,1]
	v_pk_add_f32 v[110:111], v[118:119], v[110:111] neg_lo:[0,1] neg_hi:[0,1]
	v_mov_b32_e32 v85, v95
	v_pk_add_f32 v[90:91], v[90:91], v[92:93] neg_lo:[0,1] neg_hi:[0,1]
	v_pk_add_f32 v[92:93], v[98:99], v[110:111] neg_lo:[0,1] neg_hi:[0,1]
	v_pk_add_f32 v[84:85], v[84:85], v[86:87] neg_lo:[0,1] neg_hi:[0,1]
	v_pk_add_f32 v[86:87], v[88:89], v[114:115] neg_lo:[0,1] neg_hi:[0,1]
	v_pk_add_f32 v[94:95], v[112:113], v[92:93]
	v_pk_add_f32 v[88:89], v[86:87], v[84:85]
	v_mov_b32_e32 v85, v113
	v_mov_b32_e32 v87, v93
	v_pk_add_f32 v[86:87], v[84:85], v[86:87]
	v_mov_b32_e32 v92, v88
	v_pk_add_f32 v[86:87], v[86:87], v[116:117] neg_lo:[0,1] neg_hi:[0,1]
	v_mov_b32_e32 v93, v95
	v_pk_add_f32 v[90:91], v[100:101], v[90:91] neg_lo:[0,1] neg_hi:[0,1]
	v_pk_add_f32 v[92:93], v[92:93], v[86:87] neg_lo:[0,1] neg_hi:[0,1]
	v_pk_add_f32 v[86:87], v[90:91], v[86:87] neg_lo:[0,1] neg_hi:[0,1]
	v_pk_add_f32 v[84:85], v[84:85], v[92:93] neg_lo:[0,1] neg_hi:[0,1]
	s_nop 0
	v_pk_add_f32 v[84:85], v[86:87], v[84:85]
	v_pk_add_f32 v[86:87], v[94:95], v[88:89]
	s_nop 0
	v_pk_add_f32 v[88:89], v[102:103], v[86:87]
	s_nop 0
	v_pk_add_f32 v[90:91], v[88:89], v[102:103] neg_lo:[0,1] neg_hi:[0,1]
	s_nop 0
	v_pk_add_f32 v[86:87], v[86:87], v[90:91] neg_lo:[0,1] neg_hi:[0,1]
	s_nop 0
	v_pk_add_f32 v[84:85], v[84:85], v[86:87]
	s_nop 0
	v_pk_add_f32 v[84:85], v[88:89], v[84:85]
	s_nop 0
	v_cndmask_b32_e32 v83, v160, v84, vcc
	v_cmp_neq_f32_e32 vcc, s8, v133
	s_nop 1
	v_cndmask_b32_e32 v84, v160, v85, vcc
	v_cmp_ngt_f32_e32 vcc, -1.0, v133
	s_nop 1
	v_cndmask_b32_e32 v84, v161, v84, vcc
	v_cmp_ngt_f32_e32 vcc, -1.0, v131
	s_nop 1
	v_cndmask_b32_e32 v83, v161, v83, vcc
	v_cmp_neq_f32_e32 vcc, -1.0, v131
	s_nop 1
	v_cndmask_b32_e32 v83, v162, v83, vcc
	v_cmp_neq_f32_e32 vcc, -1.0, v133
	s_nop 1
	v_cndmask_b32_e32 v84, v162, v84, vcc
	v_cmp_lt_f32_e64 vcc, |v131|, s9
	v_cndmask_b32_e64 v85, v84, v133, s[0:1]
	s_nop 0
	v_cndmask_b32_e32 v84, v83, v131, vcc
	v_pk_add_f32 v[80:81], v[80:81], v[84:85]
	global_store_dwordx4 v[76:77], v[78:81], off
	global_load_dwordx4 v[78:81], v0, s[74:75] offset:64
	s_waitcnt vmcnt(0)
; __device__ __forceinline__ float softplusf(float x) { return fmaxf(x, 0.f) + log1pf(__expf(-fabsf(x))); }
; __device__ void phaseA_tile(const Params& p, int l, int mt, int nt, char* smem) {
;     ...
;                 for (int j = 0; j < 2; ++j) {
;                     const int c = j * 16 + g4 * 4;
;                     const float4 db = *(const float4*)(p.dt_bias + l * 32 + c);
;                     const f32x4 v = acc[i][j];
;                     *(float4*)(p.dtb + (size_t)row * 32 + c) =
;                         make_float4(softplusf(v[0] + db.x), softplusf(v[1] + db.y), softplusf(v[2] + db.z), softplusf(v[3] + db.w));
	v_add_f32_e32 v83, v26, v78
	v_max_f32_e32 v78, 0, v83
	v_mul_f32_e64 v83, |v83|, s2
	v_exp_f32_e32 v83, v83
	s_nop 0
	v_add_f32_e32 v86, 1.0, v83
	v_add_f32_e32 v84, -1.0, v86
	v_sub_f32_e32 v85, v84, v86
	v_add_f32_e32 v85, 1.0, v85
	v_sub_f32_e32 v84, v83, v84
	v_add_f32_e32 v87, v84, v85
	v_frexp_mant_f32_e32 v84, v86
	v_cmp_gt_f32_e32 vcc, s26, v84
	v_cvt_f64_f32_e32 v[84:85], v86
	v_frexp_exp_i32_f64_e32 v84, v[84:85]
	v_subbrev_co_u32_e32 v97, vcc, 0, v84, vcc
	v_sub_u32_e32 v85, 0, v97
	v_ldexp_f32 v84, v86, v85
	v_ldexp_f32 v86, v87, v85
	v_add_f32_e32 v85, v27, v79
	v_max_f32_e32 v79, 0, v85
	v_mul_f32_e64 v85, |v85|, s2
	v_exp_f32_e32 v130, v85
	s_nop 0
	v_add_f32_e32 v85, 1.0, v130
	v_add_f32_e32 v87, -1.0, v85
	v_sub_f32_e32 v88, v87, v85
	v_add_f32_e32 v88, 1.0, v88
	v_sub_f32_e32 v87, v130, v87
	v_add_f32_e32 v87, v87, v88
	v_frexp_mant_f32_e32 v88, v85
	v_cmp_gt_f32_e32 vcc, s26, v88
	v_cvt_f64_f32_e32 v[88:89], v85
	v_frexp_exp_i32_f64_e32 v88, v[88:89]
	v_subbrev_co_u32_e32 v122, vcc, 0, v88, vcc
	v_sub_u32_e32 v88, 0, v122
	v_ldexp_f32 v85, v85, v88
	v_ldexp_f32 v87, v87, v88
	v_pk_add_f32 v[88:89], v[84:85], 1.0 op_sel_hi:[1,0]
	v_pk_add_f32 v[98:99], v[84:85], -1.0 op_sel_hi:[1,0]
	v_pk_add_f32 v[90:91], v[88:89], -1.0 op_sel_hi:[1,0]
	v_pk_add_f32 v[100:101], v[98:99], 1.0 op_sel_hi:[1,0]
	v_pk_add_f32 v[90:91], v[84:85], v[90:91] neg_lo:[0,1] neg_hi:[0,1]
	v_pk_add_f32 v[84:85], v[84:85], v[100:101] neg_lo:[0,1] neg_hi:[0,1]
	v_pk_add_f32 v[90:91], v[86:87], v[90:91]
	v_pk_add_f32 v[84:85], v[86:87], v[84:85]
	v_pk_add_f32 v[92:93], v[88:89], v[90:91]
	v_pk_add_f32 v[86:87], v[98:99], v[84:85]
	v_rcp_f32_e32 v94, v92
	v_rcp_f32_e32 v95, v93
	v_pk_add_f32 v[88:89], v[92:93], v[88:89] neg_lo:[0,1] neg_hi:[0,1]
	v_pk_add_f32 v[98:99], v[86:87], v[98:99] neg_lo:[0,1] neg_hi:[0,1]
	v_pk_add_f32 v[88:89], v[90:91], v[88:89] neg_lo:[0,1] neg_hi:[0,1]
	v_pk_mul_f32 v[90:91], v[86:87], v[94:95]
	v_pk_add_f32 v[84:85], v[84:85], v[98:99] neg_lo:[0,1] neg_hi:[0,1]
	v_pk_mul_f32 v[98:99], v[92:93], v[90:91]
	v_cmp_lt_f32_e64 s[0:1], |v130|, s9
	v_pk_fma_f32 v[100:101], v[90:91], v[92:93], v[98:99] neg_lo:[0,0,1] neg_hi:[0,0,1]
	s_nop 0
	v_pk_fma_f32 v[100:101], v[90:91], v[88:89], v[100:101]
	s_nop 0
	v_pk_add_f32 v[102:103], v[98:99], v[100:101]
	s_nop 0
	v_pk_add_f32 v[110:111], v[86:87], v[102:103] neg_lo:[0,1] neg_hi:[0,1]
	v_pk_add_f32 v[98:99], v[102:103], v[98:99] neg_lo:[0,1] neg_hi:[0,1]
	v_pk_add_f32 v[86:87], v[86:87], v[110:111] neg_lo:[0,1] neg_hi:[0,1]
	s_nop 0
	v_pk_add_f32 v[86:87], v[86:87], v[102:103] neg_lo:[0,1] neg_hi:[0,1]
	s_nop 0
	v_pk_add_f32 v[84:85], v[84:85], v[86:87]
	v_pk_add_f32 v[86:87], v[98:99], v[100:101] neg_lo:[0,1] neg_hi:[0,1]
	s_nop 0
	v_pk_add_f32 v[84:85], v[86:87], v[84:85]
	s_nop 0
	v_pk_add_f32 v[86:87], v[110:111], v[84:85]
	s_nop 0
	v_pk_mul_f32 v[98:99], v[94:95], v[86:87]
	s_nop 0
	v_pk_mul_f32 v[100:101], v[92:93], v[98:99]
	s_nop 0
	v_pk_fma_f32 v[92:93], v[98:99], v[92:93], v[100:101] neg_lo:[0,0,1] neg_hi:[0,0,1]
	s_nop 0
	v_pk_fma_f32 v[88:89], v[98:99], v[88:89], v[92:93]
	v_pk_add_f32 v[92:93], v[110:111], v[86:87] neg_lo:[0,1] neg_hi:[0,1]
	s_nop 0
	v_pk_add_f32 v[84:85], v[84:85], v[92:93]
	v_pk_add_f32 v[92:93], v[100:101], v[88:89]
	s_nop 0
	v_pk_add_f32 v[102:103], v[86:87], v[92:93] neg_lo:[0,1] neg_hi:[0,1]
	v_pk_add_f32 v[100:101], v[92:93], v[100:101] neg_lo:[0,1] neg_hi:[0,1]
	v_pk_add_f32 v[86:87], v[86:87], v[102:103] neg_lo:[0,1] neg_hi:[0,1]
	s_nop 0
	v_pk_add_f32 v[86:87], v[86:87], v[92:93] neg_lo:[0,1] neg_hi:[0,1]
	s_nop 0
	v_pk_add_f32 v[84:85], v[84:85], v[86:87]
	v_pk_add_f32 v[86:87], v[100:101], v[88:89] neg_lo:[0,1] neg_hi:[0,1]
	s_nop 0
	v_pk_add_f32 v[84:85], v[86:87], v[84:85]
	v_pk_add_f32 v[86:87], v[90:91], v[98:99]
	v_pk_add_f32 v[84:85], v[102:103], v[84:85]
	v_pk_add_f32 v[88:89], v[86:87], v[90:91] neg_lo:[0,1] neg_hi:[0,1]
	v_pk_mul_f32 v[84:85], v[94:95], v[84:85]
	v_pk_add_f32 v[88:89], v[98:99], v[88:89] neg_lo:[0,1] neg_hi:[0,1]
	s_nop 0
	v_pk_add_f32 v[84:85], v[88:89], v[84:85]
	s_nop 0
	v_pk_add_f32 v[88:89], v[86:87], v[84:85]
	s_nop 0
	v_pk_add_f32 v[86:87], v[88:89], v[86:87] neg_lo:[0,1] neg_hi:[0,1]
	v_pk_mul_f32 v[90:91], v[88:89], v[88:89]
	v_pk_add_f32 v[84:85], v[84:85], v[86:87] neg_lo:[0,1] neg_hi:[0,1]
	v_pk_fma_f32 v[92:93], v[90:91], s[28:29], v[66:67] op_sel_hi:[1,0,0]
	v_ldexp_f32 v95, v85, 1
	v_add_f32_e32 v85, v28, v80
	v_max_f32_e32 v80, 0, v85
	v_mul_f32_e64 v85, |v85|, s2
	v_exp_f32_e32 v131, v85
	v_ldexp_f32 v86, v88, 1
	v_pk_fma_f32 v[92:93], v[90:91], v[92:93], s[30:31] op_sel_hi:[1,1,0]
	v_ldexp_f32 v87, v89, 1
	v_add_f32_e32 v85, 1.0, v131
	v_pk_mul_f32 v[88:89], v[88:89], v[90:91]
	v_add_f32_e32 v90, -1.0, v85
	v_sub_f32_e32 v91, v90, v85
	v_add_f32_e32 v91, 1.0, v91
	v_sub_f32_e32 v90, v131, v90
	v_add_f32_e32 v94, v90, v91
	v_frexp_mant_f32_e32 v90, v85
	v_cmp_gt_f32_e32 vcc, s26, v90
	v_cvt_f64_f32_e32 v[90:91], v85
	v_frexp_exp_i32_f64_e32 v90, v[90:91]
	v_subbrev_co_u32_e32 v132, vcc, 0, v90, vcc
	v_sub_u32_e32 v91, 0, v132
	v_ldexp_f32 v90, v85, v91
	v_add_f32_e32 v85, v29, v81
	v_max_f32_e32 v81, 0, v85
	v_mul_f32_e64 v85, |v85|, s2
	v_exp_f32_e32 v133, v85
	v_ldexp_f32 v98, v94, v91
	v_pk_mul_f32 v[88:89], v[88:89], v[92:93]
	v_ldexp_f32 v84, v84, 1
	v_add_f32_e32 v85, 1.0, v133
	v_add_f32_e32 v91, -1.0, v85
	v_sub_f32_e32 v94, v91, v85
	v_add_f32_e32 v94, 1.0, v94
	v_sub_f32_e32 v91, v133, v91
	v_add_f32_e32 v94, v91, v94
	v_frexp_mant_f32_e32 v91, v85
	v_cvt_f64_f32_e32 v[100:101], v85
	v_cmp_gt_f32_e32 vcc, s26, v91
	v_frexp_exp_i32_f64_e32 v91, v[100:101]
	v_pk_add_f32 v[92:93], v[86:87], v[88:89]
; __device__ __forceinline__ float softplusf(float x) { return fmaxf(x, 0.f) + log1pf(__expf(-fabsf(x))); }
; __device__ void phaseA_tile(const Params& p, int l, int mt, int nt, char* smem) {
;     ...
;                 for (int j = 0; j < 2; ++j) {
;                     const int c = j * 16 + g4 * 4;
;                     const float4 db = *(const float4*)(p.dt_bias + l * 32 + c);
;                     const f32x4 v = acc[i][j];
;                     *(float4*)(p.dtb + (size_t)row * 32 + c) =
;                         make_float4(softplusf(v[0] + db.x), softplusf(v[1] + db.y), softplusf(v[2] + db.z), softplusf(v[3] + db.w));
	v_subbrev_co_u32_e32 v134, vcc, 0, v91, vcc
	v_sub_u32_e32 v99, 0, v134
	v_ldexp_f32 v91, v85, v99
	v_pk_add_f32 v[100:101], v[90:91], 1.0 op_sel_hi:[1,0]
	v_ldexp_f32 v99, v94, v99
	v_pk_add_f32 v[102:103], v[100:101], -1.0 op_sel_hi:[1,0]
	v_pk_add_f32 v[114:115], v[90:91], -1.0 op_sel_hi:[1,0]
	v_pk_add_f32 v[102:103], v[90:91], v[102:103] neg_lo:[0,1] neg_hi:[0,1]
	v_pk_add_f32 v[116:117], v[114:115], 1.0 op_sel_hi:[1,0]
	v_pk_add_f32 v[102:103], v[98:99], v[102:103]
	v_pk_add_f32 v[90:91], v[90:91], v[116:117] neg_lo:[0,1] neg_hi:[0,1]
	v_pk_add_f32 v[110:111], v[100:101], v[102:103]
	v_pk_add_f32 v[90:91], v[98:99], v[90:91]
	v_rcp_f32_e32 v112, v110
	v_rcp_f32_e32 v113, v111
	v_pk_add_f32 v[98:99], v[114:115], v[90:91]
	v_pk_add_f32 v[100:101], v[110:111], v[100:101] neg_lo:[0,1] neg_hi:[0,1]
	v_pk_add_f32 v[114:115], v[98:99], v[114:115] neg_lo:[0,1] neg_hi:[0,1]
	v_pk_add_f32 v[100:101], v[102:103], v[100:101] neg_lo:[0,1] neg_hi:[0,1]
	v_pk_mul_f32 v[102:103], v[98:99], v[112:113]
	v_pk_add_f32 v[90:91], v[90:91], v[114:115] neg_lo:[0,1] neg_hi:[0,1]
	v_pk_mul_f32 v[114:115], v[110:111], v[102:103]
	v_pk_add_f32 v[86:87], v[92:93], v[86:87] neg_lo:[0,1] neg_hi:[0,1]
	v_pk_fma_f32 v[116:117], v[102:103], v[110:111], v[114:115] neg_lo:[0,0,1] neg_hi:[0,0,1]
	v_pk_add_f32 v[86:87], v[88:89], v[86:87] neg_lo:[0,1] neg_hi:[0,1]
	v_pk_fma_f32 v[116:117], v[102:103], v[100:101], v[116:117]
	v_mov_b32_e32 v89, v87
	v_pk_add_f32 v[118:119], v[114:115], v[116:117]
	v_mov_b32_e32 v85, v95
	v_pk_add_f32 v[120:121], v[98:99], v[118:119] neg_lo:[0,1] neg_hi:[0,1]
	v_pk_add_f32 v[114:115], v[118:119], v[114:115] neg_lo:[0,1] neg_hi:[0,1]
	v_pk_add_f32 v[98:99], v[98:99], v[120:121] neg_lo:[0,1] neg_hi:[0,1]
	v_mov_b32_e32 v126, v92
	v_pk_add_f32 v[98:99], v[98:99], v[118:119] neg_lo:[0,1] neg_hi:[0,1]
	v_cmp_neq_f32_e32 vcc, s8, v83
	v_pk_add_f32 v[90:91], v[90:91], v[98:99]
	v_pk_add_f32 v[98:99], v[114:115], v[116:117] neg_lo:[0,1] neg_hi:[0,1]
	s_nop 0
	v_pk_add_f32 v[90:91], v[98:99], v[90:91]
	s_nop 0
	v_pk_add_f32 v[98:99], v[120:121], v[90:91]
	s_nop 0
	v_pk_mul_f32 v[114:115], v[112:113], v[98:99]
	s_nop 0
	v_pk_mul_f32 v[116:117], v[110:111], v[114:115]
	s_nop 0
	v_pk_fma_f32 v[110:111], v[114:115], v[110:111], v[116:117] neg_lo:[0,0,1] neg_hi:[0,0,1]
	s_nop 0
	v_pk_fma_f32 v[100:101], v[114:115], v[100:101], v[110:111]
	v_pk_add_f32 v[110:111], v[120:121], v[98:99] neg_lo:[0,1] neg_hi:[0,1]
	s_nop 0
	v_pk_add_f32 v[90:91], v[90:91], v[110:111]
	v_pk_add_f32 v[110:111], v[116:117], v[100:101]
	s_nop 0
	v_pk_add_f32 v[118:119], v[98:99], v[110:111] neg_lo:[0,1] neg_hi:[0,1]
	v_pk_add_f32 v[116:117], v[110:111], v[116:117] neg_lo:[0,1] neg_hi:[0,1]
	v_pk_add_f32 v[98:99], v[98:99], v[118:119] neg_lo:[0,1] neg_hi:[0,1]
	s_nop 0
	v_pk_add_f32 v[98:99], v[98:99], v[110:111] neg_lo:[0,1] neg_hi:[0,1]
	s_nop 0
	v_pk_add_f32 v[90:91], v[90:91], v[98:99]
	v_pk_add_f32 v[98:99], v[116:117], v[100:101] neg_lo:[0,1] neg_hi:[0,1]
	s_nop 0
	v_pk_add_f32 v[90:91], v[98:99], v[90:91]
	v_pk_add_f32 v[98:99], v[102:103], v[114:115]
	v_pk_add_f32 v[90:91], v[118:119], v[90:91]
	v_pk_add_f32 v[100:101], v[98:99], v[102:103] neg_lo:[0,1] neg_hi:[0,1]
	v_pk_mul_f32 v[90:91], v[112:113], v[90:91]
	v_pk_add_f32 v[100:101], v[114:115], v[100:101] neg_lo:[0,1] neg_hi:[0,1]
	s_nop 0
	v_pk_add_f32 v[90:91], v[100:101], v[90:91]
	s_nop 0
	v_pk_add_f32 v[100:101], v[98:99], v[90:91]
	s_nop 0
	v_pk_mul_f32 v[102:103], v[100:101], v[100:101]
	v_pk_add_f32 v[98:99], v[100:101], v[98:99] neg_lo:[0,1] neg_hi:[0,1]
	v_pk_fma_f32 v[110:111], v[102:103], s[28:29], v[66:67] op_sel_hi:[1,0,0]
	v_pk_add_f32 v[90:91], v[90:91], v[98:99] neg_lo:[0,1] neg_hi:[0,1]
	v_ldexp_f32 v98, v100, 1
	v_pk_fma_f32 v[110:111], v[102:103], v[110:111], s[30:31] op_sel_hi:[1,1,0]
	v_ldexp_f32 v99, v101, 1
	v_pk_mul_f32 v[100:101], v[100:101], v[102:103]
	v_cvt_f32_i32_e32 v103, v122
	v_cvt_f32_i32_e32 v102, v97
	v_ldexp_f32 v113, v91, 1
	v_ldexp_f32 v90, v90, 1
	v_mov_b32_e32 v91, v113
	v_pk_mul_f32 v[114:115], v[102:103], s[12:13] op_sel_hi:[1,0]
	s_nop 0
	v_pk_fma_f32 v[116:117], v[102:103], s[12:13], v[114:115] op_sel_hi:[1,0,1] neg_lo:[0,0,1] neg_hi:[0,0,1]
	v_mov_b32_e32 v88, v114
	v_pk_fma_f32 v[102:103], v[102:103], s[14:15], v[116:117] op_sel_hi:[1,0,1]
	v_mov_b32_e32 v123, v115
	v_mov_b32_e32 v94, v102
	v_pk_add_f32 v[88:89], v[88:89], v[94:95]
	v_pk_add_f32 v[94:95], v[84:85], v[86:87]
	v_mov_b32_e32 v87, v93
	v_mov_b32_e32 v85, v95
	v_pk_add_f32 v[116:117], v[114:115], v[102:103]
	v_pk_add_f32 v[84:85], v[84:85], v[86:87]
	v_pk_add_f32 v[86:87], v[92:93], v[94:95]
	v_mov_b32_e32 v127, v117
	v_pk_add_f32 v[118:119], v[116:117], v[86:87]
	v_mov_b32_e32 v124, v86
	v_mov_b32_e32 v125, v119
	v_pk_add_f32 v[124:125], v[124:125], v[126:127] neg_lo:[0,1] neg_hi:[0,1]
	v_mov_b32_e32 v120, v118
	v_mov_b32_e32 v121, v117
	v_mov_b32_e32 v122, v116
	v_mov_b32_e32 v126, v116
	v_mov_b32_e32 v127, v119
	v_mov_b32_e32 v115, v125
	v_pk_add_f32 v[120:121], v[120:121], v[122:123] neg_lo:[0,1] neg_hi:[0,1]
	v_mov_b32_e32 v122, v86
	v_mov_b32_e32 v123, v103
	v_pk_add_f32 v[114:115], v[126:127], v[114:115] neg_lo:[0,1] neg_hi:[0,1]
	v_pk_add_f32 v[122:123], v[122:123], v[120:121] neg_lo:[0,1] neg_hi:[0,1]
	v_mov_b32_e32 v126, v114
	v_mov_b32_e32 v127, v121
	v_mov_b32_e32 v128, v118
	v_mov_b32_e32 v129, v87
	v_mov_b32_e32 v121, v93
	v_pk_add_f32 v[126:127], v[102:103], v[126:127] neg_lo:[0,1] neg_hi:[0,1]
	v_pk_add_f32 v[120:121], v[128:129], v[120:121] neg_lo:[0,1] neg_hi:[0,1]
	v_mov_b32_e32 v103, v117
	v_pk_add_f32 v[86:87], v[86:87], v[92:93] neg_lo:[0,1] neg_hi:[0,1]
; __device__ __forceinline__ float softplusf(float x) { return fmaxf(x, 0.f) + log1pf(__expf(-fabsf(x))); }
; __device__ __forceinline__ float logsigf(float x) { return fminf(x, 0.f) - log1pf(__expf(-fabsf(x))); }
; __device__ void phaseA_tile(const Params& p, int l, int mt, int nt, char* smem) {
;     ...
;                 for (int j = 0; j < 2; ++j) {
;                     const int c = j * 16 + g4 * 4;
;                     const float4 db = *(const float4*)(p.dt_bias + l * 32 + c);
;                     const f32x4 v = acc[i][j];
;                     *(float4*)(p.dtb + (size_t)row * 32 + c) =
;                         make_float4(softplusf(v[0] + db.x), softplusf(v[1] + db.y), softplusf(v[2] + db.z), softplusf(v[3] + db.w));
;                 }
;                 {
;                     const int c = g4 * 4;
;                     const float4 fb = *(const float4*)(p.b_f + l * 16 + c);
	v_pk_add_f32 v[88:89], v[88:89], v[120:121] neg_lo:[0,1] neg_hi:[0,1]
	v_pk_add_f32 v[92:93], v[102:103], v[114:115] neg_lo:[0,1] neg_hi:[0,1]
	v_pk_add_f32 v[84:85], v[84:85], v[124:125] neg_lo:[0,1] neg_hi:[0,1]
	v_pk_add_f32 v[86:87], v[94:95], v[86:87] neg_lo:[0,1] neg_hi:[0,1]
	v_pk_add_f32 v[94:95], v[84:85], v[92:93]
	v_mov_b32_e32 v93, v123
	v_mov_b32_e32 v85, v89
	v_pk_add_f32 v[102:103], v[122:123], v[88:89]
	v_pk_add_f32 v[84:85], v[92:93], v[84:85]
	v_mov_b32_e32 v88, v94
	v_pk_add_f32 v[84:85], v[84:85], v[126:127] neg_lo:[0,1] neg_hi:[0,1]
	v_mov_b32_e32 v89, v103
	v_pk_add_f32 v[88:89], v[88:89], v[84:85] neg_lo:[0,1] neg_hi:[0,1]
	v_pk_add_f32 v[84:85], v[86:87], v[84:85] neg_lo:[0,1] neg_hi:[0,1]
	v_pk_add_f32 v[88:89], v[92:93], v[88:89] neg_lo:[0,1] neg_hi:[0,1]
	v_pk_add_f32 v[86:87], v[102:103], v[94:95]
	v_pk_add_f32 v[84:85], v[84:85], v[88:89]
	v_pk_add_f32 v[88:89], v[118:119], v[86:87]
	s_nop 0
	v_pk_add_f32 v[92:93], v[88:89], v[118:119] neg_lo:[0,1] neg_hi:[0,1]
	s_nop 0
	v_pk_add_f32 v[86:87], v[86:87], v[92:93] neg_lo:[0,1] neg_hi:[0,1]
	s_nop 0
	v_pk_add_f32 v[84:85], v[84:85], v[86:87]
	s_nop 0
	v_pk_add_f32 v[84:85], v[88:89], v[84:85]
	v_pk_mul_f32 v[88:89], v[100:101], v[110:111]
	v_cndmask_b32_e32 v84, v160, v84, vcc
	v_cmp_neq_f32_e32 vcc, s8, v130
	v_pk_add_f32 v[92:93], v[98:99], v[88:89]
	s_nop 0
	v_cndmask_b32_e32 v85, v160, v85, vcc
	v_cmp_ngt_f32_e32 vcc, -1.0, v130
	v_pk_add_f32 v[98:99], v[92:93], v[98:99] neg_lo:[0,1] neg_hi:[0,1]
	v_mov_b32_e32 v116, v92
	v_cndmask_b32_e32 v85, v161, v85, vcc
	v_cmp_ngt_f32_e32 vcc, -1.0, v83
	v_pk_add_f32 v[88:89], v[88:89], v[98:99] neg_lo:[0,1] neg_hi:[0,1]
	s_nop 0
	v_cndmask_b32_e32 v84, v161, v84, vcc
	v_cmp_neq_f32_e32 vcc, -1.0, v83
	v_pk_add_f32 v[100:101], v[90:91], v[88:89]
	v_mov_b32_e32 v99, v89
	v_cndmask_b32_e32 v84, v162, v84, vcc
	v_cmp_neq_f32_e32 vcc, -1.0, v130
	v_mov_b32_e32 v91, v101
	v_mov_b32_e32 v89, v93
	v_cndmask_b32_e32 v85, v162, v85, vcc
	v_cmp_lt_f32_e64 vcc, |v83|, s9
	v_cndmask_b32_e64 v85, v85, v130, s[0:1]
	v_pk_add_f32 v[88:89], v[90:91], v[88:89]
	v_cndmask_b32_e32 v84, v84, v83, vcc
	v_pk_add_f32 v[78:79], v[78:79], v[84:85]
	v_cvt_f32_i32_e32 v85, v134
	v_cvt_f32_i32_e32 v84, v132
	v_pk_add_f32 v[90:91], v[92:93], v[100:101]
	v_cmp_neq_f32_e32 vcc, s8, v131
	v_mov_b32_e32 v114, v90
	v_pk_mul_f32 v[86:87], v[84:85], s[12:13] op_sel_hi:[1,0]
	v_mov_b32_e32 v119, v91
	v_pk_fma_f32 v[94:95], v[84:85], s[12:13], v[86:87] op_sel_hi:[1,0,1] neg_lo:[0,0,1] neg_hi:[0,0,1]
	v_mov_b32_e32 v98, v86
	v_pk_fma_f32 v[84:85], v[84:85], s[14:15], v[94:95] op_sel_hi:[1,0,1]
	v_cmp_lt_f32_e64 s[0:1], |v133|, s9
	v_pk_add_f32 v[94:95], v[86:87], v[84:85]
	v_mov_b32_e32 v112, v84
	v_pk_add_f32 v[102:103], v[94:95], v[90:91]
	v_mov_b32_e32 v117, v95
	v_mov_b32_e32 v115, v103
	v_pk_add_f32 v[114:115], v[114:115], v[116:117] neg_lo:[0,1] neg_hi:[0,1]
	v_pk_add_f32 v[98:99], v[98:99], v[112:113]
	v_mov_b32_e32 v110, v102
	v_mov_b32_e32 v111, v95
	v_mov_b32_e32 v112, v94
	v_mov_b32_e32 v113, v87
	v_mov_b32_e32 v116, v94
	v_mov_b32_e32 v117, v103
	v_mov_b32_e32 v87, v115
	v_pk_add_f32 v[110:111], v[110:111], v[112:113] neg_lo:[0,1] neg_hi:[0,1]
	v_mov_b32_e32 v112, v90
	v_mov_b32_e32 v113, v85
	v_pk_add_f32 v[86:87], v[116:117], v[86:87] neg_lo:[0,1] neg_hi:[0,1]
	v_pk_add_f32 v[112:113], v[112:113], v[110:111] neg_lo:[0,1] neg_hi:[0,1]
	v_mov_b32_e32 v116, v86
	v_mov_b32_e32 v117, v111
	v_mov_b32_e32 v118, v102
	v_mov_b32_e32 v111, v93
	v_pk_add_f32 v[116:117], v[84:85], v[116:117] neg_lo:[0,1] neg_hi:[0,1]
	v_pk_add_f32 v[110:111], v[118:119], v[110:111] neg_lo:[0,1] neg_hi:[0,1]
	v_mov_b32_e32 v85, v95
	v_pk_add_f32 v[90:91], v[90:91], v[92:93] neg_lo:[0,1] neg_hi:[0,1]
	v_pk_add_f32 v[92:93], v[98:99], v[110:111] neg_lo:[0,1] neg_hi:[0,1]
	v_pk_add_f32 v[84:85], v[84:85], v[86:87] neg_lo:[0,1] neg_hi:[0,1]
	v_pk_add_f32 v[86:87], v[88:89], v[114:115] neg_lo:[0,1] neg_hi:[0,1]
	v_pk_add_f32 v[94:95], v[112:113], v[92:93]
	v_pk_add_f32 v[88:89], v[86:87], v[84:85]
	v_mov_b32_e32 v85, v113
	v_mov_b32_e32 v87, v93
	v_pk_add_f32 v[86:87], v[84:85], v[86:87]
	v_mov_b32_e32 v92, v88
	v_pk_add_f32 v[86:87], v[86:87], v[116:117] neg_lo:[0,1] neg_hi:[0,1]
	v_mov_b32_e32 v93, v95
	v_pk_add_f32 v[90:91], v[100:101], v[90:91] neg_lo:[0,1] neg_hi:[0,1]
	v_pk_add_f32 v[92:93], v[92:93], v[86:87] neg_lo:[0,1] neg_hi:[0,1]
	v_pk_add_f32 v[86:87], v[90:91], v[86:87] neg_lo:[0,1] neg_hi:[0,1]
	v_pk_add_f32 v[84:85], v[84:85], v[92:93] neg_lo:[0,1] neg_hi:[0,1]
	s_nop 0
	v_pk_add_f32 v[84:85], v[86:87], v[84:85]
	v_pk_add_f32 v[86:87], v[94:95], v[88:89]
	s_nop 0
	v_pk_add_f32 v[88:89], v[102:103], v[86:87]
	s_nop 0
	v_pk_add_f32 v[90:91], v[88:89], v[102:103] neg_lo:[0,1] neg_hi:[0,1]
	s_nop 0
	v_pk_add_f32 v[86:87], v[86:87], v[90:91] neg_lo:[0,1] neg_hi:[0,1]
	s_nop 0
	v_pk_add_f32 v[84:85], v[84:85], v[86:87]
	s_nop 0
	v_pk_add_f32 v[84:85], v[88:89], v[84:85]
	s_nop 0
	v_cndmask_b32_e32 v83, v160, v84, vcc
	v_cmp_neq_f32_e32 vcc, s8, v133
	s_nop 1
	v_cndmask_b32_e32 v84, v160, v85, vcc
	v_cmp_ngt_f32_e32 vcc, -1.0, v133
	s_nop 1
	v_cndmask_b32_e32 v84, v161, v84, vcc
	v_cmp_ngt_f32_e32 vcc, -1.0, v131
	s_nop 1
	v_cndmask_b32_e32 v83, v161, v83, vcc
	v_cmp_neq_f32_e32 vcc, -1.0, v131
	s_nop 1
	v_cndmask_b32_e32 v83, v162, v83, vcc
	v_cmp_neq_f32_e32 vcc, -1.0, v133
	s_nop 1
	v_cndmask_b32_e32 v84, v162, v84, vcc
	v_cmp_lt_f32_e64 vcc, |v131|, s9
	v_cndmask_b32_e64 v85, v84, v133, s[0:1]
	s_nop 0
	v_cndmask_b32_e32 v84, v83, v131, vcc
	v_pk_add_f32 v[80:81], v[80:81], v[84:85]
	global_store_dwordx4 v[76:77], v[78:81], off offset:64
	global_load_dwordx4 v[76:79], v0, s[78:79]
	s_waitcnt vmcnt(0)
; __device__ __forceinline__ float logsigf(float x) { return fminf(x, 0.f) - log1pf(__expf(-fabsf(x))); }
; __device__ void phaseA_tile(const Params& p, int l, int mt, int nt, char* smem) {
;     ...
;                 {
;                     const int c = g4 * 4;
;                     const float4 fb = *(const float4*)(p.b_f + l * 16 + c);
;                     const f32x4 v = acc[i][2];
;                     float4 lf = make_float4(logsigf(v[0] + fb.x), logsigf(v[1] + fb.y), logsigf(v[2] + fb.z), logsigf(v[3] + fb.w));
	v_add_f32_e32 v80, v22, v76
	v_min_f32_e32 v76, 0, v80
	v_mul_f32_e64 v80, |v80|, s2
	v_exp_f32_e32 v83, v80
	s_nop 0
	v_add_f32_e32 v84, 1.0, v83
	v_add_f32_e32 v80, -1.0, v84
	v_sub_f32_e32 v81, v80, v84
	v_add_f32_e32 v81, 1.0, v81
	v_sub_f32_e32 v80, v83, v80
	v_add_f32_e32 v85, v80, v81
	v_frexp_mant_f32_e32 v80, v84
	v_cmp_gt_f32_e32 vcc, s26, v80
	v_cvt_f64_f32_e32 v[80:81], v84
	v_frexp_exp_i32_f64_e32 v80, v[80:81]
	v_subbrev_co_u32_e32 v97, vcc, 0, v80, vcc
	v_sub_u32_e32 v81, 0, v97
	v_ldexp_f32 v80, v84, v81
	v_ldexp_f32 v84, v85, v81
	v_add_f32_e32 v81, v23, v77
	v_min_f32_e32 v77, 0, v81
	v_mul_f32_e64 v81, |v81|, s2
	v_exp_f32_e32 v128, v81
	s_nop 0
	v_add_f32_e32 v81, 1.0, v128
	v_add_f32_e32 v85, -1.0, v81
	v_sub_f32_e32 v86, v85, v81
	v_add_f32_e32 v86, 1.0, v86
	v_sub_f32_e32 v85, v128, v85
	v_add_f32_e32 v85, v85, v86
	v_frexp_mant_f32_e32 v86, v81
	v_cmp_gt_f32_e32 vcc, s26, v86
	v_cvt_f64_f32_e32 v[86:87], v81
	v_frexp_exp_i32_f64_e32 v86, v[86:87]
	v_subbrev_co_u32_e32 v120, vcc, 0, v86, vcc
	v_sub_u32_e32 v86, 0, v120
	v_ldexp_f32 v81, v81, v86
	v_ldexp_f32 v85, v85, v86
	v_pk_add_f32 v[86:87], v[80:81], 1.0 op_sel_hi:[1,0]
	v_pk_add_f32 v[94:95], v[80:81], -1.0 op_sel_hi:[1,0]
	v_pk_add_f32 v[88:89], v[86:87], -1.0 op_sel_hi:[1,0]
	v_pk_add_f32 v[98:99], v[94:95], 1.0 op_sel_hi:[1,0]
	v_pk_add_f32 v[88:89], v[80:81], v[88:89] neg_lo:[0,1] neg_hi:[0,1]
	v_pk_add_f32 v[80:81], v[80:81], v[98:99] neg_lo:[0,1] neg_hi:[0,1]
	v_pk_add_f32 v[88:89], v[84:85], v[88:89]
	v_pk_add_f32 v[80:81], v[84:85], v[80:81]
	v_pk_add_f32 v[90:91], v[86:87], v[88:89]
	v_pk_add_f32 v[84:85], v[94:95], v[80:81]
	v_rcp_f32_e32 v92, v90
	v_rcp_f32_e32 v93, v91
	v_pk_add_f32 v[86:87], v[90:91], v[86:87] neg_lo:[0,1] neg_hi:[0,1]
	v_pk_add_f32 v[94:95], v[84:85], v[94:95] neg_lo:[0,1] neg_hi:[0,1]
	v_pk_add_f32 v[86:87], v[88:89], v[86:87] neg_lo:[0,1] neg_hi:[0,1]
	v_pk_mul_f32 v[88:89], v[84:85], v[92:93]
	v_pk_add_f32 v[80:81], v[80:81], v[94:95] neg_lo:[0,1] neg_hi:[0,1]
	v_pk_mul_f32 v[94:95], v[90:91], v[88:89]
	v_cmp_lt_f32_e64 s[0:1], |v128|, s9
	v_pk_fma_f32 v[98:99], v[88:89], v[90:91], v[94:95] neg_lo:[0,0,1] neg_hi:[0,0,1]
	s_nop 0
	v_pk_fma_f32 v[98:99], v[88:89], v[86:87], v[98:99]
	s_nop 0
	v_pk_add_f32 v[100:101], v[94:95], v[98:99]
	s_nop 0
	v_pk_add_f32 v[102:103], v[84:85], v[100:101] neg_lo:[0,1] neg_hi:[0,1]
	v_pk_add_f32 v[94:95], v[100:101], v[94:95] neg_lo:[0,1] neg_hi:[0,1]
	v_pk_add_f32 v[84:85], v[84:85], v[102:103] neg_lo:[0,1] neg_hi:[0,1]
	s_nop 0
	v_pk_add_f32 v[84:85], v[84:85], v[100:101] neg_lo:[0,1] neg_hi:[0,1]
	s_nop 0
	v_pk_add_f32 v[80:81], v[80:81], v[84:85]
	v_pk_add_f32 v[84:85], v[94:95], v[98:99] neg_lo:[0,1] neg_hi:[0,1]
	s_nop 0
	v_pk_add_f32 v[80:81], v[84:85], v[80:81]
	s_nop 0
	v_pk_add_f32 v[84:85], v[102:103], v[80:81]
	s_nop 0
	v_pk_mul_f32 v[94:95], v[92:93], v[84:85]
	s_nop 0
	v_pk_mul_f32 v[98:99], v[90:91], v[94:95]
	s_nop 0
	v_pk_fma_f32 v[90:91], v[94:95], v[90:91], v[98:99] neg_lo:[0,0,1] neg_hi:[0,0,1]
	s_nop 0
	v_pk_fma_f32 v[86:87], v[94:95], v[86:87], v[90:91]
	v_pk_add_f32 v[90:91], v[102:103], v[84:85] neg_lo:[0,1] neg_hi:[0,1]
	s_nop 0
	v_pk_add_f32 v[80:81], v[80:81], v[90:91]
	v_pk_add_f32 v[90:91], v[98:99], v[86:87]
	s_nop 0
	v_pk_add_f32 v[100:101], v[84:85], v[90:91] neg_lo:[0,1] neg_hi:[0,1]
	v_pk_add_f32 v[98:99], v[90:91], v[98:99] neg_lo:[0,1] neg_hi:[0,1]
	v_pk_add_f32 v[84:85], v[84:85], v[100:101] neg_lo:[0,1] neg_hi:[0,1]
	s_nop 0
	v_pk_add_f32 v[84:85], v[84:85], v[90:91] neg_lo:[0,1] neg_hi:[0,1]
	s_nop 0
	v_pk_add_f32 v[80:81], v[80:81], v[84:85]
	v_pk_add_f32 v[84:85], v[98:99], v[86:87] neg_lo:[0,1] neg_hi:[0,1]
	s_nop 0
	v_pk_add_f32 v[80:81], v[84:85], v[80:81]
	v_pk_add_f32 v[84:85], v[88:89], v[94:95]
	v_pk_add_f32 v[80:81], v[100:101], v[80:81]
	v_pk_add_f32 v[86:87], v[84:85], v[88:89] neg_lo:[0,1] neg_hi:[0,1]
	v_pk_mul_f32 v[80:81], v[92:93], v[80:81]
	v_pk_add_f32 v[86:87], v[94:95], v[86:87] neg_lo:[0,1] neg_hi:[0,1]
	s_nop 0
	v_pk_add_f32 v[80:81], v[86:87], v[80:81]
	s_nop 0
	v_pk_add_f32 v[86:87], v[84:85], v[80:81]
	s_nop 0
	v_pk_add_f32 v[84:85], v[86:87], v[84:85] neg_lo:[0,1] neg_hi:[0,1]
	v_pk_mul_f32 v[88:89], v[86:87], v[86:87]
	v_pk_add_f32 v[80:81], v[80:81], v[84:85] neg_lo:[0,1] neg_hi:[0,1]
	v_pk_fma_f32 v[90:91], v[88:89], s[28:29], v[66:67] op_sel_hi:[1,0,0]
	v_ldexp_f32 v93, v81, 1
	v_add_f32_e32 v81, v24, v78
	v_min_f32_e32 v78, 0, v81
	v_mul_f32_e64 v81, |v81|, s2
	v_exp_f32_e32 v129, v81
	v_ldexp_f32 v84, v86, 1
	v_pk_fma_f32 v[90:91], v[88:89], v[90:91], s[30:31] op_sel_hi:[1,1,0]
	v_ldexp_f32 v85, v87, 1
	v_add_f32_e32 v81, 1.0, v129
	v_pk_mul_f32 v[86:87], v[86:87], v[88:89]
	v_add_f32_e32 v88, -1.0, v81
	v_sub_f32_e32 v89, v88, v81
	v_add_f32_e32 v89, 1.0, v89
	v_sub_f32_e32 v88, v129, v88
	v_add_f32_e32 v92, v88, v89
	v_frexp_mant_f32_e32 v88, v81
	v_cmp_gt_f32_e32 vcc, s26, v88
	v_cvt_f64_f32_e32 v[88:89], v81
	v_frexp_exp_i32_f64_e32 v88, v[88:89]
	v_subbrev_co_u32_e32 v130, vcc, 0, v88, vcc
	v_sub_u32_e32 v89, 0, v130
	v_ldexp_f32 v88, v81, v89
	v_add_f32_e32 v81, v25, v79
	v_min_f32_e32 v79, 0, v81
	v_mul_f32_e64 v81, |v81|, s2
	v_exp_f32_e32 v131, v81
	v_ldexp_f32 v94, v92, v89
	v_pk_mul_f32 v[86:87], v[86:87], v[90:91]
	v_ldexp_f32 v80, v80, 1
	v_add_f32_e32 v81, 1.0, v131
	v_add_f32_e32 v89, -1.0, v81
	v_sub_f32_e32 v92, v89, v81
	v_add_f32_e32 v92, 1.0, v92
	v_sub_f32_e32 v89, v131, v89
	v_add_f32_e32 v92, v89, v92
	v_frexp_mant_f32_e32 v89, v81
	v_cvt_f64_f32_e32 v[98:99], v81
	v_cmp_gt_f32_e32 vcc, s26, v89
	v_frexp_exp_i32_f64_e32 v89, v[98:99]
	v_pk_add_f32 v[90:91], v[84:85], v[86:87]
; __device__ __forceinline__ float logsigf(float x) { return fminf(x, 0.f) - log1pf(__expf(-fabsf(x))); }
; __device__ void phaseA_tile(const Params& p, int l, int mt, int nt, char* smem) {
;     ...
;                 {
;                     const int c = g4 * 4;
;                     const float4 fb = *(const float4*)(p.b_f + l * 16 + c);
;                     const f32x4 v = acc[i][2];
;                     float4 lf = make_float4(logsigf(v[0] + fb.x), logsigf(v[1] + fb.y), logsigf(v[2] + fb.z), logsigf(v[3] + fb.w));
	v_subbrev_co_u32_e32 v132, vcc, 0, v89, vcc
	v_sub_u32_e32 v95, 0, v132
	v_ldexp_f32 v89, v81, v95
	v_pk_add_f32 v[98:99], v[88:89], 1.0 op_sel_hi:[1,0]
	v_ldexp_f32 v95, v92, v95
	v_pk_add_f32 v[100:101], v[98:99], -1.0 op_sel_hi:[1,0]
	v_pk_add_f32 v[112:113], v[88:89], -1.0 op_sel_hi:[1,0]
	v_pk_add_f32 v[100:101], v[88:89], v[100:101] neg_lo:[0,1] neg_hi:[0,1]
	v_pk_add_f32 v[114:115], v[112:113], 1.0 op_sel_hi:[1,0]
	v_pk_add_f32 v[100:101], v[94:95], v[100:101]
	v_pk_add_f32 v[88:89], v[88:89], v[114:115] neg_lo:[0,1] neg_hi:[0,1]
	v_pk_add_f32 v[102:103], v[98:99], v[100:101]
	v_pk_add_f32 v[88:89], v[94:95], v[88:89]
	v_rcp_f32_e32 v110, v102
	v_rcp_f32_e32 v111, v103
	v_pk_add_f32 v[94:95], v[112:113], v[88:89]
	v_pk_add_f32 v[98:99], v[102:103], v[98:99] neg_lo:[0,1] neg_hi:[0,1]
	v_pk_add_f32 v[112:113], v[94:95], v[112:113] neg_lo:[0,1] neg_hi:[0,1]
	v_pk_add_f32 v[98:99], v[100:101], v[98:99] neg_lo:[0,1] neg_hi:[0,1]
	v_pk_mul_f32 v[100:101], v[94:95], v[110:111]
	v_pk_add_f32 v[88:89], v[88:89], v[112:113] neg_lo:[0,1] neg_hi:[0,1]
	v_pk_mul_f32 v[112:113], v[102:103], v[100:101]
	v_pk_add_f32 v[84:85], v[90:91], v[84:85] neg_lo:[0,1] neg_hi:[0,1]
	v_pk_fma_f32 v[114:115], v[100:101], v[102:103], v[112:113] neg_lo:[0,0,1] neg_hi:[0,0,1]
	v_add_u32_e32 v81, 0xffff8000, v68
	v_pk_fma_f32 v[114:115], v[100:101], v[98:99], v[114:115]
	v_pk_add_f32 v[84:85], v[86:87], v[84:85] neg_lo:[0,1] neg_hi:[0,1]
	v_pk_add_f32 v[116:117], v[112:113], v[114:115]
	v_cndmask_b32_e64 v68, v68, v81, s[60:61]
	v_pk_add_f32 v[118:119], v[94:95], v[116:117] neg_lo:[0,1] neg_hi:[0,1]
	v_pk_add_f32 v[112:113], v[116:117], v[112:113] neg_lo:[0,1] neg_hi:[0,1]
	v_pk_add_f32 v[94:95], v[94:95], v[118:119] neg_lo:[0,1] neg_hi:[0,1]
	v_mov_b32_e32 v87, v85
	v_pk_add_f32 v[94:95], v[94:95], v[116:117] neg_lo:[0,1] neg_hi:[0,1]
	v_mov_b32_e32 v124, v90
	v_pk_add_f32 v[88:89], v[88:89], v[94:95]
	v_pk_add_f32 v[94:95], v[112:113], v[114:115] neg_lo:[0,1] neg_hi:[0,1]
	v_cmp_neq_f32_e32 vcc, s8, v83
	v_pk_add_f32 v[88:89], v[94:95], v[88:89]
	s_nop 0
	v_pk_add_f32 v[94:95], v[118:119], v[88:89]
	s_nop 0
	v_pk_mul_f32 v[112:113], v[110:111], v[94:95]
	s_nop 0
	v_pk_mul_f32 v[114:115], v[102:103], v[112:113]
	s_nop 0
	v_pk_fma_f32 v[102:103], v[112:113], v[102:103], v[114:115] neg_lo:[0,0,1] neg_hi:[0,0,1]
	s_nop 0
	v_pk_fma_f32 v[98:99], v[112:113], v[98:99], v[102:103]
	v_pk_add_f32 v[102:103], v[118:119], v[94:95] neg_lo:[0,1] neg_hi:[0,1]
	s_nop 0
	v_pk_add_f32 v[88:89], v[88:89], v[102:103]
	v_pk_add_f32 v[102:103], v[114:115], v[98:99]
	s_nop 0
	v_pk_add_f32 v[116:117], v[94:95], v[102:103] neg_lo:[0,1] neg_hi:[0,1]
	v_pk_add_f32 v[114:115], v[102:103], v[114:115] neg_lo:[0,1] neg_hi:[0,1]
	v_pk_add_f32 v[94:95], v[94:95], v[116:117] neg_lo:[0,1] neg_hi:[0,1]
	s_nop 0
	v_pk_add_f32 v[94:95], v[94:95], v[102:103] neg_lo:[0,1] neg_hi:[0,1]
	s_nop 0
	v_pk_add_f32 v[88:89], v[88:89], v[94:95]
	v_pk_add_f32 v[94:95], v[114:115], v[98:99] neg_lo:[0,1] neg_hi:[0,1]
	s_nop 0
	v_pk_add_f32 v[88:89], v[94:95], v[88:89]
	v_pk_add_f32 v[94:95], v[100:101], v[112:113]
	v_pk_add_f32 v[88:89], v[116:117], v[88:89]
	v_pk_add_f32 v[98:99], v[94:95], v[100:101] neg_lo:[0,1] neg_hi:[0,1]
	v_pk_mul_f32 v[88:89], v[110:111], v[88:89]
	v_pk_add_f32 v[98:99], v[112:113], v[98:99] neg_lo:[0,1] neg_hi:[0,1]
	s_nop 0
	v_pk_add_f32 v[88:89], v[98:99], v[88:89]
	s_nop 0
	v_pk_add_f32 v[98:99], v[94:95], v[88:89]
	s_nop 0
	v_pk_mul_f32 v[100:101], v[98:99], v[98:99]
	v_pk_add_f32 v[94:95], v[98:99], v[94:95] neg_lo:[0,1] neg_hi:[0,1]
	v_pk_fma_f32 v[102:103], v[100:101], s[28:29], v[66:67] op_sel_hi:[1,0,0]
	v_pk_add_f32 v[88:89], v[88:89], v[94:95] neg_lo:[0,1] neg_hi:[0,1]
	v_ldexp_f32 v94, v98, 1
	v_pk_fma_f32 v[102:103], v[100:101], v[102:103], s[30:31] op_sel_hi:[1,1,0]
	v_ldexp_f32 v95, v99, 1
	v_pk_mul_f32 v[98:99], v[98:99], v[100:101]
	v_cvt_f32_i32_e32 v101, v120
	v_cvt_f32_i32_e32 v100, v97
	v_ldexp_f32 v111, v89, 1
	v_ashrrev_i32_e32 v89, 31, v81
	v_mov_b32_e32 v81, v93
	v_pk_mul_f32 v[112:113], v[100:101], s[12:13] op_sel_hi:[1,0]
	v_ldexp_f32 v88, v88, 1
	v_pk_fma_f32 v[114:115], v[100:101], s[12:13], v[112:113] op_sel_hi:[1,0,1] neg_lo:[0,0,1] neg_hi:[0,0,1]
	v_mov_b32_e32 v86, v112
	v_pk_fma_f32 v[100:101], v[100:101], s[14:15], v[114:115] op_sel_hi:[1,0,1]
	v_mov_b32_e32 v121, v113
	v_mov_b32_e32 v92, v100
	v_pk_add_f32 v[86:87], v[86:87], v[92:93]
	v_pk_add_f32 v[92:93], v[80:81], v[84:85]
	v_mov_b32_e32 v85, v91
	v_mov_b32_e32 v81, v93
	v_pk_add_f32 v[114:115], v[112:113], v[100:101]
	v_pk_add_f32 v[80:81], v[80:81], v[84:85]
	v_pk_add_f32 v[84:85], v[90:91], v[92:93]
	v_mov_b32_e32 v125, v115
	v_pk_add_f32 v[116:117], v[114:115], v[84:85]
	v_mov_b32_e32 v122, v84
	v_mov_b32_e32 v123, v117
	v_pk_add_f32 v[122:123], v[122:123], v[124:125] neg_lo:[0,1] neg_hi:[0,1]
	v_mov_b32_e32 v118, v116
	v_mov_b32_e32 v119, v115
	v_mov_b32_e32 v120, v114
	v_mov_b32_e32 v124, v114
	v_mov_b32_e32 v125, v117
	v_mov_b32_e32 v113, v123
	v_pk_add_f32 v[118:119], v[118:119], v[120:121] neg_lo:[0,1] neg_hi:[0,1]
	v_mov_b32_e32 v120, v84
	v_mov_b32_e32 v121, v101
	v_pk_add_f32 v[112:113], v[124:125], v[112:113] neg_lo:[0,1] neg_hi:[0,1]
	v_pk_add_f32 v[120:121], v[120:121], v[118:119] neg_lo:[0,1] neg_hi:[0,1]
	v_mov_b32_e32 v124, v112
	v_mov_b32_e32 v125, v119
	v_mov_b32_e32 v126, v116
	v_mov_b32_e32 v127, v85
	v_mov_b32_e32 v119, v91
	v_pk_add_f32 v[124:125], v[100:101], v[124:125] neg_lo:[0,1] neg_hi:[0,1]
	v_pk_add_f32 v[118:119], v[126:127], v[118:119] neg_lo:[0,1] neg_hi:[0,1]
	v_mov_b32_e32 v101, v115
	v_pk_add_f32 v[84:85], v[84:85], v[90:91] neg_lo:[0,1] neg_hi:[0,1]
; __device__ __forceinline__ float softplusf(float x) { return fmaxf(x, 0.f) + log1pf(__expf(-fabsf(x))); }
; __device__ __forceinline__ float logsigf(float x) { return fminf(x, 0.f) - log1pf(__expf(-fabsf(x))); }
; __device__ void phaseA_tile(const Params& p, int l, int mt, int nt, char* smem) {
;     ...
;             for (int i = 0; i < 4; ++i) {
;                 const int rl = wr * 64 + i * 16 + r;
;                 const int row = m0 + rl;
; #pragma unroll
;                 for (int j = 0; j < 2; ++j) {
;                     const int c = j * 16 + g4 * 4;
;                     const float4 db = *(const float4*)(p.dt_bias + l * 32 + c);
;                     const f32x4 v = acc[i][j];
;                     *(float4*)(p.dtb + (size_t)row * 32 + c) =
;                         make_float4(softplusf(v[0] + db.x), softplusf(v[1] + db.y), softplusf(v[2] + db.z), softplusf(v[3] + db.w));
;                 }
;                 {
;                     const int c = g4 * 4;
;                     const float4 fb = *(const float4*)(p.b_f + l * 16 + c);
;                     const f32x4 v = acc[i][2];
;                     float4 lf = make_float4(logsigf(v[0] + fb.x), logsigf(v[1] + fb.y), logsigf(v[2] + fb.z), logsigf(v[3] + fb.w));
;                     float* o = samp ? (p.out + O_LFS + ((size_t)l * TSM + (row - TP)) * 16 + c)
;                                     : (p.out + O_LFP + ((size_t)l * TP + row) * 16 + c);
;                     *(float4*)o = lf;
;                     *(float4*)(lf_s + rl * 16 + c) = lf;
	v_pk_add_f32 v[86:87], v[86:87], v[118:119] neg_lo:[0,1] neg_hi:[0,1]
	v_pk_add_f32 v[90:91], v[100:101], v[112:113] neg_lo:[0,1] neg_hi:[0,1]
	v_pk_add_f32 v[80:81], v[80:81], v[122:123] neg_lo:[0,1] neg_hi:[0,1]
	v_pk_add_f32 v[84:85], v[92:93], v[84:85] neg_lo:[0,1] neg_hi:[0,1]
	v_pk_add_f32 v[92:93], v[80:81], v[90:91]
	v_mov_b32_e32 v91, v121
	v_mov_b32_e32 v81, v87
	v_pk_add_f32 v[100:101], v[120:121], v[86:87]
	v_pk_add_f32 v[80:81], v[90:91], v[80:81]
	v_mov_b32_e32 v86, v92
	v_pk_add_f32 v[80:81], v[80:81], v[124:125] neg_lo:[0,1] neg_hi:[0,1]
	v_mov_b32_e32 v87, v101
	v_pk_add_f32 v[86:87], v[86:87], v[80:81] neg_lo:[0,1] neg_hi:[0,1]
	v_pk_add_f32 v[80:81], v[84:85], v[80:81] neg_lo:[0,1] neg_hi:[0,1]
	v_pk_add_f32 v[86:87], v[90:91], v[86:87] neg_lo:[0,1] neg_hi:[0,1]
	v_pk_add_f32 v[84:85], v[100:101], v[92:93]
	v_pk_add_f32 v[80:81], v[80:81], v[86:87]
	v_pk_add_f32 v[86:87], v[116:117], v[84:85]
	v_cndmask_b32_e64 v69, v69, v89, s[60:61]
	v_pk_add_f32 v[90:91], v[86:87], v[116:117] neg_lo:[0,1] neg_hi:[0,1]
	v_mov_b32_e32 v89, v111
	v_pk_add_f32 v[84:85], v[84:85], v[90:91] neg_lo:[0,1] neg_hi:[0,1]
	v_lshlrev_b64 v[68:69], 6, v[68:69]
	v_pk_add_f32 v[80:81], v[80:81], v[84:85]
	v_lshl_add_u64 v[68:69], s[6:7], 0, v[68:69]
	v_pk_add_f32 v[80:81], v[86:87], v[80:81]
	v_pk_mul_f32 v[86:87], v[98:99], v[102:103]
	v_cndmask_b32_e32 v80, v160, v80, vcc
	v_cmp_neq_f32_e32 vcc, s8, v128
	v_pk_add_f32 v[90:91], v[94:95], v[86:87]
	v_lshl_add_u64 v[68:69], v[68:69], 0, v[0:1]
	v_cndmask_b32_e32 v81, v160, v81, vcc
	v_cmp_ngt_f32_e32 vcc, -1.0, v128
	v_pk_add_f32 v[94:95], v[90:91], v[94:95] neg_lo:[0,1] neg_hi:[0,1]
	v_mov_b32_e32 v114, v90
	v_cndmask_b32_e32 v81, v161, v81, vcc
	v_cmp_ngt_f32_e32 vcc, -1.0, v83
	v_pk_add_f32 v[86:87], v[86:87], v[94:95] neg_lo:[0,1] neg_hi:[0,1]
	s_nop 0
	v_cndmask_b32_e32 v80, v161, v80, vcc
	v_cmp_neq_f32_e32 vcc, -1.0, v83
	v_pk_add_f32 v[98:99], v[88:89], v[86:87]
	v_mov_b32_e32 v95, v87
	v_cndmask_b32_e32 v80, v162, v80, vcc
	v_cmp_neq_f32_e32 vcc, -1.0, v128
	v_mov_b32_e32 v89, v99
	v_mov_b32_e32 v87, v91
	v_cndmask_b32_e32 v81, v162, v81, vcc
	v_cmp_lt_f32_e64 vcc, |v83|, s9
	v_cndmask_b32_e64 v81, v81, v128, s[0:1]
	v_pk_add_f32 v[86:87], v[88:89], v[86:87]
	v_cndmask_b32_e32 v80, v80, v83, vcc
	v_pk_add_f32 v[76:77], v[76:77], v[80:81] neg_lo:[0,1] neg_hi:[0,1]
	v_cvt_f32_i32_e32 v81, v132
	v_cvt_f32_i32_e32 v80, v130
	v_pk_add_f32 v[88:89], v[90:91], v[98:99]
	v_cmp_neq_f32_e32 vcc, s8, v129
	v_mov_b32_e32 v112, v88
	v_pk_mul_f32 v[84:85], v[80:81], s[12:13] op_sel_hi:[1,0]
	v_mov_b32_e32 v117, v89
	v_pk_fma_f32 v[92:93], v[80:81], s[12:13], v[84:85] op_sel_hi:[1,0,1] neg_lo:[0,0,1] neg_hi:[0,0,1]
	v_mov_b32_e32 v94, v84
	v_pk_fma_f32 v[80:81], v[80:81], s[14:15], v[92:93] op_sel_hi:[1,0,1]
	v_cmp_lt_f32_e64 s[0:1], |v131|, s9
	v_pk_add_f32 v[92:93], v[84:85], v[80:81]
	v_mov_b32_e32 v110, v80
	v_pk_add_f32 v[100:101], v[92:93], v[88:89]
	v_mov_b32_e32 v115, v93
	v_mov_b32_e32 v113, v101
	v_pk_add_f32 v[112:113], v[112:113], v[114:115] neg_lo:[0,1] neg_hi:[0,1]
	v_pk_add_f32 v[94:95], v[94:95], v[110:111]
	v_mov_b32_e32 v102, v100
	v_mov_b32_e32 v103, v93
	v_mov_b32_e32 v110, v92
	v_mov_b32_e32 v111, v85
	v_mov_b32_e32 v114, v92
	v_mov_b32_e32 v115, v101
	v_mov_b32_e32 v85, v113
	v_pk_add_f32 v[102:103], v[102:103], v[110:111] neg_lo:[0,1] neg_hi:[0,1]
	v_mov_b32_e32 v110, v88
	v_mov_b32_e32 v111, v81
	v_pk_add_f32 v[84:85], v[114:115], v[84:85] neg_lo:[0,1] neg_hi:[0,1]
	v_pk_add_f32 v[110:111], v[110:111], v[102:103] neg_lo:[0,1] neg_hi:[0,1]
	v_mov_b32_e32 v114, v84
	v_mov_b32_e32 v115, v103
	v_mov_b32_e32 v116, v100
	v_mov_b32_e32 v103, v91
	v_pk_add_f32 v[114:115], v[80:81], v[114:115] neg_lo:[0,1] neg_hi:[0,1]
	v_pk_add_f32 v[102:103], v[116:117], v[102:103] neg_lo:[0,1] neg_hi:[0,1]
	v_mov_b32_e32 v81, v93
	v_pk_add_f32 v[88:89], v[88:89], v[90:91] neg_lo:[0,1] neg_hi:[0,1]
	v_pk_add_f32 v[90:91], v[94:95], v[102:103] neg_lo:[0,1] neg_hi:[0,1]
	v_pk_add_f32 v[80:81], v[80:81], v[84:85] neg_lo:[0,1] neg_hi:[0,1]
	v_pk_add_f32 v[84:85], v[86:87], v[112:113] neg_lo:[0,1] neg_hi:[0,1]
	v_pk_add_f32 v[92:93], v[110:111], v[90:91]
	v_pk_add_f32 v[86:87], v[84:85], v[80:81]
	v_mov_b32_e32 v81, v111
	v_mov_b32_e32 v85, v91
	v_pk_add_f32 v[84:85], v[80:81], v[84:85]
	v_mov_b32_e32 v90, v86
	v_pk_add_f32 v[84:85], v[84:85], v[114:115] neg_lo:[0,1] neg_hi:[0,1]
	v_mov_b32_e32 v91, v93
	v_pk_add_f32 v[88:89], v[98:99], v[88:89] neg_lo:[0,1] neg_hi:[0,1]
	v_pk_add_f32 v[90:91], v[90:91], v[84:85] neg_lo:[0,1] neg_hi:[0,1]
	v_pk_add_f32 v[84:85], v[88:89], v[84:85] neg_lo:[0,1] neg_hi:[0,1]
	v_pk_add_f32 v[80:81], v[80:81], v[90:91] neg_lo:[0,1] neg_hi:[0,1]
	s_nop 0
	v_pk_add_f32 v[80:81], v[84:85], v[80:81]
	v_pk_add_f32 v[84:85], v[92:93], v[86:87]
	s_nop 0
	v_pk_add_f32 v[86:87], v[100:101], v[84:85]
	s_nop 0
	v_pk_add_f32 v[88:89], v[86:87], v[100:101] neg_lo:[0,1] neg_hi:[0,1]
	s_nop 0
	v_pk_add_f32 v[84:85], v[84:85], v[88:89] neg_lo:[0,1] neg_hi:[0,1]
	s_nop 0
	v_pk_add_f32 v[80:81], v[80:81], v[84:85]
	s_nop 0
	v_pk_add_f32 v[80:81], v[86:87], v[80:81]
	s_nop 0
	v_cndmask_b32_e32 v80, v160, v80, vcc
	v_cmp_neq_f32_e32 vcc, s8, v131
	s_nop 1
	v_cndmask_b32_e32 v81, v160, v81, vcc
	v_cmp_ngt_f32_e32 vcc, -1.0, v131
	s_nop 1
	v_cndmask_b32_e32 v81, v161, v81, vcc
	v_cmp_ngt_f32_e32 vcc, -1.0, v129
	s_nop 1
	v_cndmask_b32_e32 v80, v161, v80, vcc
	v_cmp_neq_f32_e32 vcc, -1.0, v129
	s_nop 1
	v_cndmask_b32_e32 v80, v162, v80, vcc
	v_cmp_neq_f32_e32 vcc, -1.0, v131
	s_nop 1
	v_cndmask_b32_e32 v81, v162, v81, vcc
	v_cmp_lt_f32_e64 vcc, |v129|, s9
	v_cndmask_b32_e64 v81, v81, v131, s[0:1]
	s_nop 0
	v_cndmask_b32_e32 v80, v80, v129, vcc
	v_pk_add_f32 v[78:79], v[78:79], v[80:81] neg_lo:[0,1] neg_hi:[0,1]
	global_store_dwordx4 v[68:69], v[76:79], off
	v_lshl_or_b32 v68, v82, 6, v0
	ds_write_b128 v68, v[76:79]
	global_load_dwordx4 v[78:81], v0, s[74:75]
	v_add_u32_e32 v68, s54, v71
	v_ashrrev_i32_e32 v69, 31, v68
	v_lshlrev_b64 v[76:77], 7, v[68:69]
	v_lshl_add_u64 v[76:77], s[10:11], 0, v[76:77]
	v_lshl_add_u64 v[76:77], v[76:77], 0, v[0:1]
	s_waitcnt vmcnt(0)
; __device__ __forceinline__ float softplusf(float x) { return fmaxf(x, 0.f) + log1pf(__expf(-fabsf(x))); }
; __device__ void phaseA_tile(const Params& p, int l, int mt, int nt, char* smem) {
;     ...
;                 for (int j = 0; j < 2; ++j) {
;                     const int c = j * 16 + g4 * 4;
;                     const float4 db = *(const float4*)(p.dt_bias + l * 32 + c);
;                     const f32x4 v = acc[i][j];
;                     *(float4*)(p.dtb + (size_t)row * 32 + c) =
;                         make_float4(softplusf(v[0] + db.x), softplusf(v[1] + db.y), softplusf(v[2] + db.z), softplusf(v[3] + db.w));
	v_add_f32_e32 v82, v14, v78
	v_max_f32_e32 v78, 0, v82
	v_mul_f32_e64 v82, |v82|, s2
	v_exp_f32_e32 v97, v82
	s_nop 0
	v_add_f32_e32 v84, 1.0, v97
	v_add_f32_e32 v82, -1.0, v84
	v_sub_f32_e32 v83, v82, v84
	v_add_f32_e32 v83, 1.0, v83
	v_sub_f32_e32 v82, v97, v82
	v_add_f32_e32 v85, v82, v83
	v_frexp_mant_f32_e32 v82, v84
	v_cmp_gt_f32_e32 vcc, s26, v82
	v_cvt_f64_f32_e32 v[82:83], v84
	v_frexp_exp_i32_f64_e32 v82, v[82:83]
	v_subbrev_co_u32_e32 v120, vcc, 0, v82, vcc
	v_sub_u32_e32 v83, 0, v120
	v_ldexp_f32 v82, v84, v83
	v_ldexp_f32 v84, v85, v83
	v_add_f32_e32 v83, v15, v79
	v_max_f32_e32 v79, 0, v83
	v_mul_f32_e64 v83, |v83|, s2
	v_exp_f32_e32 v128, v83
	s_nop 0
	v_add_f32_e32 v83, 1.0, v128
	v_add_f32_e32 v85, -1.0, v83
	v_sub_f32_e32 v86, v85, v83
	v_add_f32_e32 v86, 1.0, v86
	v_sub_f32_e32 v85, v128, v85
	v_add_f32_e32 v85, v85, v86
	v_frexp_mant_f32_e32 v86, v83
	v_cmp_gt_f32_e32 vcc, s26, v86
	v_cvt_f64_f32_e32 v[86:87], v83
	v_frexp_exp_i32_f64_e32 v86, v[86:87]
	v_subbrev_co_u32_e32 v121, vcc, 0, v86, vcc
	v_sub_u32_e32 v86, 0, v121
	v_ldexp_f32 v83, v83, v86
	v_ldexp_f32 v85, v85, v86
	v_pk_add_f32 v[86:87], v[82:83], 1.0 op_sel_hi:[1,0]
	v_pk_add_f32 v[94:95], v[82:83], -1.0 op_sel_hi:[1,0]
	v_pk_add_f32 v[88:89], v[86:87], -1.0 op_sel_hi:[1,0]
	v_pk_add_f32 v[98:99], v[94:95], 1.0 op_sel_hi:[1,0]
	v_pk_add_f32 v[88:89], v[82:83], v[88:89] neg_lo:[0,1] neg_hi:[0,1]
	v_pk_add_f32 v[82:83], v[82:83], v[98:99] neg_lo:[0,1] neg_hi:[0,1]
	v_pk_add_f32 v[88:89], v[84:85], v[88:89]
	v_pk_add_f32 v[82:83], v[84:85], v[82:83]
	v_pk_add_f32 v[90:91], v[86:87], v[88:89]
	v_pk_add_f32 v[84:85], v[94:95], v[82:83]
	v_rcp_f32_e32 v92, v90
	v_rcp_f32_e32 v93, v91
	v_pk_add_f32 v[86:87], v[90:91], v[86:87] neg_lo:[0,1] neg_hi:[0,1]
	v_pk_add_f32 v[94:95], v[84:85], v[94:95] neg_lo:[0,1] neg_hi:[0,1]
	v_pk_add_f32 v[86:87], v[88:89], v[86:87] neg_lo:[0,1] neg_hi:[0,1]
	v_pk_mul_f32 v[88:89], v[84:85], v[92:93]
	v_pk_add_f32 v[82:83], v[82:83], v[94:95] neg_lo:[0,1] neg_hi:[0,1]
	v_pk_mul_f32 v[94:95], v[90:91], v[88:89]
	v_cmp_lt_f32_e64 s[0:1], |v128|, s9
	v_pk_fma_f32 v[98:99], v[88:89], v[90:91], v[94:95] neg_lo:[0,0,1] neg_hi:[0,0,1]
	s_nop 0
	v_pk_fma_f32 v[98:99], v[88:89], v[86:87], v[98:99]
	s_nop 0
	v_pk_add_f32 v[100:101], v[94:95], v[98:99]
	s_nop 0
	v_pk_add_f32 v[102:103], v[84:85], v[100:101] neg_lo:[0,1] neg_hi:[0,1]
	v_pk_add_f32 v[94:95], v[100:101], v[94:95] neg_lo:[0,1] neg_hi:[0,1]
	v_pk_add_f32 v[84:85], v[84:85], v[102:103] neg_lo:[0,1] neg_hi:[0,1]
	s_nop 0
	v_pk_add_f32 v[84:85], v[84:85], v[100:101] neg_lo:[0,1] neg_hi:[0,1]
	s_nop 0
	v_pk_add_f32 v[82:83], v[82:83], v[84:85]
	v_pk_add_f32 v[84:85], v[94:95], v[98:99] neg_lo:[0,1] neg_hi:[0,1]
	s_nop 0
	v_pk_add_f32 v[82:83], v[84:85], v[82:83]
	s_nop 0
	v_pk_add_f32 v[84:85], v[102:103], v[82:83]
	s_nop 0
	v_pk_mul_f32 v[94:95], v[92:93], v[84:85]
	s_nop 0
	v_pk_mul_f32 v[98:99], v[90:91], v[94:95]
	s_nop 0
	v_pk_fma_f32 v[90:91], v[94:95], v[90:91], v[98:99] neg_lo:[0,0,1] neg_hi:[0,0,1]
	s_nop 0
	v_pk_fma_f32 v[86:87], v[94:95], v[86:87], v[90:91]
	v_pk_add_f32 v[90:91], v[102:103], v[84:85] neg_lo:[0,1] neg_hi:[0,1]
	s_nop 0
	v_pk_add_f32 v[82:83], v[82:83], v[90:91]
	v_pk_add_f32 v[90:91], v[98:99], v[86:87]
	s_nop 0
	v_pk_add_f32 v[100:101], v[84:85], v[90:91] neg_lo:[0,1] neg_hi:[0,1]
	v_pk_add_f32 v[98:99], v[90:91], v[98:99] neg_lo:[0,1] neg_hi:[0,1]
	v_pk_add_f32 v[84:85], v[84:85], v[100:101] neg_lo:[0,1] neg_hi:[0,1]
	s_nop 0
	v_pk_add_f32 v[84:85], v[84:85], v[90:91] neg_lo:[0,1] neg_hi:[0,1]
	s_nop 0
	v_pk_add_f32 v[82:83], v[82:83], v[84:85]
	v_pk_add_f32 v[84:85], v[98:99], v[86:87] neg_lo:[0,1] neg_hi:[0,1]
	s_nop 0
	v_pk_add_f32 v[82:83], v[84:85], v[82:83]
	v_pk_add_f32 v[84:85], v[88:89], v[94:95]
	v_pk_add_f32 v[82:83], v[100:101], v[82:83]
	v_pk_add_f32 v[86:87], v[84:85], v[88:89] neg_lo:[0,1] neg_hi:[0,1]
	v_pk_mul_f32 v[82:83], v[92:93], v[82:83]
	v_pk_add_f32 v[86:87], v[94:95], v[86:87] neg_lo:[0,1] neg_hi:[0,1]
	s_nop 0
	v_pk_add_f32 v[82:83], v[86:87], v[82:83]
	s_nop 0
	v_pk_add_f32 v[86:87], v[84:85], v[82:83]
	s_nop 0
	v_pk_add_f32 v[84:85], v[86:87], v[84:85] neg_lo:[0,1] neg_hi:[0,1]
	v_pk_mul_f32 v[88:89], v[86:87], v[86:87]
	v_pk_add_f32 v[82:83], v[82:83], v[84:85] neg_lo:[0,1] neg_hi:[0,1]
	v_pk_fma_f32 v[90:91], v[88:89], s[28:29], v[66:67] op_sel_hi:[1,0,0]
	v_ldexp_f32 v93, v83, 1
	v_add_f32_e32 v83, v16, v80
	v_max_f32_e32 v80, 0, v83
	v_mul_f32_e64 v83, |v83|, s2
	v_exp_f32_e32 v129, v83
	v_ldexp_f32 v84, v86, 1
	v_pk_fma_f32 v[90:91], v[88:89], v[90:91], s[30:31] op_sel_hi:[1,1,0]
	v_ldexp_f32 v85, v87, 1
	v_add_f32_e32 v83, 1.0, v129
	v_pk_mul_f32 v[86:87], v[86:87], v[88:89]
	v_add_f32_e32 v88, -1.0, v83
	v_sub_f32_e32 v89, v88, v83
	v_add_f32_e32 v89, 1.0, v89
	v_sub_f32_e32 v88, v129, v88
	v_add_f32_e32 v92, v88, v89
	v_frexp_mant_f32_e32 v88, v83
	v_cmp_gt_f32_e32 vcc, s26, v88
	v_cvt_f64_f32_e32 v[88:89], v83
	v_frexp_exp_i32_f64_e32 v88, v[88:89]
	v_subbrev_co_u32_e32 v130, vcc, 0, v88, vcc
	v_sub_u32_e32 v89, 0, v130
	v_ldexp_f32 v88, v83, v89
	v_add_f32_e32 v83, v17, v81
	v_max_f32_e32 v81, 0, v83
	v_mul_f32_e64 v83, |v83|, s2
	v_exp_f32_e32 v131, v83
	v_ldexp_f32 v94, v92, v89
	v_pk_mul_f32 v[86:87], v[86:87], v[90:91]
	v_ldexp_f32 v82, v82, 1
	v_add_f32_e32 v83, 1.0, v131
	v_add_f32_e32 v89, -1.0, v83
	v_sub_f32_e32 v92, v89, v83
	v_add_f32_e32 v92, 1.0, v92
	v_sub_f32_e32 v89, v131, v89
	v_add_f32_e32 v92, v89, v92
	v_frexp_mant_f32_e32 v89, v83
	v_cvt_f64_f32_e32 v[98:99], v83
	v_cmp_gt_f32_e32 vcc, s26, v89
	v_frexp_exp_i32_f64_e32 v89, v[98:99]
	v_pk_add_f32 v[90:91], v[84:85], v[86:87]
; __device__ __forceinline__ float softplusf(float x) { return fmaxf(x, 0.f) + log1pf(__expf(-fabsf(x))); }
; __device__ void phaseA_tile(const Params& p, int l, int mt, int nt, char* smem) {
;     ...
;                 for (int j = 0; j < 2; ++j) {
;                     const int c = j * 16 + g4 * 4;
;                     const float4 db = *(const float4*)(p.dt_bias + l * 32 + c);
;                     const f32x4 v = acc[i][j];
;                     *(float4*)(p.dtb + (size_t)row * 32 + c) =
;                         make_float4(softplusf(v[0] + db.x), softplusf(v[1] + db.y), softplusf(v[2] + db.z), softplusf(v[3] + db.w));
	v_subbrev_co_u32_e32 v132, vcc, 0, v89, vcc
	v_sub_u32_e32 v95, 0, v132
	v_ldexp_f32 v89, v83, v95
	v_pk_add_f32 v[98:99], v[88:89], 1.0 op_sel_hi:[1,0]
	v_ldexp_f32 v95, v92, v95
	v_pk_add_f32 v[100:101], v[98:99], -1.0 op_sel_hi:[1,0]
	v_pk_add_f32 v[112:113], v[88:89], -1.0 op_sel_hi:[1,0]
	v_pk_add_f32 v[100:101], v[88:89], v[100:101] neg_lo:[0,1] neg_hi:[0,1]
	v_pk_add_f32 v[114:115], v[112:113], 1.0 op_sel_hi:[1,0]
	v_pk_add_f32 v[100:101], v[94:95], v[100:101]
	v_pk_add_f32 v[88:89], v[88:89], v[114:115] neg_lo:[0,1] neg_hi:[0,1]
	v_pk_add_f32 v[102:103], v[98:99], v[100:101]
	v_pk_add_f32 v[88:89], v[94:95], v[88:89]
	v_rcp_f32_e32 v110, v102
	v_rcp_f32_e32 v111, v103
	v_pk_add_f32 v[94:95], v[112:113], v[88:89]
	v_pk_add_f32 v[98:99], v[102:103], v[98:99] neg_lo:[0,1] neg_hi:[0,1]
	v_pk_add_f32 v[112:113], v[94:95], v[112:113] neg_lo:[0,1] neg_hi:[0,1]
	v_pk_add_f32 v[98:99], v[100:101], v[98:99] neg_lo:[0,1] neg_hi:[0,1]
	v_pk_mul_f32 v[100:101], v[94:95], v[110:111]
	v_pk_add_f32 v[88:89], v[88:89], v[112:113] neg_lo:[0,1] neg_hi:[0,1]
	v_pk_mul_f32 v[112:113], v[102:103], v[100:101]
	v_pk_add_f32 v[84:85], v[90:91], v[84:85] neg_lo:[0,1] neg_hi:[0,1]
	v_pk_fma_f32 v[114:115], v[100:101], v[102:103], v[112:113] neg_lo:[0,0,1] neg_hi:[0,0,1]
	v_pk_add_f32 v[84:85], v[86:87], v[84:85] neg_lo:[0,1] neg_hi:[0,1]
	v_pk_fma_f32 v[114:115], v[100:101], v[98:99], v[114:115]
	v_mov_b32_e32 v87, v85
	v_pk_add_f32 v[116:117], v[112:113], v[114:115]
	v_mov_b32_e32 v83, v93
	v_pk_add_f32 v[118:119], v[94:95], v[116:117] neg_lo:[0,1] neg_hi:[0,1]
	v_pk_add_f32 v[112:113], v[116:117], v[112:113] neg_lo:[0,1] neg_hi:[0,1]
	v_pk_add_f32 v[94:95], v[94:95], v[118:119] neg_lo:[0,1] neg_hi:[0,1]
	v_mov_b32_e32 v124, v90
	v_pk_add_f32 v[94:95], v[94:95], v[116:117] neg_lo:[0,1] neg_hi:[0,1]
	v_cmp_neq_f32_e32 vcc, s8, v97
	v_pk_add_f32 v[88:89], v[88:89], v[94:95]
	v_pk_add_f32 v[94:95], v[112:113], v[114:115] neg_lo:[0,1] neg_hi:[0,1]
	s_nop 0
	v_pk_add_f32 v[88:89], v[94:95], v[88:89]
	s_nop 0
	v_pk_add_f32 v[94:95], v[118:119], v[88:89]
	s_nop 0
	v_pk_mul_f32 v[112:113], v[110:111], v[94:95]
	s_nop 0
	v_pk_mul_f32 v[114:115], v[102:103], v[112:113]
	s_nop 0
	v_pk_fma_f32 v[102:103], v[112:113], v[102:103], v[114:115] neg_lo:[0,0,1] neg_hi:[0,0,1]
	s_nop 0
	v_pk_fma_f32 v[98:99], v[112:113], v[98:99], v[102:103]
	v_pk_add_f32 v[102:103], v[118:119], v[94:95] neg_lo:[0,1] neg_hi:[0,1]
	s_nop 0
	v_pk_add_f32 v[88:89], v[88:89], v[102:103]
	v_pk_add_f32 v[102:103], v[114:115], v[98:99]
	s_nop 0
	v_pk_add_f32 v[116:117], v[94:95], v[102:103] neg_lo:[0,1] neg_hi:[0,1]
	v_pk_add_f32 v[114:115], v[102:103], v[114:115] neg_lo:[0,1] neg_hi:[0,1]
	v_pk_add_f32 v[94:95], v[94:95], v[116:117] neg_lo:[0,1] neg_hi:[0,1]
	s_nop 0
	v_pk_add_f32 v[94:95], v[94:95], v[102:103] neg_lo:[0,1] neg_hi:[0,1]
	s_nop 0
	v_pk_add_f32 v[88:89], v[88:89], v[94:95]
	v_pk_add_f32 v[94:95], v[114:115], v[98:99] neg_lo:[0,1] neg_hi:[0,1]
	s_nop 0
	v_pk_add_f32 v[88:89], v[94:95], v[88:89]
	v_pk_add_f32 v[94:95], v[100:101], v[112:113]
	v_pk_add_f32 v[88:89], v[116:117], v[88:89]
	v_pk_add_f32 v[98:99], v[94:95], v[100:101] neg_lo:[0,1] neg_hi:[0,1]
	v_pk_mul_f32 v[88:89], v[110:111], v[88:89]
	v_pk_add_f32 v[98:99], v[112:113], v[98:99] neg_lo:[0,1] neg_hi:[0,1]
	s_nop 0
	v_pk_add_f32 v[88:89], v[98:99], v[88:89]
	s_nop 0
	v_pk_add_f32 v[98:99], v[94:95], v[88:89]
	s_nop 0
	v_pk_mul_f32 v[100:101], v[98:99], v[98:99]
	v_pk_add_f32 v[94:95], v[98:99], v[94:95] neg_lo:[0,1] neg_hi:[0,1]
	v_pk_fma_f32 v[102:103], v[100:101], s[28:29], v[66:67] op_sel_hi:[1,0,0]
	v_pk_add_f32 v[88:89], v[88:89], v[94:95] neg_lo:[0,1] neg_hi:[0,1]
	v_ldexp_f32 v94, v98, 1
	v_pk_fma_f32 v[102:103], v[100:101], v[102:103], s[30:31] op_sel_hi:[1,1,0]
	v_ldexp_f32 v95, v99, 1
	v_pk_mul_f32 v[98:99], v[98:99], v[100:101]
	v_cvt_f32_i32_e32 v101, v121
	v_cvt_f32_i32_e32 v100, v120
	v_ldexp_f32 v111, v89, 1
	v_ldexp_f32 v88, v88, 1
	v_mov_b32_e32 v89, v111
	v_pk_mul_f32 v[112:113], v[100:101], s[12:13] op_sel_hi:[1,0]
	s_nop 0
	v_pk_fma_f32 v[114:115], v[100:101], s[12:13], v[112:113] op_sel_hi:[1,0,1] neg_lo:[0,0,1] neg_hi:[0,0,1]
	v_mov_b32_e32 v86, v112
	v_pk_fma_f32 v[100:101], v[100:101], s[14:15], v[114:115] op_sel_hi:[1,0,1]
	v_mov_b32_e32 v121, v113
	v_mov_b32_e32 v92, v100
	v_pk_add_f32 v[86:87], v[86:87], v[92:93]
	v_pk_add_f32 v[92:93], v[82:83], v[84:85]
	v_mov_b32_e32 v85, v91
	v_mov_b32_e32 v83, v93
	v_pk_add_f32 v[114:115], v[112:113], v[100:101]
	v_pk_add_f32 v[82:83], v[82:83], v[84:85]
	v_pk_add_f32 v[84:85], v[90:91], v[92:93]
	v_mov_b32_e32 v125, v115
	v_pk_add_f32 v[116:117], v[114:115], v[84:85]
	v_mov_b32_e32 v122, v84
	v_mov_b32_e32 v123, v117
	v_pk_add_f32 v[122:123], v[122:123], v[124:125] neg_lo:[0,1] neg_hi:[0,1]
	v_mov_b32_e32 v118, v116
	v_mov_b32_e32 v119, v115
	v_mov_b32_e32 v120, v114
	v_mov_b32_e32 v124, v114
	v_mov_b32_e32 v125, v117
	v_mov_b32_e32 v113, v123
	v_pk_add_f32 v[118:119], v[118:119], v[120:121] neg_lo:[0,1] neg_hi:[0,1]
	v_mov_b32_e32 v120, v84
	v_mov_b32_e32 v121, v101
	v_pk_add_f32 v[112:113], v[124:125], v[112:113] neg_lo:[0,1] neg_hi:[0,1]
	v_pk_add_f32 v[120:121], v[120:121], v[118:119] neg_lo:[0,1] neg_hi:[0,1]
	v_mov_b32_e32 v124, v112
	v_mov_b32_e32 v125, v119
	v_mov_b32_e32 v126, v116
	v_mov_b32_e32 v127, v85
	v_mov_b32_e32 v119, v91
	v_pk_add_f32 v[124:125], v[100:101], v[124:125] neg_lo:[0,1] neg_hi:[0,1]
	v_pk_add_f32 v[118:119], v[126:127], v[118:119] neg_lo:[0,1] neg_hi:[0,1]
	v_mov_b32_e32 v101, v115
	v_pk_add_f32 v[84:85], v[84:85], v[90:91] neg_lo:[0,1] neg_hi:[0,1]
	v_pk_add_f32 v[86:87], v[86:87], v[118:119] neg_lo:[0,1] neg_hi:[0,1]
; __device__ __forceinline__ float softplusf(float x) { return fmaxf(x, 0.f) + log1pf(__expf(-fabsf(x))); }
; __device__ void phaseA_tile(const Params& p, int l, int mt, int nt, char* smem) {
;     ...
;                 for (int j = 0; j < 2; ++j) {
;                     const int c = j * 16 + g4 * 4;
;                     const float4 db = *(const float4*)(p.dt_bias + l * 32 + c);
;                     const f32x4 v = acc[i][j];
;                     *(float4*)(p.dtb + (size_t)row * 32 + c) =
;                         make_float4(softplusf(v[0] + db.x), softplusf(v[1] + db.y), softplusf(v[2] + db.z), softplusf(v[3] + db.w));
	v_pk_add_f32 v[90:91], v[100:101], v[112:113] neg_lo:[0,1] neg_hi:[0,1]
	v_pk_add_f32 v[82:83], v[82:83], v[122:123] neg_lo:[0,1] neg_hi:[0,1]
	v_pk_add_f32 v[84:85], v[92:93], v[84:85] neg_lo:[0,1] neg_hi:[0,1]
	v_pk_add_f32 v[92:93], v[82:83], v[90:91]
	v_mov_b32_e32 v91, v121
	v_mov_b32_e32 v83, v87
	v_pk_add_f32 v[100:101], v[120:121], v[86:87]
	v_pk_add_f32 v[82:83], v[90:91], v[82:83]
	v_mov_b32_e32 v86, v92
	v_pk_add_f32 v[82:83], v[82:83], v[124:125] neg_lo:[0,1] neg_hi:[0,1]
	v_mov_b32_e32 v87, v101
	v_pk_add_f32 v[86:87], v[86:87], v[82:83] neg_lo:[0,1] neg_hi:[0,1]
	v_pk_add_f32 v[82:83], v[84:85], v[82:83] neg_lo:[0,1] neg_hi:[0,1]
	v_pk_add_f32 v[86:87], v[90:91], v[86:87] neg_lo:[0,1] neg_hi:[0,1]
	v_pk_add_f32 v[84:85], v[100:101], v[92:93]
	v_pk_add_f32 v[82:83], v[82:83], v[86:87]
	v_pk_add_f32 v[86:87], v[116:117], v[84:85]
	s_nop 0
	v_pk_add_f32 v[90:91], v[86:87], v[116:117] neg_lo:[0,1] neg_hi:[0,1]
	s_nop 0
	v_pk_add_f32 v[84:85], v[84:85], v[90:91] neg_lo:[0,1] neg_hi:[0,1]
	s_nop 0
	v_pk_add_f32 v[82:83], v[82:83], v[84:85]
	s_nop 0
	v_pk_add_f32 v[82:83], v[86:87], v[82:83]
	v_pk_mul_f32 v[86:87], v[98:99], v[102:103]
	v_cndmask_b32_e32 v82, v160, v82, vcc
	v_cmp_neq_f32_e32 vcc, s8, v128
	v_pk_add_f32 v[90:91], v[94:95], v[86:87]
	s_nop 0
	v_cndmask_b32_e32 v83, v160, v83, vcc
	v_cmp_ngt_f32_e32 vcc, -1.0, v128
	v_pk_add_f32 v[94:95], v[90:91], v[94:95] neg_lo:[0,1] neg_hi:[0,1]
	v_mov_b32_e32 v114, v90
	v_cndmask_b32_e32 v83, v161, v83, vcc
	v_cmp_ngt_f32_e32 vcc, -1.0, v97
	v_pk_add_f32 v[86:87], v[86:87], v[94:95] neg_lo:[0,1] neg_hi:[0,1]
	s_nop 0
	v_cndmask_b32_e32 v82, v161, v82, vcc
	v_cmp_neq_f32_e32 vcc, -1.0, v97
	v_pk_add_f32 v[98:99], v[88:89], v[86:87]
	v_mov_b32_e32 v95, v87
	v_cndmask_b32_e32 v82, v162, v82, vcc
	v_cmp_neq_f32_e32 vcc, -1.0, v128
	v_mov_b32_e32 v89, v99
	v_mov_b32_e32 v87, v91
	v_cndmask_b32_e32 v83, v162, v83, vcc
	v_cmp_lt_f32_e64 vcc, |v97|, s9
	v_cndmask_b32_e64 v83, v83, v128, s[0:1]
	v_pk_add_f32 v[86:87], v[88:89], v[86:87]
	v_cndmask_b32_e32 v82, v82, v97, vcc
	v_pk_add_f32 v[78:79], v[78:79], v[82:83]
	v_cvt_f32_i32_e32 v83, v132
	v_cvt_f32_i32_e32 v82, v130
	v_pk_add_f32 v[88:89], v[90:91], v[98:99]
	v_cmp_neq_f32_e32 vcc, s8, v129
	v_mov_b32_e32 v112, v88
	v_pk_mul_f32 v[84:85], v[82:83], s[12:13] op_sel_hi:[1,0]
	v_mov_b32_e32 v117, v89
	v_pk_fma_f32 v[92:93], v[82:83], s[12:13], v[84:85] op_sel_hi:[1,0,1] neg_lo:[0,0,1] neg_hi:[0,0,1]
	v_mov_b32_e32 v94, v84
	v_pk_fma_f32 v[82:83], v[82:83], s[14:15], v[92:93] op_sel_hi:[1,0,1]
	v_cmp_lt_f32_e64 s[0:1], |v131|, s9
	v_pk_add_f32 v[92:93], v[84:85], v[82:83]
	v_mov_b32_e32 v110, v82
	v_pk_add_f32 v[100:101], v[92:93], v[88:89]
	v_mov_b32_e32 v115, v93
	v_mov_b32_e32 v113, v101
	v_pk_add_f32 v[112:113], v[112:113], v[114:115] neg_lo:[0,1] neg_hi:[0,1]
	v_pk_add_f32 v[94:95], v[94:95], v[110:111]
	v_mov_b32_e32 v102, v100
	v_mov_b32_e32 v103, v93
	v_mov_b32_e32 v110, v92
	v_mov_b32_e32 v111, v85
	v_mov_b32_e32 v114, v92
	v_mov_b32_e32 v115, v101
	v_mov_b32_e32 v85, v113
	v_pk_add_f32 v[102:103], v[102:103], v[110:111] neg_lo:[0,1] neg_hi:[0,1]
	v_mov_b32_e32 v110, v88
	v_mov_b32_e32 v111, v83
	v_pk_add_f32 v[84:85], v[114:115], v[84:85] neg_lo:[0,1] neg_hi:[0,1]
	v_pk_add_f32 v[110:111], v[110:111], v[102:103] neg_lo:[0,1] neg_hi:[0,1]
	v_mov_b32_e32 v114, v84
	v_mov_b32_e32 v115, v103
	v_mov_b32_e32 v116, v100
	v_mov_b32_e32 v103, v91
	v_pk_add_f32 v[114:115], v[82:83], v[114:115] neg_lo:[0,1] neg_hi:[0,1]
	v_pk_add_f32 v[102:103], v[116:117], v[102:103] neg_lo:[0,1] neg_hi:[0,1]
	v_mov_b32_e32 v83, v93
	v_pk_add_f32 v[88:89], v[88:89], v[90:91] neg_lo:[0,1] neg_hi:[0,1]
	v_pk_add_f32 v[90:91], v[94:95], v[102:103] neg_lo:[0,1] neg_hi:[0,1]
	v_pk_add_f32 v[82:83], v[82:83], v[84:85] neg_lo:[0,1] neg_hi:[0,1]
	v_pk_add_f32 v[84:85], v[86:87], v[112:113] neg_lo:[0,1] neg_hi:[0,1]
	v_pk_add_f32 v[92:93], v[110:111], v[90:91]
	v_pk_add_f32 v[86:87], v[84:85], v[82:83]
	v_mov_b32_e32 v83, v111
	v_mov_b32_e32 v85, v91
	v_pk_add_f32 v[84:85], v[82:83], v[84:85]
	v_mov_b32_e32 v90, v86
	v_pk_add_f32 v[84:85], v[84:85], v[114:115] neg_lo:[0,1] neg_hi:[0,1]
	v_mov_b32_e32 v91, v93
	v_pk_add_f32 v[88:89], v[98:99], v[88:89] neg_lo:[0,1] neg_hi:[0,1]
	v_pk_add_f32 v[90:91], v[90:91], v[84:85] neg_lo:[0,1] neg_hi:[0,1]
	v_pk_add_f32 v[84:85], v[88:89], v[84:85] neg_lo:[0,1] neg_hi:[0,1]
	v_pk_add_f32 v[82:83], v[82:83], v[90:91] neg_lo:[0,1] neg_hi:[0,1]
	s_nop 0
	v_pk_add_f32 v[82:83], v[84:85], v[82:83]
	v_pk_add_f32 v[84:85], v[92:93], v[86:87]
	s_nop 0
	v_pk_add_f32 v[86:87], v[100:101], v[84:85]
	s_nop 0
	v_pk_add_f32 v[88:89], v[86:87], v[100:101] neg_lo:[0,1] neg_hi:[0,1]
	s_nop 0
	v_pk_add_f32 v[84:85], v[84:85], v[88:89] neg_lo:[0,1] neg_hi:[0,1]
	s_nop 0
	v_pk_add_f32 v[82:83], v[82:83], v[84:85]
	s_nop 0
	v_pk_add_f32 v[82:83], v[86:87], v[82:83]
	s_nop 0
	v_cndmask_b32_e32 v82, v160, v82, vcc
	v_cmp_neq_f32_e32 vcc, s8, v131
	s_nop 1
	v_cndmask_b32_e32 v83, v160, v83, vcc
	v_cmp_ngt_f32_e32 vcc, -1.0, v131
	s_nop 1
	v_cndmask_b32_e32 v83, v161, v83, vcc
	v_cmp_ngt_f32_e32 vcc, -1.0, v129
	s_nop 1
	v_cndmask_b32_e32 v82, v161, v82, vcc
	v_cmp_neq_f32_e32 vcc, -1.0, v129
	s_nop 1
	v_cndmask_b32_e32 v82, v162, v82, vcc
	v_cmp_neq_f32_e32 vcc, -1.0, v131
	s_nop 1
	v_cndmask_b32_e32 v83, v162, v83, vcc
	v_cmp_lt_f32_e64 vcc, |v129|, s9
	v_cndmask_b32_e64 v83, v83, v131, s[0:1]
	s_nop 0
	v_cndmask_b32_e32 v82, v82, v129, vcc
	v_pk_add_f32 v[80:81], v[80:81], v[82:83]
	global_store_dwordx4 v[76:77], v[78:81], off
	global_load_dwordx4 v[78:81], v0, s[74:75] offset:64
	s_waitcnt vmcnt(0)
; __device__ __forceinline__ float softplusf(float x) { return fmaxf(x, 0.f) + log1pf(__expf(-fabsf(x))); }
; __device__ void phaseA_tile(const Params& p, int l, int mt, int nt, char* smem) {
;     ...
;                 for (int j = 0; j < 2; ++j) {
;                     const int c = j * 16 + g4 * 4;
;                     const float4 db = *(const float4*)(p.dt_bias + l * 32 + c);
;                     const f32x4 v = acc[i][j];
;                     *(float4*)(p.dtb + (size_t)row * 32 + c) =
;                         make_float4(softplusf(v[0] + db.x), softplusf(v[1] + db.y), softplusf(v[2] + db.z), softplusf(v[3] + db.w));
	v_add_f32_e32 v82, v10, v78
	v_max_f32_e32 v78, 0, v82
	v_mul_f32_e64 v82, |v82|, s2
	v_exp_f32_e32 v97, v82
	s_nop 0
	v_add_f32_e32 v84, 1.0, v97
	v_add_f32_e32 v82, -1.0, v84
	v_sub_f32_e32 v83, v82, v84
	v_add_f32_e32 v83, 1.0, v83
	v_sub_f32_e32 v82, v97, v82
	v_add_f32_e32 v85, v82, v83
	v_frexp_mant_f32_e32 v82, v84
	v_cmp_gt_f32_e32 vcc, s26, v82
	v_cvt_f64_f32_e32 v[82:83], v84
	v_frexp_exp_i32_f64_e32 v82, v[82:83]
	v_subbrev_co_u32_e32 v120, vcc, 0, v82, vcc
	v_sub_u32_e32 v83, 0, v120
	v_ldexp_f32 v82, v84, v83
	v_ldexp_f32 v84, v85, v83
	v_add_f32_e32 v83, v11, v79
	v_max_f32_e32 v79, 0, v83
	v_mul_f32_e64 v83, |v83|, s2
	v_exp_f32_e32 v128, v83
	s_nop 0
	v_add_f32_e32 v83, 1.0, v128
	v_add_f32_e32 v85, -1.0, v83
	v_sub_f32_e32 v86, v85, v83
	v_add_f32_e32 v86, 1.0, v86
	v_sub_f32_e32 v85, v128, v85
	v_add_f32_e32 v85, v85, v86
	v_frexp_mant_f32_e32 v86, v83
	v_cmp_gt_f32_e32 vcc, s26, v86
	v_cvt_f64_f32_e32 v[86:87], v83
	v_frexp_exp_i32_f64_e32 v86, v[86:87]
	v_subbrev_co_u32_e32 v121, vcc, 0, v86, vcc
	v_sub_u32_e32 v86, 0, v121
	v_ldexp_f32 v83, v83, v86
	v_ldexp_f32 v85, v85, v86
	v_pk_add_f32 v[86:87], v[82:83], 1.0 op_sel_hi:[1,0]
	v_pk_add_f32 v[94:95], v[82:83], -1.0 op_sel_hi:[1,0]
	v_pk_add_f32 v[88:89], v[86:87], -1.0 op_sel_hi:[1,0]
	v_pk_add_f32 v[98:99], v[94:95], 1.0 op_sel_hi:[1,0]
	v_pk_add_f32 v[88:89], v[82:83], v[88:89] neg_lo:[0,1] neg_hi:[0,1]
	v_pk_add_f32 v[82:83], v[82:83], v[98:99] neg_lo:[0,1] neg_hi:[0,1]
	v_pk_add_f32 v[88:89], v[84:85], v[88:89]
	v_pk_add_f32 v[82:83], v[84:85], v[82:83]
	v_pk_add_f32 v[90:91], v[86:87], v[88:89]
	v_pk_add_f32 v[84:85], v[94:95], v[82:83]
	v_rcp_f32_e32 v92, v90
	v_rcp_f32_e32 v93, v91
	v_pk_add_f32 v[86:87], v[90:91], v[86:87] neg_lo:[0,1] neg_hi:[0,1]
	v_pk_add_f32 v[94:95], v[84:85], v[94:95] neg_lo:[0,1] neg_hi:[0,1]
	v_pk_add_f32 v[86:87], v[88:89], v[86:87] neg_lo:[0,1] neg_hi:[0,1]
	v_pk_mul_f32 v[88:89], v[84:85], v[92:93]
	v_pk_add_f32 v[82:83], v[82:83], v[94:95] neg_lo:[0,1] neg_hi:[0,1]
	v_pk_mul_f32 v[94:95], v[90:91], v[88:89]
	v_cmp_lt_f32_e64 s[0:1], |v128|, s9
	v_pk_fma_f32 v[98:99], v[88:89], v[90:91], v[94:95] neg_lo:[0,0,1] neg_hi:[0,0,1]
	s_nop 0
	v_pk_fma_f32 v[98:99], v[88:89], v[86:87], v[98:99]
	s_nop 0
	v_pk_add_f32 v[100:101], v[94:95], v[98:99]
	s_nop 0
	v_pk_add_f32 v[102:103], v[84:85], v[100:101] neg_lo:[0,1] neg_hi:[0,1]
	v_pk_add_f32 v[94:95], v[100:101], v[94:95] neg_lo:[0,1] neg_hi:[0,1]
	v_pk_add_f32 v[84:85], v[84:85], v[102:103] neg_lo:[0,1] neg_hi:[0,1]
	s_nop 0
	v_pk_add_f32 v[84:85], v[84:85], v[100:101] neg_lo:[0,1] neg_hi:[0,1]
	s_nop 0
	v_pk_add_f32 v[82:83], v[82:83], v[84:85]
	v_pk_add_f32 v[84:85], v[94:95], v[98:99] neg_lo:[0,1] neg_hi:[0,1]
	s_nop 0
	v_pk_add_f32 v[82:83], v[84:85], v[82:83]
	s_nop 0
	v_pk_add_f32 v[84:85], v[102:103], v[82:83]
	s_nop 0
	v_pk_mul_f32 v[94:95], v[92:93], v[84:85]
	s_nop 0
	v_pk_mul_f32 v[98:99], v[90:91], v[94:95]
	s_nop 0
	v_pk_fma_f32 v[90:91], v[94:95], v[90:91], v[98:99] neg_lo:[0,0,1] neg_hi:[0,0,1]
	s_nop 0
	v_pk_fma_f32 v[86:87], v[94:95], v[86:87], v[90:91]
	v_pk_add_f32 v[90:91], v[102:103], v[84:85] neg_lo:[0,1] neg_hi:[0,1]
	s_nop 0
	v_pk_add_f32 v[82:83], v[82:83], v[90:91]
	v_pk_add_f32 v[90:91], v[98:99], v[86:87]
	s_nop 0
	v_pk_add_f32 v[100:101], v[84:85], v[90:91] neg_lo:[0,1] neg_hi:[0,1]
	v_pk_add_f32 v[98:99], v[90:91], v[98:99] neg_lo:[0,1] neg_hi:[0,1]
	v_pk_add_f32 v[84:85], v[84:85], v[100:101] neg_lo:[0,1] neg_hi:[0,1]
	s_nop 0
	v_pk_add_f32 v[84:85], v[84:85], v[90:91] neg_lo:[0,1] neg_hi:[0,1]
	s_nop 0
	v_pk_add_f32 v[82:83], v[82:83], v[84:85]
	v_pk_add_f32 v[84:85], v[98:99], v[86:87] neg_lo:[0,1] neg_hi:[0,1]
	s_nop 0
	v_pk_add_f32 v[82:83], v[84:85], v[82:83]
	v_pk_add_f32 v[84:85], v[88:89], v[94:95]
	v_pk_add_f32 v[82:83], v[100:101], v[82:83]
	v_pk_add_f32 v[86:87], v[84:85], v[88:89] neg_lo:[0,1] neg_hi:[0,1]
	v_pk_mul_f32 v[82:83], v[92:93], v[82:83]
	v_pk_add_f32 v[86:87], v[94:95], v[86:87] neg_lo:[0,1] neg_hi:[0,1]
	s_nop 0
	v_pk_add_f32 v[82:83], v[86:87], v[82:83]
	s_nop 0
	v_pk_add_f32 v[86:87], v[84:85], v[82:83]
	s_nop 0
	v_pk_add_f32 v[84:85], v[86:87], v[84:85] neg_lo:[0,1] neg_hi:[0,1]
	v_pk_mul_f32 v[88:89], v[86:87], v[86:87]
	v_pk_add_f32 v[82:83], v[82:83], v[84:85] neg_lo:[0,1] neg_hi:[0,1]
	v_pk_fma_f32 v[90:91], v[88:89], s[28:29], v[66:67] op_sel_hi:[1,0,0]
	v_ldexp_f32 v93, v83, 1
	v_add_f32_e32 v83, v12, v80
	v_max_f32_e32 v80, 0, v83
	v_mul_f32_e64 v83, |v83|, s2
	v_exp_f32_e32 v129, v83
	v_ldexp_f32 v84, v86, 1
	v_pk_fma_f32 v[90:91], v[88:89], v[90:91], s[30:31] op_sel_hi:[1,1,0]
	v_ldexp_f32 v85, v87, 1
	v_add_f32_e32 v83, 1.0, v129
	v_pk_mul_f32 v[86:87], v[86:87], v[88:89]
	v_add_f32_e32 v88, -1.0, v83
	v_sub_f32_e32 v89, v88, v83
	v_add_f32_e32 v89, 1.0, v89
	v_sub_f32_e32 v88, v129, v88
	v_add_f32_e32 v92, v88, v89
	v_frexp_mant_f32_e32 v88, v83
	v_cmp_gt_f32_e32 vcc, s26, v88
	v_cvt_f64_f32_e32 v[88:89], v83
	v_frexp_exp_i32_f64_e32 v88, v[88:89]
	v_subbrev_co_u32_e32 v130, vcc, 0, v88, vcc
	v_sub_u32_e32 v89, 0, v130
	v_ldexp_f32 v88, v83, v89
	v_add_f32_e32 v83, v13, v81
	v_max_f32_e32 v81, 0, v83
	v_mul_f32_e64 v83, |v83|, s2
	v_exp_f32_e32 v131, v83
	v_ldexp_f32 v94, v92, v89
	v_pk_mul_f32 v[86:87], v[86:87], v[90:91]
	v_ldexp_f32 v82, v82, 1
	v_add_f32_e32 v83, 1.0, v131
	v_add_f32_e32 v89, -1.0, v83
	v_sub_f32_e32 v92, v89, v83
	v_add_f32_e32 v92, 1.0, v92
	v_sub_f32_e32 v89, v131, v89
	v_add_f32_e32 v92, v89, v92
	v_frexp_mant_f32_e32 v89, v83
	v_cvt_f64_f32_e32 v[98:99], v83
	v_cmp_gt_f32_e32 vcc, s26, v89
	v_frexp_exp_i32_f64_e32 v89, v[98:99]
	v_pk_add_f32 v[90:91], v[84:85], v[86:87]
; __device__ __forceinline__ float softplusf(float x) { return fmaxf(x, 0.f) + log1pf(__expf(-fabsf(x))); }
; __device__ void phaseA_tile(const Params& p, int l, int mt, int nt, char* smem) {
;     ...
;                 for (int j = 0; j < 2; ++j) {
;                     const int c = j * 16 + g4 * 4;
;                     const float4 db = *(const float4*)(p.dt_bias + l * 32 + c);
;                     const f32x4 v = acc[i][j];
;                     *(float4*)(p.dtb + (size_t)row * 32 + c) =
;                         make_float4(softplusf(v[0] + db.x), softplusf(v[1] + db.y), softplusf(v[2] + db.z), softplusf(v[3] + db.w));
	v_subbrev_co_u32_e32 v132, vcc, 0, v89, vcc
	v_sub_u32_e32 v95, 0, v132
	v_ldexp_f32 v89, v83, v95
	v_pk_add_f32 v[98:99], v[88:89], 1.0 op_sel_hi:[1,0]
	v_ldexp_f32 v95, v92, v95
	v_pk_add_f32 v[100:101], v[98:99], -1.0 op_sel_hi:[1,0]
	v_pk_add_f32 v[112:113], v[88:89], -1.0 op_sel_hi:[1,0]
	v_pk_add_f32 v[100:101], v[88:89], v[100:101] neg_lo:[0,1] neg_hi:[0,1]
	v_pk_add_f32 v[114:115], v[112:113], 1.0 op_sel_hi:[1,0]
	v_pk_add_f32 v[100:101], v[94:95], v[100:101]
	v_pk_add_f32 v[88:89], v[88:89], v[114:115] neg_lo:[0,1] neg_hi:[0,1]
	v_pk_add_f32 v[102:103], v[98:99], v[100:101]
	v_pk_add_f32 v[88:89], v[94:95], v[88:89]
	v_rcp_f32_e32 v110, v102
	v_rcp_f32_e32 v111, v103
	v_pk_add_f32 v[94:95], v[112:113], v[88:89]
	v_pk_add_f32 v[98:99], v[102:103], v[98:99] neg_lo:[0,1] neg_hi:[0,1]
	v_pk_add_f32 v[112:113], v[94:95], v[112:113] neg_lo:[0,1] neg_hi:[0,1]
	v_pk_add_f32 v[98:99], v[100:101], v[98:99] neg_lo:[0,1] neg_hi:[0,1]
	v_pk_mul_f32 v[100:101], v[94:95], v[110:111]
	v_pk_add_f32 v[88:89], v[88:89], v[112:113] neg_lo:[0,1] neg_hi:[0,1]
	v_pk_mul_f32 v[112:113], v[102:103], v[100:101]
	v_pk_add_f32 v[84:85], v[90:91], v[84:85] neg_lo:[0,1] neg_hi:[0,1]
	v_pk_fma_f32 v[114:115], v[100:101], v[102:103], v[112:113] neg_lo:[0,0,1] neg_hi:[0,0,1]
	v_pk_add_f32 v[84:85], v[86:87], v[84:85] neg_lo:[0,1] neg_hi:[0,1]
	v_pk_fma_f32 v[114:115], v[100:101], v[98:99], v[114:115]
	v_mov_b32_e32 v87, v85
	v_pk_add_f32 v[116:117], v[112:113], v[114:115]
	v_mov_b32_e32 v83, v93
	v_pk_add_f32 v[118:119], v[94:95], v[116:117] neg_lo:[0,1] neg_hi:[0,1]
	v_pk_add_f32 v[112:113], v[116:117], v[112:113] neg_lo:[0,1] neg_hi:[0,1]
	v_pk_add_f32 v[94:95], v[94:95], v[118:119] neg_lo:[0,1] neg_hi:[0,1]
	v_mov_b32_e32 v124, v90
	v_pk_add_f32 v[94:95], v[94:95], v[116:117] neg_lo:[0,1] neg_hi:[0,1]
	v_cmp_neq_f32_e32 vcc, s8, v97
	v_pk_add_f32 v[88:89], v[88:89], v[94:95]
	v_pk_add_f32 v[94:95], v[112:113], v[114:115] neg_lo:[0,1] neg_hi:[0,1]
	s_nop 0
	v_pk_add_f32 v[88:89], v[94:95], v[88:89]
	s_nop 0
	v_pk_add_f32 v[94:95], v[118:119], v[88:89]
	s_nop 0
	v_pk_mul_f32 v[112:113], v[110:111], v[94:95]
	s_nop 0
	v_pk_mul_f32 v[114:115], v[102:103], v[112:113]
	s_nop 0
	v_pk_fma_f32 v[102:103], v[112:113], v[102:103], v[114:115] neg_lo:[0,0,1] neg_hi:[0,0,1]
	s_nop 0
	v_pk_fma_f32 v[98:99], v[112:113], v[98:99], v[102:103]
	v_pk_add_f32 v[102:103], v[118:119], v[94:95] neg_lo:[0,1] neg_hi:[0,1]
	s_nop 0
	v_pk_add_f32 v[88:89], v[88:89], v[102:103]
	v_pk_add_f32 v[102:103], v[114:115], v[98:99]
	s_nop 0
	v_pk_add_f32 v[116:117], v[94:95], v[102:103] neg_lo:[0,1] neg_hi:[0,1]
	v_pk_add_f32 v[114:115], v[102:103], v[114:115] neg_lo:[0,1] neg_hi:[0,1]
	v_pk_add_f32 v[94:95], v[94:95], v[116:117] neg_lo:[0,1] neg_hi:[0,1]
	s_nop 0
	v_pk_add_f32 v[94:95], v[94:95], v[102:103] neg_lo:[0,1] neg_hi:[0,1]
	s_nop 0
	v_pk_add_f32 v[88:89], v[88:89], v[94:95]
	v_pk_add_f32 v[94:95], v[114:115], v[98:99] neg_lo:[0,1] neg_hi:[0,1]
	s_nop 0
	v_pk_add_f32 v[88:89], v[94:95], v[88:89]
	v_pk_add_f32 v[94:95], v[100:101], v[112:113]
	v_pk_add_f32 v[88:89], v[116:117], v[88:89]
	v_pk_add_f32 v[98:99], v[94:95], v[100:101] neg_lo:[0,1] neg_hi:[0,1]
	v_pk_mul_f32 v[88:89], v[110:111], v[88:89]
	v_pk_add_f32 v[98:99], v[112:113], v[98:99] neg_lo:[0,1] neg_hi:[0,1]
	s_nop 0
	v_pk_add_f32 v[88:89], v[98:99], v[88:89]
	s_nop 0
	v_pk_add_f32 v[98:99], v[94:95], v[88:89]
	s_nop 0
	v_pk_mul_f32 v[100:101], v[98:99], v[98:99]
	v_pk_add_f32 v[94:95], v[98:99], v[94:95] neg_lo:[0,1] neg_hi:[0,1]
	v_pk_fma_f32 v[102:103], v[100:101], s[28:29], v[66:67] op_sel_hi:[1,0,0]
	v_pk_add_f32 v[88:89], v[88:89], v[94:95] neg_lo:[0,1] neg_hi:[0,1]
	v_ldexp_f32 v94, v98, 1
	v_pk_fma_f32 v[102:103], v[100:101], v[102:103], s[30:31] op_sel_hi:[1,1,0]
	v_ldexp_f32 v95, v99, 1
	v_pk_mul_f32 v[98:99], v[98:99], v[100:101]
	v_cvt_f32_i32_e32 v101, v121
	v_cvt_f32_i32_e32 v100, v120
	v_ldexp_f32 v111, v89, 1
	v_ldexp_f32 v88, v88, 1
	v_mov_b32_e32 v89, v111
	v_pk_mul_f32 v[112:113], v[100:101], s[12:13] op_sel_hi:[1,0]
	s_nop 0
	v_pk_fma_f32 v[114:115], v[100:101], s[12:13], v[112:113] op_sel_hi:[1,0,1] neg_lo:[0,0,1] neg_hi:[0,0,1]
	v_mov_b32_e32 v86, v112
	v_pk_fma_f32 v[100:101], v[100:101], s[14:15], v[114:115] op_sel_hi:[1,0,1]
	v_mov_b32_e32 v121, v113
	v_mov_b32_e32 v92, v100
	v_pk_add_f32 v[86:87], v[86:87], v[92:93]
	v_pk_add_f32 v[92:93], v[82:83], v[84:85]
	v_mov_b32_e32 v85, v91
	v_mov_b32_e32 v83, v93
	v_pk_add_f32 v[114:115], v[112:113], v[100:101]
	v_pk_add_f32 v[82:83], v[82:83], v[84:85]
	v_pk_add_f32 v[84:85], v[90:91], v[92:93]
	v_mov_b32_e32 v125, v115
	v_pk_add_f32 v[116:117], v[114:115], v[84:85]
	v_mov_b32_e32 v122, v84
	v_mov_b32_e32 v123, v117
	v_pk_add_f32 v[122:123], v[122:123], v[124:125] neg_lo:[0,1] neg_hi:[0,1]
	v_mov_b32_e32 v118, v116
	v_mov_b32_e32 v119, v115
	v_mov_b32_e32 v120, v114
	v_mov_b32_e32 v124, v114
	v_mov_b32_e32 v125, v117
	v_mov_b32_e32 v113, v123
	v_pk_add_f32 v[118:119], v[118:119], v[120:121] neg_lo:[0,1] neg_hi:[0,1]
	v_mov_b32_e32 v120, v84
	v_mov_b32_e32 v121, v101
	v_pk_add_f32 v[112:113], v[124:125], v[112:113] neg_lo:[0,1] neg_hi:[0,1]
	v_pk_add_f32 v[120:121], v[120:121], v[118:119] neg_lo:[0,1] neg_hi:[0,1]
	v_mov_b32_e32 v124, v112
	v_mov_b32_e32 v125, v119
	v_mov_b32_e32 v126, v116
	v_mov_b32_e32 v127, v85
	v_mov_b32_e32 v119, v91
	v_pk_add_f32 v[124:125], v[100:101], v[124:125] neg_lo:[0,1] neg_hi:[0,1]
	v_pk_add_f32 v[118:119], v[126:127], v[118:119] neg_lo:[0,1] neg_hi:[0,1]
	v_mov_b32_e32 v101, v115
	v_pk_add_f32 v[84:85], v[84:85], v[90:91] neg_lo:[0,1] neg_hi:[0,1]
	v_pk_add_f32 v[86:87], v[86:87], v[118:119] neg_lo:[0,1] neg_hi:[0,1]
; __device__ __forceinline__ float softplusf(float x) { return fmaxf(x, 0.f) + log1pf(__expf(-fabsf(x))); }
; __device__ void phaseA_tile(const Params& p, int l, int mt, int nt, char* smem) {
;     ...
;                 for (int j = 0; j < 2; ++j) {
;                     const int c = j * 16 + g4 * 4;
;                     const float4 db = *(const float4*)(p.dt_bias + l * 32 + c);
;                     const f32x4 v = acc[i][j];
;                     *(float4*)(p.dtb + (size_t)row * 32 + c) =
;                         make_float4(softplusf(v[0] + db.x), softplusf(v[1] + db.y), softplusf(v[2] + db.z), softplusf(v[3] + db.w));
;                 }
;                 {
;                     const int c = g4 * 4;
;                     const float4 fb = *(const float4*)(p.b_f + l * 16 + c);
	v_pk_add_f32 v[90:91], v[100:101], v[112:113] neg_lo:[0,1] neg_hi:[0,1]
	v_pk_add_f32 v[82:83], v[82:83], v[122:123] neg_lo:[0,1] neg_hi:[0,1]
	v_pk_add_f32 v[84:85], v[92:93], v[84:85] neg_lo:[0,1] neg_hi:[0,1]
	v_pk_add_f32 v[92:93], v[82:83], v[90:91]
	v_mov_b32_e32 v91, v121
	v_mov_b32_e32 v83, v87
	v_pk_add_f32 v[100:101], v[120:121], v[86:87]
	v_pk_add_f32 v[82:83], v[90:91], v[82:83]
	v_mov_b32_e32 v86, v92
	v_pk_add_f32 v[82:83], v[82:83], v[124:125] neg_lo:[0,1] neg_hi:[0,1]
	v_mov_b32_e32 v87, v101
	v_pk_add_f32 v[86:87], v[86:87], v[82:83] neg_lo:[0,1] neg_hi:[0,1]
	v_pk_add_f32 v[82:83], v[84:85], v[82:83] neg_lo:[0,1] neg_hi:[0,1]
	v_pk_add_f32 v[86:87], v[90:91], v[86:87] neg_lo:[0,1] neg_hi:[0,1]
	v_pk_add_f32 v[84:85], v[100:101], v[92:93]
	v_pk_add_f32 v[82:83], v[82:83], v[86:87]
	v_pk_add_f32 v[86:87], v[116:117], v[84:85]
	s_nop 0
	v_pk_add_f32 v[90:91], v[86:87], v[116:117] neg_lo:[0,1] neg_hi:[0,1]
	s_nop 0
	v_pk_add_f32 v[84:85], v[84:85], v[90:91] neg_lo:[0,1] neg_hi:[0,1]
	s_nop 0
	v_pk_add_f32 v[82:83], v[82:83], v[84:85]
	s_nop 0
	v_pk_add_f32 v[82:83], v[86:87], v[82:83]
	v_pk_mul_f32 v[86:87], v[98:99], v[102:103]
	v_cndmask_b32_e32 v82, v160, v82, vcc
	v_cmp_neq_f32_e32 vcc, s8, v128
	v_pk_add_f32 v[90:91], v[94:95], v[86:87]
	s_nop 0
	v_cndmask_b32_e32 v83, v160, v83, vcc
	v_cmp_ngt_f32_e32 vcc, -1.0, v128
	v_pk_add_f32 v[94:95], v[90:91], v[94:95] neg_lo:[0,1] neg_hi:[0,1]
	v_mov_b32_e32 v114, v90
	v_cndmask_b32_e32 v83, v161, v83, vcc
	v_cmp_ngt_f32_e32 vcc, -1.0, v97
	v_pk_add_f32 v[86:87], v[86:87], v[94:95] neg_lo:[0,1] neg_hi:[0,1]
	s_nop 0
	v_cndmask_b32_e32 v82, v161, v82, vcc
	v_cmp_neq_f32_e32 vcc, -1.0, v97
	v_pk_add_f32 v[98:99], v[88:89], v[86:87]
	v_mov_b32_e32 v95, v87
	v_cndmask_b32_e32 v82, v162, v82, vcc
	v_cmp_neq_f32_e32 vcc, -1.0, v128
	v_mov_b32_e32 v89, v99
	v_mov_b32_e32 v87, v91
	v_cndmask_b32_e32 v83, v162, v83, vcc
	v_cmp_lt_f32_e64 vcc, |v97|, s9
	v_cndmask_b32_e64 v83, v83, v128, s[0:1]
	v_pk_add_f32 v[86:87], v[88:89], v[86:87]
	v_cndmask_b32_e32 v82, v82, v97, vcc
	v_pk_add_f32 v[78:79], v[78:79], v[82:83]
	v_cvt_f32_i32_e32 v83, v132
	v_cvt_f32_i32_e32 v82, v130
	v_pk_add_f32 v[88:89], v[90:91], v[98:99]
	v_cmp_neq_f32_e32 vcc, s8, v129
	v_mov_b32_e32 v112, v88
	v_pk_mul_f32 v[84:85], v[82:83], s[12:13] op_sel_hi:[1,0]
	v_mov_b32_e32 v117, v89
	v_pk_fma_f32 v[92:93], v[82:83], s[12:13], v[84:85] op_sel_hi:[1,0,1] neg_lo:[0,0,1] neg_hi:[0,0,1]
	v_mov_b32_e32 v94, v84
	v_pk_fma_f32 v[82:83], v[82:83], s[14:15], v[92:93] op_sel_hi:[1,0,1]
	v_cmp_lt_f32_e64 s[0:1], |v131|, s9
	v_pk_add_f32 v[92:93], v[84:85], v[82:83]
	v_mov_b32_e32 v110, v82
	v_pk_add_f32 v[100:101], v[92:93], v[88:89]
	v_mov_b32_e32 v115, v93
	v_mov_b32_e32 v113, v101
	v_pk_add_f32 v[112:113], v[112:113], v[114:115] neg_lo:[0,1] neg_hi:[0,1]
	v_pk_add_f32 v[94:95], v[94:95], v[110:111]
	v_mov_b32_e32 v102, v100
	v_mov_b32_e32 v103, v93
	v_mov_b32_e32 v110, v92
	v_mov_b32_e32 v111, v85
	v_mov_b32_e32 v114, v92
	v_mov_b32_e32 v115, v101
	v_mov_b32_e32 v85, v113
	v_pk_add_f32 v[102:103], v[102:103], v[110:111] neg_lo:[0,1] neg_hi:[0,1]
	v_mov_b32_e32 v110, v88
	v_mov_b32_e32 v111, v83
	v_pk_add_f32 v[84:85], v[114:115], v[84:85] neg_lo:[0,1] neg_hi:[0,1]
	v_pk_add_f32 v[110:111], v[110:111], v[102:103] neg_lo:[0,1] neg_hi:[0,1]
	v_mov_b32_e32 v114, v84
	v_mov_b32_e32 v115, v103
	v_mov_b32_e32 v116, v100
	v_mov_b32_e32 v103, v91
	v_pk_add_f32 v[114:115], v[82:83], v[114:115] neg_lo:[0,1] neg_hi:[0,1]
	v_pk_add_f32 v[102:103], v[116:117], v[102:103] neg_lo:[0,1] neg_hi:[0,1]
	v_mov_b32_e32 v83, v93
	v_pk_add_f32 v[88:89], v[88:89], v[90:91] neg_lo:[0,1] neg_hi:[0,1]
	v_pk_add_f32 v[90:91], v[94:95], v[102:103] neg_lo:[0,1] neg_hi:[0,1]
	v_pk_add_f32 v[82:83], v[82:83], v[84:85] neg_lo:[0,1] neg_hi:[0,1]
	v_pk_add_f32 v[84:85], v[86:87], v[112:113] neg_lo:[0,1] neg_hi:[0,1]
	v_pk_add_f32 v[92:93], v[110:111], v[90:91]
	v_pk_add_f32 v[86:87], v[84:85], v[82:83]
	v_mov_b32_e32 v83, v111
	v_mov_b32_e32 v85, v91
	v_pk_add_f32 v[84:85], v[82:83], v[84:85]
	v_mov_b32_e32 v90, v86
	v_pk_add_f32 v[84:85], v[84:85], v[114:115] neg_lo:[0,1] neg_hi:[0,1]
	v_mov_b32_e32 v91, v93
	v_pk_add_f32 v[88:89], v[98:99], v[88:89] neg_lo:[0,1] neg_hi:[0,1]
	v_pk_add_f32 v[90:91], v[90:91], v[84:85] neg_lo:[0,1] neg_hi:[0,1]
	v_pk_add_f32 v[84:85], v[88:89], v[84:85] neg_lo:[0,1] neg_hi:[0,1]
	v_pk_add_f32 v[82:83], v[82:83], v[90:91] neg_lo:[0,1] neg_hi:[0,1]
	s_nop 0
	v_pk_add_f32 v[82:83], v[84:85], v[82:83]
	v_pk_add_f32 v[84:85], v[92:93], v[86:87]
	s_nop 0
	v_pk_add_f32 v[86:87], v[100:101], v[84:85]
	s_nop 0
	v_pk_add_f32 v[88:89], v[86:87], v[100:101] neg_lo:[0,1] neg_hi:[0,1]
	s_nop 0
	v_pk_add_f32 v[84:85], v[84:85], v[88:89] neg_lo:[0,1] neg_hi:[0,1]
	s_nop 0
	v_pk_add_f32 v[82:83], v[82:83], v[84:85]
	s_nop 0
	v_pk_add_f32 v[82:83], v[86:87], v[82:83]
	s_nop 0
	v_cndmask_b32_e32 v82, v160, v82, vcc
	v_cmp_neq_f32_e32 vcc, s8, v131
	s_nop 1
	v_cndmask_b32_e32 v83, v160, v83, vcc
	v_cmp_ngt_f32_e32 vcc, -1.0, v131
	s_nop 1
	v_cndmask_b32_e32 v83, v161, v83, vcc
	v_cmp_ngt_f32_e32 vcc, -1.0, v129
	s_nop 1
	v_cndmask_b32_e32 v82, v161, v82, vcc
	v_cmp_neq_f32_e32 vcc, -1.0, v129
	s_nop 1
	v_cndmask_b32_e32 v82, v162, v82, vcc
	v_cmp_neq_f32_e32 vcc, -1.0, v131
	s_nop 1
	v_cndmask_b32_e32 v83, v162, v83, vcc
	v_cmp_lt_f32_e64 vcc, |v129|, s9
	v_cndmask_b32_e64 v83, v83, v131, s[0:1]
	s_nop 0
	v_cndmask_b32_e32 v82, v82, v129, vcc
	v_pk_add_f32 v[80:81], v[80:81], v[82:83]
	global_store_dwordx4 v[76:77], v[78:81], off offset:64
	global_load_dwordx4 v[76:79], v0, s[78:79]
	s_waitcnt vmcnt(0)
; __device__ __forceinline__ float logsigf(float x) { return fminf(x, 0.f) - log1pf(__expf(-fabsf(x))); }
; __device__ void phaseA_tile(const Params& p, int l, int mt, int nt, char* smem) {
;     ...
;                 {
;                     const int c = g4 * 4;
;                     const float4 fb = *(const float4*)(p.b_f + l * 16 + c);
;                     const f32x4 v = acc[i][2];
;                     float4 lf = make_float4(logsigf(v[0] + fb.x), logsigf(v[1] + fb.y), logsigf(v[2] + fb.z), logsigf(v[3] + fb.w));
	v_add_f32_e32 v80, v6, v76
	v_min_f32_e32 v76, 0, v80
	v_mul_f32_e64 v80, |v80|, s2
	v_exp_f32_e32 v97, v80
	s_nop 0
	v_add_f32_e32 v82, 1.0, v97
	v_add_f32_e32 v80, -1.0, v82
	v_sub_f32_e32 v81, v80, v82
	v_add_f32_e32 v81, 1.0, v81
	v_sub_f32_e32 v80, v97, v80
	v_add_f32_e32 v83, v80, v81
	v_frexp_mant_f32_e32 v80, v82
	v_cmp_gt_f32_e32 vcc, s26, v80
	v_cvt_f64_f32_e32 v[80:81], v82
	v_frexp_exp_i32_f64_e32 v80, v[80:81]
	v_subbrev_co_u32_e32 v118, vcc, 0, v80, vcc
	v_sub_u32_e32 v81, 0, v118
	v_ldexp_f32 v80, v82, v81
	v_ldexp_f32 v82, v83, v81
	v_add_f32_e32 v81, v7, v77
	v_min_f32_e32 v77, 0, v81
	v_mul_f32_e64 v81, |v81|, s2
	v_exp_f32_e32 v124, v81
	s_nop 0
	v_add_f32_e32 v81, 1.0, v124
	v_add_f32_e32 v83, -1.0, v81
	v_sub_f32_e32 v84, v83, v81
	v_add_f32_e32 v84, 1.0, v84
	v_sub_f32_e32 v83, v124, v83
	v_add_f32_e32 v83, v83, v84
	v_frexp_mant_f32_e32 v84, v81
	v_cmp_gt_f32_e32 vcc, s26, v84
	v_cvt_f64_f32_e32 v[84:85], v81
	v_frexp_exp_i32_f64_e32 v84, v[84:85]
	v_subbrev_co_u32_e32 v119, vcc, 0, v84, vcc
	v_sub_u32_e32 v84, 0, v119
	v_ldexp_f32 v81, v81, v84
	v_ldexp_f32 v83, v83, v84
	v_pk_add_f32 v[84:85], v[80:81], 1.0 op_sel_hi:[1,0]
	v_pk_add_f32 v[92:93], v[80:81], -1.0 op_sel_hi:[1,0]
	v_pk_add_f32 v[86:87], v[84:85], -1.0 op_sel_hi:[1,0]
	v_pk_add_f32 v[94:95], v[92:93], 1.0 op_sel_hi:[1,0]
	v_pk_add_f32 v[86:87], v[80:81], v[86:87] neg_lo:[0,1] neg_hi:[0,1]
	v_pk_add_f32 v[80:81], v[80:81], v[94:95] neg_lo:[0,1] neg_hi:[0,1]
	v_pk_add_f32 v[86:87], v[82:83], v[86:87]
	v_pk_add_f32 v[80:81], v[82:83], v[80:81]
	v_pk_add_f32 v[88:89], v[84:85], v[86:87]
	v_pk_add_f32 v[82:83], v[92:93], v[80:81]
	v_rcp_f32_e32 v90, v88
	v_rcp_f32_e32 v91, v89
	v_pk_add_f32 v[84:85], v[88:89], v[84:85] neg_lo:[0,1] neg_hi:[0,1]
	v_pk_add_f32 v[92:93], v[82:83], v[92:93] neg_lo:[0,1] neg_hi:[0,1]
	v_pk_add_f32 v[84:85], v[86:87], v[84:85] neg_lo:[0,1] neg_hi:[0,1]
	v_pk_mul_f32 v[86:87], v[82:83], v[90:91]
	v_pk_add_f32 v[80:81], v[80:81], v[92:93] neg_lo:[0,1] neg_hi:[0,1]
	v_pk_mul_f32 v[92:93], v[88:89], v[86:87]
	v_cmp_lt_f32_e64 s[0:1], |v124|, s9
	v_pk_fma_f32 v[94:95], v[86:87], v[88:89], v[92:93] neg_lo:[0,0,1] neg_hi:[0,0,1]
	s_nop 0
	v_pk_fma_f32 v[94:95], v[86:87], v[84:85], v[94:95]
	s_nop 0
	v_pk_add_f32 v[98:99], v[92:93], v[94:95]
	s_nop 0
	v_pk_add_f32 v[100:101], v[82:83], v[98:99] neg_lo:[0,1] neg_hi:[0,1]
	v_pk_add_f32 v[92:93], v[98:99], v[92:93] neg_lo:[0,1] neg_hi:[0,1]
	v_pk_add_f32 v[82:83], v[82:83], v[100:101] neg_lo:[0,1] neg_hi:[0,1]
	s_nop 0
	v_pk_add_f32 v[82:83], v[82:83], v[98:99] neg_lo:[0,1] neg_hi:[0,1]
	s_nop 0
	v_pk_add_f32 v[80:81], v[80:81], v[82:83]
	v_pk_add_f32 v[82:83], v[92:93], v[94:95] neg_lo:[0,1] neg_hi:[0,1]
	s_nop 0
	v_pk_add_f32 v[80:81], v[82:83], v[80:81]
	s_nop 0
	v_pk_add_f32 v[82:83], v[100:101], v[80:81]
	s_nop 0
	v_pk_mul_f32 v[92:93], v[90:91], v[82:83]
	s_nop 0
	v_pk_mul_f32 v[94:95], v[88:89], v[92:93]
	s_nop 0
	v_pk_fma_f32 v[88:89], v[92:93], v[88:89], v[94:95] neg_lo:[0,0,1] neg_hi:[0,0,1]
	s_nop 0
	v_pk_fma_f32 v[84:85], v[92:93], v[84:85], v[88:89]
	v_pk_add_f32 v[88:89], v[100:101], v[82:83] neg_lo:[0,1] neg_hi:[0,1]
	s_nop 0
	v_pk_add_f32 v[80:81], v[80:81], v[88:89]
	v_pk_add_f32 v[88:89], v[94:95], v[84:85]
	s_nop 0
	v_pk_add_f32 v[98:99], v[82:83], v[88:89] neg_lo:[0,1] neg_hi:[0,1]
	v_pk_add_f32 v[94:95], v[88:89], v[94:95] neg_lo:[0,1] neg_hi:[0,1]
	v_pk_add_f32 v[82:83], v[82:83], v[98:99] neg_lo:[0,1] neg_hi:[0,1]
	s_nop 0
	v_pk_add_f32 v[82:83], v[82:83], v[88:89] neg_lo:[0,1] neg_hi:[0,1]
	s_nop 0
	v_pk_add_f32 v[80:81], v[80:81], v[82:83]
	v_pk_add_f32 v[82:83], v[94:95], v[84:85] neg_lo:[0,1] neg_hi:[0,1]
	s_nop 0
	v_pk_add_f32 v[80:81], v[82:83], v[80:81]
	v_pk_add_f32 v[82:83], v[86:87], v[92:93]
	v_pk_add_f32 v[80:81], v[98:99], v[80:81]
	v_pk_add_f32 v[84:85], v[82:83], v[86:87] neg_lo:[0,1] neg_hi:[0,1]
	v_pk_mul_f32 v[80:81], v[90:91], v[80:81]
	v_pk_add_f32 v[84:85], v[92:93], v[84:85] neg_lo:[0,1] neg_hi:[0,1]
	s_nop 0
	v_pk_add_f32 v[80:81], v[84:85], v[80:81]
	s_nop 0
	v_pk_add_f32 v[84:85], v[82:83], v[80:81]
	s_nop 0
	v_pk_add_f32 v[82:83], v[84:85], v[82:83] neg_lo:[0,1] neg_hi:[0,1]
	v_pk_mul_f32 v[86:87], v[84:85], v[84:85]
	v_pk_add_f32 v[80:81], v[80:81], v[82:83] neg_lo:[0,1] neg_hi:[0,1]
	v_pk_fma_f32 v[88:89], v[86:87], s[28:29], v[66:67] op_sel_hi:[1,0,0]
	v_ldexp_f32 v91, v81, 1
	v_add_f32_e32 v81, v8, v78
	v_min_f32_e32 v78, 0, v81
	v_mul_f32_e64 v81, |v81|, s2
	v_exp_f32_e32 v125, v81
	v_ldexp_f32 v82, v84, 1
	v_pk_fma_f32 v[88:89], v[86:87], v[88:89], s[30:31] op_sel_hi:[1,1,0]
	v_ldexp_f32 v83, v85, 1
	v_add_f32_e32 v81, 1.0, v125
	v_pk_mul_f32 v[84:85], v[84:85], v[86:87]
	v_add_f32_e32 v86, -1.0, v81
	v_sub_f32_e32 v87, v86, v81
	v_add_f32_e32 v87, 1.0, v87
	v_sub_f32_e32 v86, v125, v86
	v_add_f32_e32 v90, v86, v87
	v_frexp_mant_f32_e32 v86, v81
	v_cmp_gt_f32_e32 vcc, s26, v86
	v_cvt_f64_f32_e32 v[86:87], v81
	v_frexp_exp_i32_f64_e32 v86, v[86:87]
	v_subbrev_co_u32_e32 v126, vcc, 0, v86, vcc
	v_sub_u32_e32 v87, 0, v126
	v_ldexp_f32 v86, v81, v87
	v_add_f32_e32 v81, v9, v79
	v_min_f32_e32 v79, 0, v81
	v_mul_f32_e64 v81, |v81|, s2
	v_exp_f32_e32 v127, v81
	v_ldexp_f32 v92, v90, v87
	v_pk_mul_f32 v[84:85], v[84:85], v[88:89]
	v_ldexp_f32 v80, v80, 1
	v_add_f32_e32 v81, 1.0, v127
	v_add_f32_e32 v87, -1.0, v81
	v_sub_f32_e32 v90, v87, v81
	v_add_f32_e32 v90, 1.0, v90
	v_sub_f32_e32 v87, v127, v87
	v_add_f32_e32 v90, v87, v90
	v_frexp_mant_f32_e32 v87, v81
	v_cvt_f64_f32_e32 v[94:95], v81
	v_cmp_gt_f32_e32 vcc, s26, v87
	v_frexp_exp_i32_f64_e32 v87, v[94:95]
	v_pk_add_f32 v[88:89], v[82:83], v[84:85]
	v_subbrev_co_u32_e32 v128, vcc, 0, v87, vcc
; __device__ __forceinline__ float logsigf(float x) { return fminf(x, 0.f) - log1pf(__expf(-fabsf(x))); }
; __device__ void phaseA_tile(const Params& p, int l, int mt, int nt, char* smem) {
;     ...
;                 {
;                     const int c = g4 * 4;
;                     const float4 fb = *(const float4*)(p.b_f + l * 16 + c);
;                     const f32x4 v = acc[i][2];
;                     float4 lf = make_float4(logsigf(v[0] + fb.x), logsigf(v[1] + fb.y), logsigf(v[2] + fb.z), logsigf(v[3] + fb.w));
;                     float* o = samp ? (p.out + O_LFS + ((size_t)l * TSM + (row - TP)) * 16 + c)
;                                     : (p.out + O_LFP + ((size_t)l * TP + row) * 16 + c);
;                     *(float4*)o = lf;
	v_sub_u32_e32 v93, 0, v128
	v_ldexp_f32 v87, v81, v93
	v_pk_add_f32 v[94:95], v[86:87], 1.0 op_sel_hi:[1,0]
	v_ldexp_f32 v93, v90, v93
	v_pk_add_f32 v[98:99], v[94:95], -1.0 op_sel_hi:[1,0]
	v_pk_add_f32 v[110:111], v[86:87], -1.0 op_sel_hi:[1,0]
	v_pk_add_f32 v[98:99], v[86:87], v[98:99] neg_lo:[0,1] neg_hi:[0,1]
	v_pk_add_f32 v[112:113], v[110:111], 1.0 op_sel_hi:[1,0]
	v_pk_add_f32 v[98:99], v[92:93], v[98:99]
	v_pk_add_f32 v[86:87], v[86:87], v[112:113] neg_lo:[0,1] neg_hi:[0,1]
	v_pk_add_f32 v[100:101], v[94:95], v[98:99]
	v_pk_add_f32 v[86:87], v[92:93], v[86:87]
	v_rcp_f32_e32 v102, v100
	v_rcp_f32_e32 v103, v101
	v_pk_add_f32 v[92:93], v[110:111], v[86:87]
	v_pk_add_f32 v[94:95], v[100:101], v[94:95] neg_lo:[0,1] neg_hi:[0,1]
	v_pk_add_f32 v[110:111], v[92:93], v[110:111] neg_lo:[0,1] neg_hi:[0,1]
	v_pk_add_f32 v[94:95], v[98:99], v[94:95] neg_lo:[0,1] neg_hi:[0,1]
	v_pk_mul_f32 v[98:99], v[92:93], v[102:103]
	v_pk_add_f32 v[86:87], v[86:87], v[110:111] neg_lo:[0,1] neg_hi:[0,1]
	v_pk_mul_f32 v[110:111], v[100:101], v[98:99]
	v_pk_add_f32 v[82:83], v[88:89], v[82:83] neg_lo:[0,1] neg_hi:[0,1]
	v_pk_fma_f32 v[112:113], v[98:99], v[100:101], v[110:111] neg_lo:[0,0,1] neg_hi:[0,0,1]
	v_pk_add_f32 v[82:83], v[84:85], v[82:83] neg_lo:[0,1] neg_hi:[0,1]
	v_pk_fma_f32 v[112:113], v[98:99], v[94:95], v[112:113]
	v_mov_b32_e32 v85, v83
	v_pk_add_f32 v[114:115], v[110:111], v[112:113]
	v_mov_b32_e32 v81, v91
	v_pk_add_f32 v[116:117], v[92:93], v[114:115] neg_lo:[0,1] neg_hi:[0,1]
	v_pk_add_f32 v[110:111], v[114:115], v[110:111] neg_lo:[0,1] neg_hi:[0,1]
	v_pk_add_f32 v[92:93], v[92:93], v[116:117] neg_lo:[0,1] neg_hi:[0,1]
	v_mov_b32_e32 v120, v88
	v_pk_add_f32 v[92:93], v[92:93], v[114:115] neg_lo:[0,1] neg_hi:[0,1]
	v_cmp_neq_f32_e32 vcc, s8, v97
	v_pk_add_f32 v[86:87], v[86:87], v[92:93]
	v_pk_add_f32 v[92:93], v[110:111], v[112:113] neg_lo:[0,1] neg_hi:[0,1]
	s_nop 0
	v_pk_add_f32 v[86:87], v[92:93], v[86:87]
	s_nop 0
	v_pk_add_f32 v[92:93], v[116:117], v[86:87]
	s_nop 0
	v_pk_mul_f32 v[110:111], v[102:103], v[92:93]
	s_nop 0
	v_pk_mul_f32 v[112:113], v[100:101], v[110:111]
	s_nop 0
	v_pk_fma_f32 v[100:101], v[110:111], v[100:101], v[112:113] neg_lo:[0,0,1] neg_hi:[0,0,1]
	s_nop 0
	v_pk_fma_f32 v[94:95], v[110:111], v[94:95], v[100:101]
	v_pk_add_f32 v[100:101], v[116:117], v[92:93] neg_lo:[0,1] neg_hi:[0,1]
	s_nop 0
	v_pk_add_f32 v[86:87], v[86:87], v[100:101]
	v_pk_add_f32 v[100:101], v[112:113], v[94:95]
	s_nop 0
	v_pk_add_f32 v[114:115], v[92:93], v[100:101] neg_lo:[0,1] neg_hi:[0,1]
	v_pk_add_f32 v[112:113], v[100:101], v[112:113] neg_lo:[0,1] neg_hi:[0,1]
	v_pk_add_f32 v[92:93], v[92:93], v[114:115] neg_lo:[0,1] neg_hi:[0,1]
	s_nop 0
	v_pk_add_f32 v[92:93], v[92:93], v[100:101] neg_lo:[0,1] neg_hi:[0,1]
	s_nop 0
	v_pk_add_f32 v[86:87], v[86:87], v[92:93]
	v_pk_add_f32 v[92:93], v[112:113], v[94:95] neg_lo:[0,1] neg_hi:[0,1]
	s_nop 0
	v_pk_add_f32 v[86:87], v[92:93], v[86:87]
	v_pk_add_f32 v[92:93], v[98:99], v[110:111]
	v_pk_add_f32 v[86:87], v[114:115], v[86:87]
	v_pk_add_f32 v[94:95], v[92:93], v[98:99] neg_lo:[0,1] neg_hi:[0,1]
	v_pk_mul_f32 v[86:87], v[102:103], v[86:87]
	v_pk_add_f32 v[94:95], v[110:111], v[94:95] neg_lo:[0,1] neg_hi:[0,1]
	s_nop 0
	v_pk_add_f32 v[86:87], v[94:95], v[86:87]
	s_nop 0
	v_pk_add_f32 v[94:95], v[92:93], v[86:87]
	s_nop 0
	v_pk_mul_f32 v[98:99], v[94:95], v[94:95]
	v_pk_add_f32 v[92:93], v[94:95], v[92:93] neg_lo:[0,1] neg_hi:[0,1]
	v_pk_fma_f32 v[66:67], v[98:99], s[28:29], v[66:67] op_sel_hi:[1,0,0]
	v_pk_add_f32 v[86:87], v[86:87], v[92:93] neg_lo:[0,1] neg_hi:[0,1]
	v_pk_fma_f32 v[100:101], v[98:99], v[66:67], s[30:31] op_sel_hi:[1,1,0]
	v_add_u32_e32 v66, 0xffff8000, v68
	v_ashrrev_i32_e32 v67, 31, v66
	v_cndmask_b32_e64 v67, v69, v67, s[60:61]
	v_cndmask_b32_e64 v66, v68, v66, s[60:61]
	v_cvt_f32_i32_e32 v69, v119
	v_cvt_f32_i32_e32 v68, v118
	v_ldexp_f32 v92, v94, 1
	v_ldexp_f32 v93, v95, 1
	v_pk_mul_f32 v[94:95], v[94:95], v[98:99]
	v_pk_mul_f32 v[98:99], v[68:69], s[12:13] op_sel_hi:[1,0]
	v_ldexp_f32 v103, v87, 1
	v_pk_fma_f32 v[110:111], v[68:69], s[12:13], v[98:99] op_sel_hi:[1,0,1] neg_lo:[0,0,1] neg_hi:[0,0,1]
	v_mov_b32_e32 v84, v98
	v_pk_fma_f32 v[68:69], v[68:69], s[14:15], v[110:111] op_sel_hi:[1,0,1]
	v_mov_b32_e32 v117, v99
	v_mov_b32_e32 v90, v68
	v_pk_add_f32 v[84:85], v[84:85], v[90:91]
	v_pk_add_f32 v[90:91], v[80:81], v[82:83]
	v_mov_b32_e32 v83, v89
	v_mov_b32_e32 v81, v91
	v_pk_add_f32 v[110:111], v[98:99], v[68:69]
	v_pk_add_f32 v[80:81], v[80:81], v[82:83]
	v_pk_add_f32 v[82:83], v[88:89], v[90:91]
	v_mov_b32_e32 v121, v111
	v_pk_add_f32 v[112:113], v[110:111], v[82:83]
	v_mov_b32_e32 v118, v82
	v_mov_b32_e32 v119, v113
	v_pk_add_f32 v[118:119], v[118:119], v[120:121] neg_lo:[0,1] neg_hi:[0,1]
	v_mov_b32_e32 v114, v112
	v_mov_b32_e32 v115, v111
	v_mov_b32_e32 v116, v110
	v_mov_b32_e32 v120, v110
	v_mov_b32_e32 v121, v113
	v_mov_b32_e32 v99, v119
	v_pk_add_f32 v[114:115], v[114:115], v[116:117] neg_lo:[0,1] neg_hi:[0,1]
	v_mov_b32_e32 v116, v82
	v_mov_b32_e32 v117, v69
	v_pk_add_f32 v[98:99], v[120:121], v[98:99] neg_lo:[0,1] neg_hi:[0,1]
	v_pk_add_f32 v[116:117], v[116:117], v[114:115] neg_lo:[0,1] neg_hi:[0,1]
	v_mov_b32_e32 v120, v98
	v_mov_b32_e32 v121, v115
	v_mov_b32_e32 v122, v112
	v_mov_b32_e32 v123, v83
	v_mov_b32_e32 v115, v89
	v_pk_add_f32 v[120:121], v[68:69], v[120:121] neg_lo:[0,1] neg_hi:[0,1]
	v_pk_add_f32 v[114:115], v[122:123], v[114:115] neg_lo:[0,1] neg_hi:[0,1]
	v_mov_b32_e32 v69, v111
	v_pk_add_f32 v[84:85], v[84:85], v[114:115] neg_lo:[0,1] neg_hi:[0,1]
	v_pk_add_f32 v[68:69], v[68:69], v[98:99] neg_lo:[0,1] neg_hi:[0,1]
; __device__ __forceinline__ float logsigf(float x) { return fminf(x, 0.f) - log1pf(__expf(-fabsf(x))); }
; __device__ void phaseA_tile(const Params& p, int l, int mt, int nt, char* smem) {
;     ...
;                 {
;                     const int c = g4 * 4;
;                     const float4 fb = *(const float4*)(p.b_f + l * 16 + c);
;                     const f32x4 v = acc[i][2];
;                     float4 lf = make_float4(logsigf(v[0] + fb.x), logsigf(v[1] + fb.y), logsigf(v[2] + fb.z), logsigf(v[3] + fb.w));
;                     float* o = samp ? (p.out + O_LFS + ((size_t)l * TSM + (row - TP)) * 16 + c)
;                                     : (p.out + O_LFP + ((size_t)l * TP + row) * 16 + c);
;                     *(float4*)o = lf;
;                     *(float4*)(lf_s + rl * 16 + c) = lf;
	v_pk_add_f32 v[80:81], v[80:81], v[118:119] neg_lo:[0,1] neg_hi:[0,1]
	v_pk_add_f32 v[82:83], v[82:83], v[88:89] neg_lo:[0,1] neg_hi:[0,1]
	v_pk_add_f32 v[88:89], v[80:81], v[68:69]
	v_mov_b32_e32 v69, v117
	v_mov_b32_e32 v81, v85
	v_pk_add_f32 v[82:83], v[90:91], v[82:83] neg_lo:[0,1] neg_hi:[0,1]
	v_pk_add_f32 v[90:91], v[116:117], v[84:85]
	v_pk_add_f32 v[80:81], v[68:69], v[80:81]
	v_mov_b32_e32 v84, v88
	v_pk_add_f32 v[80:81], v[80:81], v[120:121] neg_lo:[0,1] neg_hi:[0,1]
	v_mov_b32_e32 v85, v91
	v_pk_add_f32 v[84:85], v[84:85], v[80:81] neg_lo:[0,1] neg_hi:[0,1]
	v_pk_add_f32 v[80:81], v[82:83], v[80:81] neg_lo:[0,1] neg_hi:[0,1]
	v_pk_add_f32 v[68:69], v[68:69], v[84:85] neg_lo:[0,1] neg_hi:[0,1]
	v_ldexp_f32 v86, v86, 1
	v_pk_add_f32 v[68:69], v[80:81], v[68:69]
	v_pk_add_f32 v[80:81], v[90:91], v[88:89]
	v_mov_b32_e32 v87, v103
	v_pk_add_f32 v[82:83], v[112:113], v[80:81]
	v_lshlrev_b64 v[66:67], 6, v[66:67]
	v_pk_add_f32 v[84:85], v[82:83], v[112:113] neg_lo:[0,1] neg_hi:[0,1]
	v_lshl_add_u64 v[66:67], s[6:7], 0, v[66:67]
	v_pk_add_f32 v[80:81], v[80:81], v[84:85] neg_lo:[0,1] neg_hi:[0,1]
	v_lshl_add_u64 v[66:67], v[66:67], 0, v[0:1]
	v_pk_add_f32 v[68:69], v[68:69], v[80:81]
	v_lshl_or_b32 v0, v71, 6, v0
	v_pk_add_f32 v[68:69], v[82:83], v[68:69]
	v_pk_mul_f32 v[82:83], v[94:95], v[100:101]
	v_cndmask_b32_e32 v68, v160, v68, vcc
	v_cmp_neq_f32_e32 vcc, s8, v124
	v_pk_add_f32 v[84:85], v[92:93], v[82:83]
	s_nop 0
	v_cndmask_b32_e32 v69, v160, v69, vcc
	v_cmp_ngt_f32_e32 vcc, -1.0, v124
	v_pk_add_f32 v[90:91], v[84:85], v[92:93] neg_lo:[0,1] neg_hi:[0,1]
	v_mov_b32_e32 v110, v84
	v_cndmask_b32_e32 v69, v161, v69, vcc
	v_cmp_ngt_f32_e32 vcc, -1.0, v97
	v_pk_add_f32 v[82:83], v[82:83], v[90:91] neg_lo:[0,1] neg_hi:[0,1]
	s_nop 0
	v_cndmask_b32_e32 v68, v161, v68, vcc
	v_cmp_neq_f32_e32 vcc, -1.0, v97
	v_pk_add_f32 v[92:93], v[86:87], v[82:83]
	v_mov_b32_e32 v91, v83
	v_cndmask_b32_e32 v68, v162, v68, vcc
	v_cmp_neq_f32_e32 vcc, -1.0, v124
	v_mov_b32_e32 v87, v93
	v_mov_b32_e32 v83, v85
	v_cndmask_b32_e32 v69, v162, v69, vcc
	v_cmp_lt_f32_e64 vcc, |v97|, s9
	v_cndmask_b32_e64 v69, v69, v124, s[0:1]
	v_pk_add_f32 v[82:83], v[86:87], v[82:83]
	v_cndmask_b32_e32 v68, v68, v97, vcc
	v_pk_add_f32 v[76:77], v[76:77], v[68:69] neg_lo:[0,1] neg_hi:[0,1]
	v_cvt_f32_i32_e32 v69, v128
	v_cvt_f32_i32_e32 v68, v126
	v_pk_add_f32 v[86:87], v[84:85], v[92:93]
	v_cmp_neq_f32_e32 vcc, s8, v125
	v_mov_b32_e32 v113, v87
	v_pk_mul_f32 v[80:81], v[68:69], s[12:13] op_sel_hi:[1,0]
	v_cmp_lt_f32_e64 s[0:1], |v127|, s9
	v_pk_fma_f32 v[88:89], v[68:69], s[12:13], v[80:81] op_sel_hi:[1,0,1] neg_lo:[0,0,1] neg_hi:[0,0,1]
	v_mov_b32_e32 v90, v80
	v_pk_fma_f32 v[68:69], v[68:69], s[14:15], v[88:89] op_sel_hi:[1,0,1]
	v_mov_b32_e32 v101, v81
	v_pk_add_f32 v[88:89], v[80:81], v[68:69]
	v_mov_b32_e32 v102, v68
	v_pk_add_f32 v[94:95], v[88:89], v[86:87]
	v_pk_add_f32 v[90:91], v[90:91], v[102:103]
	v_mov_b32_e32 v102, v86
	v_mov_b32_e32 v103, v95
	v_mov_b32_e32 v111, v89
	v_pk_add_f32 v[102:103], v[102:103], v[110:111] neg_lo:[0,1] neg_hi:[0,1]
	v_mov_b32_e32 v98, v94
	v_mov_b32_e32 v99, v89
	v_mov_b32_e32 v100, v88
	v_mov_b32_e32 v110, v88
	v_mov_b32_e32 v111, v95
	v_mov_b32_e32 v81, v103
	v_pk_add_f32 v[98:99], v[98:99], v[100:101] neg_lo:[0,1] neg_hi:[0,1]
	v_mov_b32_e32 v100, v86
	v_mov_b32_e32 v101, v69
	v_pk_add_f32 v[80:81], v[110:111], v[80:81] neg_lo:[0,1] neg_hi:[0,1]
	v_pk_add_f32 v[100:101], v[100:101], v[98:99] neg_lo:[0,1] neg_hi:[0,1]
	v_mov_b32_e32 v110, v80
	v_mov_b32_e32 v111, v99
	v_mov_b32_e32 v112, v94
	v_mov_b32_e32 v99, v85
	v_pk_add_f32 v[110:111], v[68:69], v[110:111] neg_lo:[0,1] neg_hi:[0,1]
	v_pk_add_f32 v[98:99], v[112:113], v[98:99] neg_lo:[0,1] neg_hi:[0,1]
	v_mov_b32_e32 v69, v89
	v_pk_add_f32 v[84:85], v[86:87], v[84:85] neg_lo:[0,1] neg_hi:[0,1]
	v_pk_add_f32 v[86:87], v[90:91], v[98:99] neg_lo:[0,1] neg_hi:[0,1]
	v_pk_add_f32 v[68:69], v[68:69], v[80:81] neg_lo:[0,1] neg_hi:[0,1]
	v_pk_add_f32 v[80:81], v[82:83], v[102:103] neg_lo:[0,1] neg_hi:[0,1]
	v_pk_add_f32 v[88:89], v[100:101], v[86:87]
	v_pk_add_f32 v[82:83], v[80:81], v[68:69]
	v_mov_b32_e32 v69, v101
	v_mov_b32_e32 v81, v87
	v_pk_add_f32 v[80:81], v[68:69], v[80:81]
	v_mov_b32_e32 v86, v82
	v_pk_add_f32 v[80:81], v[80:81], v[110:111] neg_lo:[0,1] neg_hi:[0,1]
	v_mov_b32_e32 v87, v89
	v_pk_add_f32 v[84:85], v[92:93], v[84:85] neg_lo:[0,1] neg_hi:[0,1]
	v_pk_add_f32 v[86:87], v[86:87], v[80:81] neg_lo:[0,1] neg_hi:[0,1]
	v_pk_add_f32 v[80:81], v[84:85], v[80:81] neg_lo:[0,1] neg_hi:[0,1]
	v_pk_add_f32 v[68:69], v[68:69], v[86:87] neg_lo:[0,1] neg_hi:[0,1]
	s_nop 0
	v_pk_add_f32 v[68:69], v[80:81], v[68:69]
	v_pk_add_f32 v[80:81], v[88:89], v[82:83]
	s_nop 0
	v_pk_add_f32 v[82:83], v[94:95], v[80:81]
	s_nop 0
	v_pk_add_f32 v[84:85], v[82:83], v[94:95] neg_lo:[0,1] neg_hi:[0,1]
	s_nop 0
	v_pk_add_f32 v[80:81], v[80:81], v[84:85] neg_lo:[0,1] neg_hi:[0,1]
	s_nop 0
	v_pk_add_f32 v[68:69], v[68:69], v[80:81]
	s_nop 0
	v_pk_add_f32 v[68:69], v[82:83], v[68:69]
	s_nop 0
	v_cndmask_b32_e32 v68, v160, v68, vcc
	v_cmp_neq_f32_e32 vcc, s8, v127
	s_nop 1
	v_cndmask_b32_e32 v69, v160, v69, vcc
	v_cmp_ngt_f32_e32 vcc, -1.0, v127
	s_nop 1
	v_cndmask_b32_e32 v69, v161, v69, vcc
	v_cmp_ngt_f32_e32 vcc, -1.0, v125
	s_nop 1
	v_cndmask_b32_e32 v68, v161, v68, vcc
	v_cmp_neq_f32_e32 vcc, -1.0, v125
	s_nop 1
	v_cndmask_b32_e32 v68, v162, v68, vcc
	v_cmp_neq_f32_e32 vcc, -1.0, v127
	s_nop 1
	v_cndmask_b32_e32 v69, v162, v69, vcc
	v_cmp_lt_f32_e64 vcc, |v125|, s9
	v_cndmask_b32_e64 v69, v69, v127, s[0:1]
	s_nop 0
	v_cndmask_b32_e32 v68, v68, v125, vcc
	v_pk_add_f32 v[78:79], v[78:79], v[68:69] neg_lo:[0,1] neg_hi:[0,1]
	global_store_dwordx4 v[66:67], v[76:79], off
	ds_write_b128 v0, v[76:79]
